# nt hints extended: EpiRes residual loads, EpiUp gate loads, final rms f32 stores, prep weight source loads (on top of the rms nt loads)
# baseline (speedup 1.0000x reference)
.LBB0_8:
	s_mov_b32 s15, s2
	s_mov_b64 s[6:7], -1
	s_mov_b64 s[0:1], 0
	s_cmp_lt_i32 s2, 19
	s_mov_b64 s[4:5], 0
	s_cbranch_scc1 .LBB0_17
	s_cmp_eq_u32 s15, 19
	s_mov_b64 s[4:5], -1
	s_cbranch_scc0 .LBB0_16
	v_mov_b32_e32 v0, 0xe0
	v_mov_b32_e32 v2, 0xd8
	v_add_u32_e32 v0, s91, v0
	ds_read_b64 v[0:1], v0
	v_mov_b32_e32 v4, 0xe0
	v_add_u32_e32 v2, s91, v2
	ds_read_b64 v[2:3], v2
	s_waitcnt lgkmcnt(0)
	v_readfirstlane_b32 s9, v1
	v_add_u32_e32 v4, s91, v4
	ds_read_b64 v[4:5], v4
	v_readfirstlane_b32 s8, v0
	v_mbcnt_lo_u32_b32 v0, -1, 0
	v_mbcnt_hi_u32_b32 v0, -1, v0
	v_readlane_b32 s2, v253, 11
	v_add_u32_e32 v1, s57, v0
	v_ashrrev_i32_e32 v1, 6, v1
	v_add_u32_e32 v52, s2, v1
	s_waitcnt lgkmcnt(1)
	v_readfirstlane_b32 s11, v3
	v_readfirstlane_b32 s10, v2
	s_waitcnt lgkmcnt(0)
	v_readfirstlane_b32 s7, v5
	v_readfirstlane_b32 s6, v4
	v_cmp_gt_i32_e32 vcc, s3, v52
	s_and_saveexec_b64 s[4:5], vcc
	s_cbranch_execz .LBB0_15
	v_readfirstlane_b32 s100, v52
	s_nop 3
	v_lshlrev_b32_e32 v120, 4, v0
	v_lshlrev_b32_e32 v121, 3, v0
	v_lshlrev_b32_e32 v122, 2, v214
	v_lshlrev_b32_e32 v123, 2, v215
	v_lshlrev_b32_e32 v124, 2, v216
	v_lshlrev_b32_e32 v125, 2, v217
	v_lshlrev_b32_e32 v126, 2, v218
	v_lshlrev_b32_e32 v127, 2, v219
	s_lshr_b32 s2, s100, 6
	s_lshl_b32 s2, s2, 11
	s_and_b32 s101, s100, 63
	s_add_u32 s2, s2, s101
	s_lshl_b32 s101, s2, 12
	s_add_u32 s8, s8, s101
	s_addc_u32 s9, s9, 0
	s_add_u32 s6, s6, s101
	s_addc_u32 s7, s7, 0
	global_load_dwordx4 v[0:3], v120, s[10:11] offset:0
	global_load_dwordx4 v[4:7], v120, s[10:11] offset:1024
	global_load_dwordx4 v[8:11], v120, s[10:11] offset:2048
	global_load_dwordx4 v[12:15], v120, s[10:11] offset:3072
	s_movk_i32 s2, 3
	global_load_dwordx4 v[48:51], v120, s[8:9] offset:0 nt
	global_load_dwordx4 v[52:55], v120, s[8:9] offset:1024 nt
	global_load_dwordx4 v[56:59], v120, s[8:9] offset:2048 nt
	global_load_dwordx4 v[60:63], v120, s[8:9] offset:3072 nt
	s_add_u32 s8, s8, 0x40000
	s_addc_u32 s9, s9, 0
	global_load_dwordx4 v[64:67], v120, s[8:9] offset:0 nt
	global_load_dwordx4 v[68:71], v120, s[8:9] offset:1024 nt
	global_load_dwordx4 v[72:75], v120, s[8:9] offset:2048 nt
	global_load_dwordx4 v[76:79], v120, s[8:9] offset:3072 nt
	s_add_u32 s8, s8, 0x40000
	s_addc_u32 s9, s9, 0
	global_load_dwordx4 v[80:83], v120, s[8:9] offset:0 nt
	global_load_dwordx4 v[84:87], v120, s[8:9] offset:1024 nt
	global_load_dwordx4 v[88:91], v120, s[8:9] offset:2048 nt
	global_load_dwordx4 v[92:95], v120, s[8:9] offset:3072 nt
	s_add_u32 s8, s8, 0x40000
	s_addc_u32 s9, s9, 0
	global_load_dwordx4 v[96:99], v120, s[8:9] offset:0 nt
	global_load_dwordx4 v[100:103], v120, s[8:9] offset:1024 nt
	global_load_dwordx4 v[104:107], v120, s[8:9] offset:2048 nt
	global_load_dwordx4 v[108:111], v120, s[8:9] offset:3072 nt
	s_add_u32 s8, s8, 0x40000
	s_addc_u32 s9, s9, 0
	global_load_dwordx4 v[132:135], v120, s[8:9] offset:0 nt
	global_load_dwordx4 v[136:139], v120, s[8:9] offset:1024 nt
	global_load_dwordx4 v[140:143], v120, s[8:9] offset:2048 nt
	global_load_dwordx4 v[144:147], v120, s[8:9] offset:3072 nt
	s_add_u32 s8, s8, 0x40000
	s_addc_u32 s9, s9, 0
	global_load_dwordx4 v[166:169], v120, s[8:9] offset:0 nt
	global_load_dwordx4 v[170:173], v120, s[8:9] offset:1024 nt
	global_load_dwordx4 v[174:177], v120, s[8:9] offset:2048 nt
	global_load_dwordx4 v[178:181], v120, s[8:9] offset:3072 nt
	s_add_u32 s8, s8, 0x40000
	s_addc_u32 s9, s9, 0
	global_load_dwordx4 v[182:185], v120, s[8:9] offset:0 nt
	global_load_dwordx4 v[186:189], v120, s[8:9] offset:1024 nt
	global_load_dwordx4 v[190:193], v120, s[8:9] offset:2048 nt
	global_load_dwordx4 v[194:197], v120, s[8:9] offset:3072 nt
	s_add_u32 s8, s8, 0x40000
	s_addc_u32 s9, s9, 0
	global_load_dwordx4 v[228:231], v120, s[8:9] offset:0 nt
	global_load_dwordx4 v[232:235], v120, s[8:9] offset:1024 nt
	global_load_dwordx4 v[236:239], v120, s[8:9] offset:2048 nt
	global_load_dwordx4 v[240:243], v120, s[8:9] offset:3072 nt
	s_add_u32 s8, s8, 0x40000
	s_addc_u32 s9, s9, 0
	s_waitcnt vmcnt(28)
	v_mul_f32_e32 v112, v48, v48
	v_fmac_f32_e32 v112, v49, v49
	v_fmac_f32_e32 v112, v50, v50
	v_fmac_f32_e32 v112, v51, v51
	v_fmac_f32_e32 v112, v52, v52
	v_fmac_f32_e32 v112, v53, v53
	v_fmac_f32_e32 v112, v54, v54
	v_fmac_f32_e32 v112, v55, v55
	v_fmac_f32_e32 v112, v56, v56
	v_fmac_f32_e32 v112, v57, v57
	v_fmac_f32_e32 v112, v58, v58
	v_fmac_f32_e32 v112, v59, v59
	v_fmac_f32_e32 v112, v60, v60
	v_fmac_f32_e32 v112, v61, v61
	v_fmac_f32_e32 v112, v62, v62
	v_fmac_f32_e32 v112, v63, v63
	s_waitcnt vmcnt(24)
	v_mul_f32_e32 v113, v64, v64
	v_fmac_f32_e32 v113, v65, v65
	v_fmac_f32_e32 v113, v66, v66
	v_fmac_f32_e32 v113, v67, v67
	v_fmac_f32_e32 v113, v68, v68
	v_fmac_f32_e32 v113, v69, v69
	v_fmac_f32_e32 v113, v70, v70
	v_fmac_f32_e32 v113, v71, v71
	v_fmac_f32_e32 v113, v72, v72
	v_fmac_f32_e32 v113, v73, v73
	v_fmac_f32_e32 v113, v74, v74
	v_fmac_f32_e32 v113, v75, v75
	v_fmac_f32_e32 v113, v76, v76
	v_fmac_f32_e32 v113, v77, v77
	v_fmac_f32_e32 v113, v78, v78
	v_fmac_f32_e32 v113, v79, v79
	s_waitcnt vmcnt(20)
	v_mul_f32_e32 v114, v80, v80
	v_fmac_f32_e32 v114, v81, v81
	v_fmac_f32_e32 v114, v82, v82
	v_fmac_f32_e32 v114, v83, v83
	v_fmac_f32_e32 v114, v84, v84
	v_fmac_f32_e32 v114, v85, v85
	v_fmac_f32_e32 v114, v86, v86
	v_fmac_f32_e32 v114, v87, v87
	v_fmac_f32_e32 v114, v88, v88
	v_fmac_f32_e32 v114, v89, v89
	v_fmac_f32_e32 v114, v90, v90
	v_fmac_f32_e32 v114, v91, v91
	v_fmac_f32_e32 v114, v92, v92
	v_fmac_f32_e32 v114, v93, v93
	v_fmac_f32_e32 v114, v94, v94
	v_fmac_f32_e32 v114, v95, v95
	s_waitcnt vmcnt(16)
	v_mul_f32_e32 v115, v96, v96
	v_fmac_f32_e32 v115, v97, v97
	v_fmac_f32_e32 v115, v98, v98
	v_fmac_f32_e32 v115, v99, v99
	v_fmac_f32_e32 v115, v100, v100
	v_fmac_f32_e32 v115, v101, v101
	v_fmac_f32_e32 v115, v102, v102
	v_fmac_f32_e32 v115, v103, v103
	v_fmac_f32_e32 v115, v104, v104
	v_fmac_f32_e32 v115, v105, v105
	v_fmac_f32_e32 v115, v106, v106
	v_fmac_f32_e32 v115, v107, v107
	v_fmac_f32_e32 v115, v108, v108
	v_fmac_f32_e32 v115, v109, v109
	v_fmac_f32_e32 v115, v110, v110
	v_fmac_f32_e32 v115, v111, v111
	ds_bpermute_b32 v116, v122, v112
	ds_bpermute_b32 v117, v122, v113
	ds_bpermute_b32 v118, v122, v114
	ds_bpermute_b32 v119, v122, v115
	s_waitcnt lgkmcnt(0)
	v_add_f32_e32 v112, v112, v116
	v_add_f32_e32 v113, v113, v117
	v_add_f32_e32 v114, v114, v118
	v_add_f32_e32 v115, v115, v119
	ds_bpermute_b32 v116, v123, v112
	ds_bpermute_b32 v117, v123, v113
	ds_bpermute_b32 v118, v123, v114
	ds_bpermute_b32 v119, v123, v115
	s_waitcnt lgkmcnt(0)
	v_add_f32_e32 v112, v112, v116
	v_add_f32_e32 v113, v113, v117
	v_add_f32_e32 v114, v114, v118
	v_add_f32_e32 v115, v115, v119
	ds_bpermute_b32 v116, v124, v112
	ds_bpermute_b32 v117, v124, v113
	ds_bpermute_b32 v118, v124, v114
	ds_bpermute_b32 v119, v124, v115
	s_waitcnt lgkmcnt(0)
	v_add_f32_e32 v112, v112, v116
	v_add_f32_e32 v113, v113, v117
	v_add_f32_e32 v114, v114, v118
	v_add_f32_e32 v115, v115, v119
	ds_bpermute_b32 v116, v125, v112
	ds_bpermute_b32 v117, v125, v113
	ds_bpermute_b32 v118, v125, v114
	ds_bpermute_b32 v119, v125, v115
	s_waitcnt lgkmcnt(0)
	v_add_f32_e32 v112, v112, v116
	v_add_f32_e32 v113, v113, v117
	v_add_f32_e32 v114, v114, v118
	v_add_f32_e32 v115, v115, v119
	ds_bpermute_b32 v116, v126, v112
	ds_bpermute_b32 v117, v126, v113
	ds_bpermute_b32 v118, v126, v114
	ds_bpermute_b32 v119, v126, v115
	s_waitcnt lgkmcnt(0)
	v_add_f32_e32 v112, v112, v116
	v_add_f32_e32 v113, v113, v117
	v_add_f32_e32 v114, v114, v118
	v_add_f32_e32 v115, v115, v119
	ds_bpermute_b32 v116, v127, v112
	ds_bpermute_b32 v117, v127, v113
	ds_bpermute_b32 v118, v127, v114
	ds_bpermute_b32 v119, v127, v115
	s_waitcnt lgkmcnt(0)
	v_add_f32_e32 v112, v112, v116
	v_add_f32_e32 v113, v113, v117
	v_add_f32_e32 v114, v114, v118
	v_add_f32_e32 v115, v115, v119
	v_fmamk_f32 v112, v112, 0x3a800000, v208
	v_fmamk_f32 v113, v113, 0x3a800000, v208
	v_fmamk_f32 v114, v114, 0x3a800000, v208
	v_fmamk_f32 v115, v115, 0x3a800000, v208
	v_rsq_f32_e32 v112, v112
	v_rsq_f32_e32 v113, v113
	v_rsq_f32_e32 v114, v114
	v_rsq_f32_e32 v115, v115
	s_nop 1
	v_mul_f32_e32 v48, v48, v112
	v_mul_f32_e32 v49, v49, v112
	v_mul_f32_e32 v50, v50, v112
	v_mul_f32_e32 v51, v51, v112
	v_mul_f32_e32 v48, v0, v48
	v_mul_f32_e32 v49, v1, v49
	v_mul_f32_e32 v50, v2, v50
	v_mul_f32_e32 v51, v3, v51
	global_store_dwordx4 v120, v[48:51], s[6:7] offset:0 nt
	v_mul_f32_e32 v52, v52, v112
	v_mul_f32_e32 v53, v53, v112
	v_mul_f32_e32 v54, v54, v112
	v_mul_f32_e32 v55, v55, v112
	v_mul_f32_e32 v52, v4, v52
	v_mul_f32_e32 v53, v5, v53
	v_mul_f32_e32 v54, v6, v54
	v_mul_f32_e32 v55, v7, v55
	global_store_dwordx4 v120, v[52:55], s[6:7] offset:1024 nt
	v_mul_f32_e32 v56, v56, v112
	v_mul_f32_e32 v57, v57, v112
	v_mul_f32_e32 v58, v58, v112
	v_mul_f32_e32 v59, v59, v112
	v_mul_f32_e32 v56, v8, v56
	v_mul_f32_e32 v57, v9, v57
	v_mul_f32_e32 v58, v10, v58
	v_mul_f32_e32 v59, v11, v59
	global_store_dwordx4 v120, v[56:59], s[6:7] offset:2048 nt
	v_mul_f32_e32 v60, v60, v112
	v_mul_f32_e32 v61, v61, v112
	v_mul_f32_e32 v62, v62, v112
	v_mul_f32_e32 v63, v63, v112
	v_mul_f32_e32 v60, v12, v60
	v_mul_f32_e32 v61, v13, v61
	v_mul_f32_e32 v62, v14, v62
	v_mul_f32_e32 v63, v15, v63
	global_store_dwordx4 v120, v[60:63], s[6:7] offset:3072 nt
	s_add_u32 s6, s6, 0x40000
	s_addc_u32 s7, s7, 0
	v_mul_f32_e32 v64, v64, v113
	v_mul_f32_e32 v65, v65, v113
	v_mul_f32_e32 v66, v66, v113
	v_mul_f32_e32 v67, v67, v113
	v_mul_f32_e32 v64, v0, v64
	v_mul_f32_e32 v65, v1, v65
	v_mul_f32_e32 v66, v2, v66
	v_mul_f32_e32 v67, v3, v67
	global_store_dwordx4 v120, v[64:67], s[6:7] offset:0 nt
	v_mul_f32_e32 v68, v68, v113
	v_mul_f32_e32 v69, v69, v113
	v_mul_f32_e32 v70, v70, v113
	v_mul_f32_e32 v71, v71, v113
	v_mul_f32_e32 v68, v4, v68
	v_mul_f32_e32 v69, v5, v69
	v_mul_f32_e32 v70, v6, v70
	v_mul_f32_e32 v71, v7, v71
	global_store_dwordx4 v120, v[68:71], s[6:7] offset:1024 nt
	v_mul_f32_e32 v72, v72, v113
	v_mul_f32_e32 v73, v73, v113
	v_mul_f32_e32 v74, v74, v113
	v_mul_f32_e32 v75, v75, v113
	v_mul_f32_e32 v72, v8, v72
	v_mul_f32_e32 v73, v9, v73
	v_mul_f32_e32 v74, v10, v74
	v_mul_f32_e32 v75, v11, v75
	global_store_dwordx4 v120, v[72:75], s[6:7] offset:2048 nt
	v_mul_f32_e32 v76, v76, v113
	v_mul_f32_e32 v77, v77, v113
	v_mul_f32_e32 v78, v78, v113
	v_mul_f32_e32 v79, v79, v113
	v_mul_f32_e32 v76, v12, v76
	v_mul_f32_e32 v77, v13, v77
	v_mul_f32_e32 v78, v14, v78
	v_mul_f32_e32 v79, v15, v79
	global_store_dwordx4 v120, v[76:79], s[6:7] offset:3072 nt
	s_add_u32 s6, s6, 0x40000
	s_addc_u32 s7, s7, 0
	v_mul_f32_e32 v80, v80, v114
	v_mul_f32_e32 v81, v81, v114
	v_mul_f32_e32 v82, v82, v114
	v_mul_f32_e32 v83, v83, v114
	v_mul_f32_e32 v80, v0, v80
	v_mul_f32_e32 v81, v1, v81
	v_mul_f32_e32 v82, v2, v82
	v_mul_f32_e32 v83, v3, v83
	global_store_dwordx4 v120, v[80:83], s[6:7] offset:0 nt
	v_mul_f32_e32 v84, v84, v114
	v_mul_f32_e32 v85, v85, v114
	v_mul_f32_e32 v86, v86, v114
	v_mul_f32_e32 v87, v87, v114
	v_mul_f32_e32 v84, v4, v84
	v_mul_f32_e32 v85, v5, v85
	v_mul_f32_e32 v86, v6, v86
	v_mul_f32_e32 v87, v7, v87
	global_store_dwordx4 v120, v[84:87], s[6:7] offset:1024 nt
	v_mul_f32_e32 v88, v88, v114
	v_mul_f32_e32 v89, v89, v114
	v_mul_f32_e32 v90, v90, v114
	v_mul_f32_e32 v91, v91, v114
	v_mul_f32_e32 v88, v8, v88
	v_mul_f32_e32 v89, v9, v89
	v_mul_f32_e32 v90, v10, v90
	v_mul_f32_e32 v91, v11, v91
	global_store_dwordx4 v120, v[88:91], s[6:7] offset:2048 nt
	v_mul_f32_e32 v92, v92, v114
	v_mul_f32_e32 v93, v93, v114
	v_mul_f32_e32 v94, v94, v114
	v_mul_f32_e32 v95, v95, v114
	v_mul_f32_e32 v92, v12, v92
	v_mul_f32_e32 v93, v13, v93
	v_mul_f32_e32 v94, v14, v94
	v_mul_f32_e32 v95, v15, v95
	global_store_dwordx4 v120, v[92:95], s[6:7] offset:3072 nt
	s_add_u32 s6, s6, 0x40000
	s_addc_u32 s7, s7, 0
	v_mul_f32_e32 v96, v96, v115
	v_mul_f32_e32 v97, v97, v115
	v_mul_f32_e32 v98, v98, v115
	v_mul_f32_e32 v99, v99, v115
	v_mul_f32_e32 v96, v0, v96
	v_mul_f32_e32 v97, v1, v97
	v_mul_f32_e32 v98, v2, v98
	v_mul_f32_e32 v99, v3, v99
	global_store_dwordx4 v120, v[96:99], s[6:7] offset:0 nt
	v_mul_f32_e32 v100, v100, v115
	v_mul_f32_e32 v101, v101, v115
	v_mul_f32_e32 v102, v102, v115
	v_mul_f32_e32 v103, v103, v115
	v_mul_f32_e32 v100, v4, v100
	v_mul_f32_e32 v101, v5, v101
	v_mul_f32_e32 v102, v6, v102
	v_mul_f32_e32 v103, v7, v103
	global_store_dwordx4 v120, v[100:103], s[6:7] offset:1024 nt
	v_mul_f32_e32 v104, v104, v115
	v_mul_f32_e32 v105, v105, v115
	v_mul_f32_e32 v106, v106, v115
	v_mul_f32_e32 v107, v107, v115
	v_mul_f32_e32 v104, v8, v104
	v_mul_f32_e32 v105, v9, v105
	v_mul_f32_e32 v106, v10, v106
	v_mul_f32_e32 v107, v11, v107
	global_store_dwordx4 v120, v[104:107], s[6:7] offset:2048 nt
	v_mul_f32_e32 v108, v108, v115
	v_mul_f32_e32 v109, v109, v115
	v_mul_f32_e32 v110, v110, v115
	v_mul_f32_e32 v111, v111, v115
	v_mul_f32_e32 v108, v12, v108
	v_mul_f32_e32 v109, v13, v109
	v_mul_f32_e32 v110, v14, v110
	v_mul_f32_e32 v111, v15, v111
	global_store_dwordx4 v120, v[108:111], s[6:7] offset:3072 nt
	s_add_u32 s6, s6, 0x40000
	s_addc_u32 s7, s7, 0
.Lrms_final_loop:
	global_load_dwordx4 v[48:51], v120, s[8:9] offset:0 nt
	global_load_dwordx4 v[52:55], v120, s[8:9] offset:1024 nt
	global_load_dwordx4 v[56:59], v120, s[8:9] offset:2048 nt
	global_load_dwordx4 v[60:63], v120, s[8:9] offset:3072 nt
	s_add_u32 s8, s8, 0x40000
	s_addc_u32 s9, s9, 0
	global_load_dwordx4 v[64:67], v120, s[8:9] offset:0 nt
	global_load_dwordx4 v[68:71], v120, s[8:9] offset:1024 nt
	global_load_dwordx4 v[72:75], v120, s[8:9] offset:2048 nt
	global_load_dwordx4 v[76:79], v120, s[8:9] offset:3072 nt
	s_add_u32 s8, s8, 0x40000
	s_addc_u32 s9, s9, 0
	global_load_dwordx4 v[80:83], v120, s[8:9] offset:0 nt
	global_load_dwordx4 v[84:87], v120, s[8:9] offset:1024 nt
	global_load_dwordx4 v[88:91], v120, s[8:9] offset:2048 nt
	global_load_dwordx4 v[92:95], v120, s[8:9] offset:3072 nt
	s_add_u32 s8, s8, 0x40000
	s_addc_u32 s9, s9, 0
	global_load_dwordx4 v[96:99], v120, s[8:9] offset:0 nt
	global_load_dwordx4 v[100:103], v120, s[8:9] offset:1024 nt
	global_load_dwordx4 v[104:107], v120, s[8:9] offset:2048 nt
	global_load_dwordx4 v[108:111], v120, s[8:9] offset:3072 nt
	s_add_u32 s8, s8, 0x40000
	s_addc_u32 s9, s9, 0
	s_waitcnt vmcnt(44)
	v_mul_f32_e32 v112, v132, v132
	v_fmac_f32_e32 v112, v133, v133
	v_fmac_f32_e32 v112, v134, v134
	v_fmac_f32_e32 v112, v135, v135
	v_fmac_f32_e32 v112, v136, v136
	v_fmac_f32_e32 v112, v137, v137
	v_fmac_f32_e32 v112, v138, v138
	v_fmac_f32_e32 v112, v139, v139
	v_fmac_f32_e32 v112, v140, v140
	v_fmac_f32_e32 v112, v141, v141
	v_fmac_f32_e32 v112, v142, v142
	v_fmac_f32_e32 v112, v143, v143
	v_fmac_f32_e32 v112, v144, v144
	v_fmac_f32_e32 v112, v145, v145
	v_fmac_f32_e32 v112, v146, v146
	v_fmac_f32_e32 v112, v147, v147
	s_waitcnt vmcnt(40)
	v_mul_f32_e32 v113, v166, v166
	v_fmac_f32_e32 v113, v167, v167
	v_fmac_f32_e32 v113, v168, v168
	v_fmac_f32_e32 v113, v169, v169
	v_fmac_f32_e32 v113, v170, v170
	v_fmac_f32_e32 v113, v171, v171
	v_fmac_f32_e32 v113, v172, v172
	v_fmac_f32_e32 v113, v173, v173
	v_fmac_f32_e32 v113, v174, v174
	v_fmac_f32_e32 v113, v175, v175
	v_fmac_f32_e32 v113, v176, v176
	v_fmac_f32_e32 v113, v177, v177
	v_fmac_f32_e32 v113, v178, v178
	v_fmac_f32_e32 v113, v179, v179
	v_fmac_f32_e32 v113, v180, v180
	v_fmac_f32_e32 v113, v181, v181
	s_waitcnt vmcnt(36)
	v_mul_f32_e32 v114, v182, v182
	v_fmac_f32_e32 v114, v183, v183
	v_fmac_f32_e32 v114, v184, v184
	v_fmac_f32_e32 v114, v185, v185
	v_fmac_f32_e32 v114, v186, v186
	v_fmac_f32_e32 v114, v187, v187
	v_fmac_f32_e32 v114, v188, v188
	v_fmac_f32_e32 v114, v189, v189
	v_fmac_f32_e32 v114, v190, v190
	v_fmac_f32_e32 v114, v191, v191
	v_fmac_f32_e32 v114, v192, v192
	v_fmac_f32_e32 v114, v193, v193
	v_fmac_f32_e32 v114, v194, v194
	v_fmac_f32_e32 v114, v195, v195
	v_fmac_f32_e32 v114, v196, v196
	v_fmac_f32_e32 v114, v197, v197
	s_waitcnt vmcnt(32)
	v_mul_f32_e32 v115, v228, v228
	v_fmac_f32_e32 v115, v229, v229
	v_fmac_f32_e32 v115, v230, v230
	v_fmac_f32_e32 v115, v231, v231
	v_fmac_f32_e32 v115, v232, v232
	v_fmac_f32_e32 v115, v233, v233
	v_fmac_f32_e32 v115, v234, v234
	v_fmac_f32_e32 v115, v235, v235
	v_fmac_f32_e32 v115, v236, v236
	v_fmac_f32_e32 v115, v237, v237
	v_fmac_f32_e32 v115, v238, v238
	v_fmac_f32_e32 v115, v239, v239
	v_fmac_f32_e32 v115, v240, v240
	v_fmac_f32_e32 v115, v241, v241
	v_fmac_f32_e32 v115, v242, v242
	v_fmac_f32_e32 v115, v243, v243
	ds_bpermute_b32 v116, v122, v112
	ds_bpermute_b32 v117, v122, v113
	ds_bpermute_b32 v118, v122, v114
	ds_bpermute_b32 v119, v122, v115
	s_waitcnt lgkmcnt(0)
	v_add_f32_e32 v112, v112, v116
	v_add_f32_e32 v113, v113, v117
	v_add_f32_e32 v114, v114, v118
	v_add_f32_e32 v115, v115, v119
	ds_bpermute_b32 v116, v123, v112
	ds_bpermute_b32 v117, v123, v113
	ds_bpermute_b32 v118, v123, v114
	ds_bpermute_b32 v119, v123, v115
	s_waitcnt lgkmcnt(0)
	v_add_f32_e32 v112, v112, v116
	v_add_f32_e32 v113, v113, v117
	v_add_f32_e32 v114, v114, v118
	v_add_f32_e32 v115, v115, v119
	ds_bpermute_b32 v116, v124, v112
	ds_bpermute_b32 v117, v124, v113
	ds_bpermute_b32 v118, v124, v114
	ds_bpermute_b32 v119, v124, v115
	s_waitcnt lgkmcnt(0)
	v_add_f32_e32 v112, v112, v116
	v_add_f32_e32 v113, v113, v117
	v_add_f32_e32 v114, v114, v118
	v_add_f32_e32 v115, v115, v119
	ds_bpermute_b32 v116, v125, v112
	ds_bpermute_b32 v117, v125, v113
	ds_bpermute_b32 v118, v125, v114
	ds_bpermute_b32 v119, v125, v115
	s_waitcnt lgkmcnt(0)
	v_add_f32_e32 v112, v112, v116
	v_add_f32_e32 v113, v113, v117
	v_add_f32_e32 v114, v114, v118
	v_add_f32_e32 v115, v115, v119
	ds_bpermute_b32 v116, v126, v112
	ds_bpermute_b32 v117, v126, v113
	ds_bpermute_b32 v118, v126, v114
	ds_bpermute_b32 v119, v126, v115
	s_waitcnt lgkmcnt(0)
	v_add_f32_e32 v112, v112, v116
	v_add_f32_e32 v113, v113, v117
	v_add_f32_e32 v114, v114, v118
	v_add_f32_e32 v115, v115, v119
	ds_bpermute_b32 v116, v127, v112
	ds_bpermute_b32 v117, v127, v113
	ds_bpermute_b32 v118, v127, v114
	ds_bpermute_b32 v119, v127, v115
	s_waitcnt lgkmcnt(0)
	v_add_f32_e32 v112, v112, v116
	v_add_f32_e32 v113, v113, v117
	v_add_f32_e32 v114, v114, v118
	v_add_f32_e32 v115, v115, v119
	v_fmamk_f32 v112, v112, 0x3a800000, v208
	v_fmamk_f32 v113, v113, 0x3a800000, v208
	v_fmamk_f32 v114, v114, 0x3a800000, v208
	v_fmamk_f32 v115, v115, 0x3a800000, v208
	v_rsq_f32_e32 v112, v112
	v_rsq_f32_e32 v113, v113
	v_rsq_f32_e32 v114, v114
	v_rsq_f32_e32 v115, v115
	s_nop 1
	v_mul_f32_e32 v132, v132, v112
	v_mul_f32_e32 v133, v133, v112
	v_mul_f32_e32 v134, v134, v112
	v_mul_f32_e32 v135, v135, v112
	v_mul_f32_e32 v132, v0, v132
	v_mul_f32_e32 v133, v1, v133
	v_mul_f32_e32 v134, v2, v134
	v_mul_f32_e32 v135, v3, v135
	global_store_dwordx4 v120, v[132:135], s[6:7] offset:0 nt
	v_mul_f32_e32 v136, v136, v112
	v_mul_f32_e32 v137, v137, v112
	v_mul_f32_e32 v138, v138, v112
	v_mul_f32_e32 v139, v139, v112
	v_mul_f32_e32 v136, v4, v136
	v_mul_f32_e32 v137, v5, v137
	v_mul_f32_e32 v138, v6, v138
	v_mul_f32_e32 v139, v7, v139
	global_store_dwordx4 v120, v[136:139], s[6:7] offset:1024 nt
	v_mul_f32_e32 v140, v140, v112
	v_mul_f32_e32 v141, v141, v112
	v_mul_f32_e32 v142, v142, v112
	v_mul_f32_e32 v143, v143, v112
	v_mul_f32_e32 v140, v8, v140
	v_mul_f32_e32 v141, v9, v141
	v_mul_f32_e32 v142, v10, v142
	v_mul_f32_e32 v143, v11, v143
	global_store_dwordx4 v120, v[140:143], s[6:7] offset:2048 nt
	v_mul_f32_e32 v144, v144, v112
	v_mul_f32_e32 v145, v145, v112
	v_mul_f32_e32 v146, v146, v112
	v_mul_f32_e32 v147, v147, v112
	v_mul_f32_e32 v144, v12, v144
	v_mul_f32_e32 v145, v13, v145
	v_mul_f32_e32 v146, v14, v146
	v_mul_f32_e32 v147, v15, v147
	global_store_dwordx4 v120, v[144:147], s[6:7] offset:3072 nt
	s_add_u32 s6, s6, 0x40000
	s_addc_u32 s7, s7, 0
	v_mul_f32_e32 v166, v166, v113
	v_mul_f32_e32 v167, v167, v113
	v_mul_f32_e32 v168, v168, v113
	v_mul_f32_e32 v169, v169, v113
	v_mul_f32_e32 v166, v0, v166
	v_mul_f32_e32 v167, v1, v167
	v_mul_f32_e32 v168, v2, v168
	v_mul_f32_e32 v169, v3, v169
	global_store_dwordx4 v120, v[166:169], s[6:7] offset:0 nt
	v_mul_f32_e32 v170, v170, v113
	v_mul_f32_e32 v171, v171, v113
	v_mul_f32_e32 v172, v172, v113
	v_mul_f32_e32 v173, v173, v113
	v_mul_f32_e32 v170, v4, v170
	v_mul_f32_e32 v171, v5, v171
	v_mul_f32_e32 v172, v6, v172
	v_mul_f32_e32 v173, v7, v173
	global_store_dwordx4 v120, v[170:173], s[6:7] offset:1024 nt
	v_mul_f32_e32 v174, v174, v113
	v_mul_f32_e32 v175, v175, v113
	v_mul_f32_e32 v176, v176, v113
	v_mul_f32_e32 v177, v177, v113
	v_mul_f32_e32 v174, v8, v174
	v_mul_f32_e32 v175, v9, v175
	v_mul_f32_e32 v176, v10, v176
	v_mul_f32_e32 v177, v11, v177
	global_store_dwordx4 v120, v[174:177], s[6:7] offset:2048 nt
	v_mul_f32_e32 v178, v178, v113
	v_mul_f32_e32 v179, v179, v113
	v_mul_f32_e32 v180, v180, v113
	v_mul_f32_e32 v181, v181, v113
	v_mul_f32_e32 v178, v12, v178
	v_mul_f32_e32 v179, v13, v179
	v_mul_f32_e32 v180, v14, v180
	v_mul_f32_e32 v181, v15, v181
	global_store_dwordx4 v120, v[178:181], s[6:7] offset:3072 nt
	s_add_u32 s6, s6, 0x40000
	s_addc_u32 s7, s7, 0
	v_mul_f32_e32 v182, v182, v114
	v_mul_f32_e32 v183, v183, v114
	v_mul_f32_e32 v184, v184, v114
	v_mul_f32_e32 v185, v185, v114
	v_mul_f32_e32 v182, v0, v182
	v_mul_f32_e32 v183, v1, v183
	v_mul_f32_e32 v184, v2, v184
	v_mul_f32_e32 v185, v3, v185
	global_store_dwordx4 v120, v[182:185], s[6:7] offset:0 nt
	v_mul_f32_e32 v186, v186, v114
	v_mul_f32_e32 v187, v187, v114
	v_mul_f32_e32 v188, v188, v114
	v_mul_f32_e32 v189, v189, v114
	v_mul_f32_e32 v186, v4, v186
	v_mul_f32_e32 v187, v5, v187
	v_mul_f32_e32 v188, v6, v188
	v_mul_f32_e32 v189, v7, v189
	global_store_dwordx4 v120, v[186:189], s[6:7] offset:1024 nt
	v_mul_f32_e32 v190, v190, v114
	v_mul_f32_e32 v191, v191, v114
	v_mul_f32_e32 v192, v192, v114
	v_mul_f32_e32 v193, v193, v114
	v_mul_f32_e32 v190, v8, v190
	v_mul_f32_e32 v191, v9, v191
	v_mul_f32_e32 v192, v10, v192
	v_mul_f32_e32 v193, v11, v193
	global_store_dwordx4 v120, v[190:193], s[6:7] offset:2048 nt
	v_mul_f32_e32 v194, v194, v114
	v_mul_f32_e32 v195, v195, v114
	v_mul_f32_e32 v196, v196, v114
	v_mul_f32_e32 v197, v197, v114
	v_mul_f32_e32 v194, v12, v194
	v_mul_f32_e32 v195, v13, v195
	v_mul_f32_e32 v196, v14, v196
	v_mul_f32_e32 v197, v15, v197
	global_store_dwordx4 v120, v[194:197], s[6:7] offset:3072 nt
	s_add_u32 s6, s6, 0x40000
	s_addc_u32 s7, s7, 0
	v_mul_f32_e32 v228, v228, v115
	v_mul_f32_e32 v229, v229, v115
	v_mul_f32_e32 v230, v230, v115
	v_mul_f32_e32 v231, v231, v115
	v_mul_f32_e32 v228, v0, v228
	v_mul_f32_e32 v229, v1, v229
	v_mul_f32_e32 v230, v2, v230
	v_mul_f32_e32 v231, v3, v231
	global_store_dwordx4 v120, v[228:231], s[6:7] offset:0 nt
	v_mul_f32_e32 v232, v232, v115
	v_mul_f32_e32 v233, v233, v115
	v_mul_f32_e32 v234, v234, v115
	v_mul_f32_e32 v235, v235, v115
	v_mul_f32_e32 v232, v4, v232
	v_mul_f32_e32 v233, v5, v233
	v_mul_f32_e32 v234, v6, v234
	v_mul_f32_e32 v235, v7, v235
	global_store_dwordx4 v120, v[232:235], s[6:7] offset:1024 nt
	v_mul_f32_e32 v236, v236, v115
	v_mul_f32_e32 v237, v237, v115
	v_mul_f32_e32 v238, v238, v115
	v_mul_f32_e32 v239, v239, v115
	v_mul_f32_e32 v236, v8, v236
	v_mul_f32_e32 v237, v9, v237
	v_mul_f32_e32 v238, v10, v238
	v_mul_f32_e32 v239, v11, v239
	global_store_dwordx4 v120, v[236:239], s[6:7] offset:2048 nt
	v_mul_f32_e32 v240, v240, v115
	v_mul_f32_e32 v241, v241, v115
	v_mul_f32_e32 v242, v242, v115
	v_mul_f32_e32 v243, v243, v115
	v_mul_f32_e32 v240, v12, v240
	v_mul_f32_e32 v241, v13, v241
	v_mul_f32_e32 v242, v14, v242
	v_mul_f32_e32 v243, v15, v243
	global_store_dwordx4 v120, v[240:243], s[6:7] offset:3072 nt
	s_add_u32 s6, s6, 0x40000
	s_addc_u32 s7, s7, 0
	global_load_dwordx4 v[132:135], v120, s[8:9] offset:0 nt
	global_load_dwordx4 v[136:139], v120, s[8:9] offset:1024 nt
	global_load_dwordx4 v[140:143], v120, s[8:9] offset:2048 nt
	global_load_dwordx4 v[144:147], v120, s[8:9] offset:3072 nt
	s_add_u32 s8, s8, 0x40000
	s_addc_u32 s9, s9, 0
	global_load_dwordx4 v[166:169], v120, s[8:9] offset:0 nt
	global_load_dwordx4 v[170:173], v120, s[8:9] offset:1024 nt
	global_load_dwordx4 v[174:177], v120, s[8:9] offset:2048 nt
	global_load_dwordx4 v[178:181], v120, s[8:9] offset:3072 nt
	s_add_u32 s8, s8, 0x40000
	s_addc_u32 s9, s9, 0
	global_load_dwordx4 v[182:185], v120, s[8:9] offset:0 nt
	global_load_dwordx4 v[186:189], v120, s[8:9] offset:1024 nt
	global_load_dwordx4 v[190:193], v120, s[8:9] offset:2048 nt
	global_load_dwordx4 v[194:197], v120, s[8:9] offset:3072 nt
	s_add_u32 s8, s8, 0x40000
	s_addc_u32 s9, s9, 0
	global_load_dwordx4 v[228:231], v120, s[8:9] offset:0 nt
	global_load_dwordx4 v[232:235], v120, s[8:9] offset:1024 nt
	global_load_dwordx4 v[236:239], v120, s[8:9] offset:2048 nt
	global_load_dwordx4 v[240:243], v120, s[8:9] offset:3072 nt
	s_add_u32 s8, s8, 0x40000
	s_addc_u32 s9, s9, 0
	s_waitcnt vmcnt(44)
	v_mul_f32_e32 v112, v48, v48
	v_fmac_f32_e32 v112, v49, v49
	v_fmac_f32_e32 v112, v50, v50
	v_fmac_f32_e32 v112, v51, v51
	v_fmac_f32_e32 v112, v52, v52
	v_fmac_f32_e32 v112, v53, v53
	v_fmac_f32_e32 v112, v54, v54
	v_fmac_f32_e32 v112, v55, v55
	v_fmac_f32_e32 v112, v56, v56
	v_fmac_f32_e32 v112, v57, v57
	v_fmac_f32_e32 v112, v58, v58
	v_fmac_f32_e32 v112, v59, v59
	v_fmac_f32_e32 v112, v60, v60
	v_fmac_f32_e32 v112, v61, v61
	v_fmac_f32_e32 v112, v62, v62
	v_fmac_f32_e32 v112, v63, v63
	s_waitcnt vmcnt(40)
	v_mul_f32_e32 v113, v64, v64
	v_fmac_f32_e32 v113, v65, v65
	v_fmac_f32_e32 v113, v66, v66
	v_fmac_f32_e32 v113, v67, v67
	v_fmac_f32_e32 v113, v68, v68
	v_fmac_f32_e32 v113, v69, v69
	v_fmac_f32_e32 v113, v70, v70
	v_fmac_f32_e32 v113, v71, v71
	v_fmac_f32_e32 v113, v72, v72
	v_fmac_f32_e32 v113, v73, v73
	v_fmac_f32_e32 v113, v74, v74
	v_fmac_f32_e32 v113, v75, v75
	v_fmac_f32_e32 v113, v76, v76
	v_fmac_f32_e32 v113, v77, v77
	v_fmac_f32_e32 v113, v78, v78
	v_fmac_f32_e32 v113, v79, v79
	s_waitcnt vmcnt(36)
	v_mul_f32_e32 v114, v80, v80
	v_fmac_f32_e32 v114, v81, v81
	v_fmac_f32_e32 v114, v82, v82
	v_fmac_f32_e32 v114, v83, v83
	v_fmac_f32_e32 v114, v84, v84
	v_fmac_f32_e32 v114, v85, v85
	v_fmac_f32_e32 v114, v86, v86
	v_fmac_f32_e32 v114, v87, v87
	v_fmac_f32_e32 v114, v88, v88
	v_fmac_f32_e32 v114, v89, v89
	v_fmac_f32_e32 v114, v90, v90
	v_fmac_f32_e32 v114, v91, v91
	v_fmac_f32_e32 v114, v92, v92
	v_fmac_f32_e32 v114, v93, v93
	v_fmac_f32_e32 v114, v94, v94
	v_fmac_f32_e32 v114, v95, v95
	s_waitcnt vmcnt(32)
	v_mul_f32_e32 v115, v96, v96
	v_fmac_f32_e32 v115, v97, v97
	v_fmac_f32_e32 v115, v98, v98
	v_fmac_f32_e32 v115, v99, v99
	v_fmac_f32_e32 v115, v100, v100
	v_fmac_f32_e32 v115, v101, v101
	v_fmac_f32_e32 v115, v102, v102
	v_fmac_f32_e32 v115, v103, v103
	v_fmac_f32_e32 v115, v104, v104
	v_fmac_f32_e32 v115, v105, v105
	v_fmac_f32_e32 v115, v106, v106
	v_fmac_f32_e32 v115, v107, v107
	v_fmac_f32_e32 v115, v108, v108
	v_fmac_f32_e32 v115, v109, v109
	v_fmac_f32_e32 v115, v110, v110
	v_fmac_f32_e32 v115, v111, v111
	ds_bpermute_b32 v116, v122, v112
	ds_bpermute_b32 v117, v122, v113
	ds_bpermute_b32 v118, v122, v114
	ds_bpermute_b32 v119, v122, v115
	s_waitcnt lgkmcnt(0)
	v_add_f32_e32 v112, v112, v116
	v_add_f32_e32 v113, v113, v117
	v_add_f32_e32 v114, v114, v118
	v_add_f32_e32 v115, v115, v119
	ds_bpermute_b32 v116, v123, v112
	ds_bpermute_b32 v117, v123, v113
	ds_bpermute_b32 v118, v123, v114
	ds_bpermute_b32 v119, v123, v115
	s_waitcnt lgkmcnt(0)
	v_add_f32_e32 v112, v112, v116
	v_add_f32_e32 v113, v113, v117
	v_add_f32_e32 v114, v114, v118
	v_add_f32_e32 v115, v115, v119
	ds_bpermute_b32 v116, v124, v112
	ds_bpermute_b32 v117, v124, v113
	ds_bpermute_b32 v118, v124, v114
	ds_bpermute_b32 v119, v124, v115
	s_waitcnt lgkmcnt(0)
	v_add_f32_e32 v112, v112, v116
	v_add_f32_e32 v113, v113, v117
	v_add_f32_e32 v114, v114, v118
	v_add_f32_e32 v115, v115, v119
	ds_bpermute_b32 v116, v125, v112
	ds_bpermute_b32 v117, v125, v113
	ds_bpermute_b32 v118, v125, v114
	ds_bpermute_b32 v119, v125, v115
	s_waitcnt lgkmcnt(0)
	v_add_f32_e32 v112, v112, v116
	v_add_f32_e32 v113, v113, v117
	v_add_f32_e32 v114, v114, v118
	v_add_f32_e32 v115, v115, v119
	ds_bpermute_b32 v116, v126, v112
	ds_bpermute_b32 v117, v126, v113
	ds_bpermute_b32 v118, v126, v114
	ds_bpermute_b32 v119, v126, v115
	s_waitcnt lgkmcnt(0)
	v_add_f32_e32 v112, v112, v116
	v_add_f32_e32 v113, v113, v117
	v_add_f32_e32 v114, v114, v118
	v_add_f32_e32 v115, v115, v119
	ds_bpermute_b32 v116, v127, v112
	ds_bpermute_b32 v117, v127, v113
	ds_bpermute_b32 v118, v127, v114
	ds_bpermute_b32 v119, v127, v115
	s_waitcnt lgkmcnt(0)
	v_add_f32_e32 v112, v112, v116
	v_add_f32_e32 v113, v113, v117
	v_add_f32_e32 v114, v114, v118
	v_add_f32_e32 v115, v115, v119
	v_fmamk_f32 v112, v112, 0x3a800000, v208
	v_fmamk_f32 v113, v113, 0x3a800000, v208
	v_fmamk_f32 v114, v114, 0x3a800000, v208
	v_fmamk_f32 v115, v115, 0x3a800000, v208
	v_rsq_f32_e32 v112, v112
	v_rsq_f32_e32 v113, v113
	v_rsq_f32_e32 v114, v114
	v_rsq_f32_e32 v115, v115
	s_nop 1
	v_mul_f32_e32 v48, v48, v112
	v_mul_f32_e32 v49, v49, v112
	v_mul_f32_e32 v50, v50, v112
	v_mul_f32_e32 v51, v51, v112
	v_mul_f32_e32 v48, v0, v48
	v_mul_f32_e32 v49, v1, v49
	v_mul_f32_e32 v50, v2, v50
	v_mul_f32_e32 v51, v3, v51
	global_store_dwordx4 v120, v[48:51], s[6:7] offset:0 nt
	v_mul_f32_e32 v52, v52, v112
	v_mul_f32_e32 v53, v53, v112
	v_mul_f32_e32 v54, v54, v112
	v_mul_f32_e32 v55, v55, v112
	v_mul_f32_e32 v52, v4, v52
	v_mul_f32_e32 v53, v5, v53
	v_mul_f32_e32 v54, v6, v54
	v_mul_f32_e32 v55, v7, v55
	global_store_dwordx4 v120, v[52:55], s[6:7] offset:1024 nt
	v_mul_f32_e32 v56, v56, v112
	v_mul_f32_e32 v57, v57, v112
	v_mul_f32_e32 v58, v58, v112
	v_mul_f32_e32 v59, v59, v112
	v_mul_f32_e32 v56, v8, v56
	v_mul_f32_e32 v57, v9, v57
	v_mul_f32_e32 v58, v10, v58
	v_mul_f32_e32 v59, v11, v59
	global_store_dwordx4 v120, v[56:59], s[6:7] offset:2048 nt
	v_mul_f32_e32 v60, v60, v112
	v_mul_f32_e32 v61, v61, v112
	v_mul_f32_e32 v62, v62, v112
	v_mul_f32_e32 v63, v63, v112
	v_mul_f32_e32 v60, v12, v60
	v_mul_f32_e32 v61, v13, v61
	v_mul_f32_e32 v62, v14, v62
	v_mul_f32_e32 v63, v15, v63
	global_store_dwordx4 v120, v[60:63], s[6:7] offset:3072 nt
	s_add_u32 s6, s6, 0x40000
	s_addc_u32 s7, s7, 0
	v_mul_f32_e32 v64, v64, v113
	v_mul_f32_e32 v65, v65, v113
	v_mul_f32_e32 v66, v66, v113
	v_mul_f32_e32 v67, v67, v113
	v_mul_f32_e32 v64, v0, v64
	v_mul_f32_e32 v65, v1, v65
	v_mul_f32_e32 v66, v2, v66
	v_mul_f32_e32 v67, v3, v67
	global_store_dwordx4 v120, v[64:67], s[6:7] offset:0 nt
	v_mul_f32_e32 v68, v68, v113
	v_mul_f32_e32 v69, v69, v113
	v_mul_f32_e32 v70, v70, v113
	v_mul_f32_e32 v71, v71, v113
	v_mul_f32_e32 v68, v4, v68
	v_mul_f32_e32 v69, v5, v69
	v_mul_f32_e32 v70, v6, v70
	v_mul_f32_e32 v71, v7, v71
	global_store_dwordx4 v120, v[68:71], s[6:7] offset:1024 nt
	v_mul_f32_e32 v72, v72, v113
	v_mul_f32_e32 v73, v73, v113
	v_mul_f32_e32 v74, v74, v113
	v_mul_f32_e32 v75, v75, v113
	v_mul_f32_e32 v72, v8, v72
	v_mul_f32_e32 v73, v9, v73
	v_mul_f32_e32 v74, v10, v74
	v_mul_f32_e32 v75, v11, v75
	global_store_dwordx4 v120, v[72:75], s[6:7] offset:2048 nt
	v_mul_f32_e32 v76, v76, v113
	v_mul_f32_e32 v77, v77, v113
	v_mul_f32_e32 v78, v78, v113
	v_mul_f32_e32 v79, v79, v113
	v_mul_f32_e32 v76, v12, v76
	v_mul_f32_e32 v77, v13, v77
	v_mul_f32_e32 v78, v14, v78
	v_mul_f32_e32 v79, v15, v79
	global_store_dwordx4 v120, v[76:79], s[6:7] offset:3072 nt
	s_add_u32 s6, s6, 0x40000
	s_addc_u32 s7, s7, 0
	v_mul_f32_e32 v80, v80, v114
	v_mul_f32_e32 v81, v81, v114
	v_mul_f32_e32 v82, v82, v114
	v_mul_f32_e32 v83, v83, v114
	v_mul_f32_e32 v80, v0, v80
	v_mul_f32_e32 v81, v1, v81
	v_mul_f32_e32 v82, v2, v82
	v_mul_f32_e32 v83, v3, v83
	global_store_dwordx4 v120, v[80:83], s[6:7] offset:0 nt
	v_mul_f32_e32 v84, v84, v114
	v_mul_f32_e32 v85, v85, v114
	v_mul_f32_e32 v86, v86, v114
	v_mul_f32_e32 v87, v87, v114
	v_mul_f32_e32 v84, v4, v84
	v_mul_f32_e32 v85, v5, v85
	v_mul_f32_e32 v86, v6, v86
	v_mul_f32_e32 v87, v7, v87
	global_store_dwordx4 v120, v[84:87], s[6:7] offset:1024 nt
	v_mul_f32_e32 v88, v88, v114
	v_mul_f32_e32 v89, v89, v114
	v_mul_f32_e32 v90, v90, v114
	v_mul_f32_e32 v91, v91, v114
	v_mul_f32_e32 v88, v8, v88
	v_mul_f32_e32 v89, v9, v89
	v_mul_f32_e32 v90, v10, v90
	v_mul_f32_e32 v91, v11, v91
	global_store_dwordx4 v120, v[88:91], s[6:7] offset:2048 nt
	v_mul_f32_e32 v92, v92, v114
	v_mul_f32_e32 v93, v93, v114
	v_mul_f32_e32 v94, v94, v114
	v_mul_f32_e32 v95, v95, v114
	v_mul_f32_e32 v92, v12, v92
	v_mul_f32_e32 v93, v13, v93
	v_mul_f32_e32 v94, v14, v94
	v_mul_f32_e32 v95, v15, v95
	global_store_dwordx4 v120, v[92:95], s[6:7] offset:3072 nt
	s_add_u32 s6, s6, 0x40000
	s_addc_u32 s7, s7, 0
	v_mul_f32_e32 v96, v96, v115
	v_mul_f32_e32 v97, v97, v115
	v_mul_f32_e32 v98, v98, v115
	v_mul_f32_e32 v99, v99, v115
	v_mul_f32_e32 v96, v0, v96
	v_mul_f32_e32 v97, v1, v97
	v_mul_f32_e32 v98, v2, v98
	v_mul_f32_e32 v99, v3, v99
	global_store_dwordx4 v120, v[96:99], s[6:7] offset:0 nt
	v_mul_f32_e32 v100, v100, v115
	v_mul_f32_e32 v101, v101, v115
	v_mul_f32_e32 v102, v102, v115
	v_mul_f32_e32 v103, v103, v115
	v_mul_f32_e32 v100, v4, v100
	v_mul_f32_e32 v101, v5, v101
	v_mul_f32_e32 v102, v6, v102
	v_mul_f32_e32 v103, v7, v103
	global_store_dwordx4 v120, v[100:103], s[6:7] offset:1024 nt
	v_mul_f32_e32 v104, v104, v115
	v_mul_f32_e32 v105, v105, v115
	v_mul_f32_e32 v106, v106, v115
	v_mul_f32_e32 v107, v107, v115
	v_mul_f32_e32 v104, v8, v104
	v_mul_f32_e32 v105, v9, v105
	v_mul_f32_e32 v106, v10, v106
	v_mul_f32_e32 v107, v11, v107
	global_store_dwordx4 v120, v[104:107], s[6:7] offset:2048 nt
	v_mul_f32_e32 v108, v108, v115
	v_mul_f32_e32 v109, v109, v115
	v_mul_f32_e32 v110, v110, v115
	v_mul_f32_e32 v111, v111, v115
	v_mul_f32_e32 v108, v12, v108
	v_mul_f32_e32 v109, v13, v109
	v_mul_f32_e32 v110, v14, v110
	v_mul_f32_e32 v111, v15, v111
	global_store_dwordx4 v120, v[108:111], s[6:7] offset:3072 nt
	s_add_u32 s6, s6, 0x40000
	s_addc_u32 s7, s7, 0
	s_sub_u32 s2, s2, 1
	s_cmp_lg_u32 s2, 0
	s_cbranch_scc1 .Lrms_final_loop
	s_waitcnt vmcnt(28)
	v_mul_f32_e32 v112, v132, v132
	v_fmac_f32_e32 v112, v133, v133
	v_fmac_f32_e32 v112, v134, v134
	v_fmac_f32_e32 v112, v135, v135
	v_fmac_f32_e32 v112, v136, v136
	v_fmac_f32_e32 v112, v137, v137
	v_fmac_f32_e32 v112, v138, v138
	v_fmac_f32_e32 v112, v139, v139
	v_fmac_f32_e32 v112, v140, v140
	v_fmac_f32_e32 v112, v141, v141
	v_fmac_f32_e32 v112, v142, v142
	v_fmac_f32_e32 v112, v143, v143
	v_fmac_f32_e32 v112, v144, v144
	v_fmac_f32_e32 v112, v145, v145
	v_fmac_f32_e32 v112, v146, v146
	v_fmac_f32_e32 v112, v147, v147
	s_waitcnt vmcnt(24)
	v_mul_f32_e32 v113, v166, v166
	v_fmac_f32_e32 v113, v167, v167
	v_fmac_f32_e32 v113, v168, v168
	v_fmac_f32_e32 v113, v169, v169
	v_fmac_f32_e32 v113, v170, v170
	v_fmac_f32_e32 v113, v171, v171
	v_fmac_f32_e32 v113, v172, v172
	v_fmac_f32_e32 v113, v173, v173
	v_fmac_f32_e32 v113, v174, v174
	v_fmac_f32_e32 v113, v175, v175
	v_fmac_f32_e32 v113, v176, v176
	v_fmac_f32_e32 v113, v177, v177
	v_fmac_f32_e32 v113, v178, v178
	v_fmac_f32_e32 v113, v179, v179
	v_fmac_f32_e32 v113, v180, v180
	v_fmac_f32_e32 v113, v181, v181
	s_waitcnt vmcnt(20)
	v_mul_f32_e32 v114, v182, v182
	v_fmac_f32_e32 v114, v183, v183
	v_fmac_f32_e32 v114, v184, v184
	v_fmac_f32_e32 v114, v185, v185
	v_fmac_f32_e32 v114, v186, v186
	v_fmac_f32_e32 v114, v187, v187
	v_fmac_f32_e32 v114, v188, v188
	v_fmac_f32_e32 v114, v189, v189
	v_fmac_f32_e32 v114, v190, v190
	v_fmac_f32_e32 v114, v191, v191
	v_fmac_f32_e32 v114, v192, v192
	v_fmac_f32_e32 v114, v193, v193
	v_fmac_f32_e32 v114, v194, v194
	v_fmac_f32_e32 v114, v195, v195
	v_fmac_f32_e32 v114, v196, v196
	v_fmac_f32_e32 v114, v197, v197
	s_waitcnt vmcnt(16)
	v_mul_f32_e32 v115, v228, v228
	v_fmac_f32_e32 v115, v229, v229
	v_fmac_f32_e32 v115, v230, v230
	v_fmac_f32_e32 v115, v231, v231
	v_fmac_f32_e32 v115, v232, v232
	v_fmac_f32_e32 v115, v233, v233
	v_fmac_f32_e32 v115, v234, v234
	v_fmac_f32_e32 v115, v235, v235
	v_fmac_f32_e32 v115, v236, v236
	v_fmac_f32_e32 v115, v237, v237
	v_fmac_f32_e32 v115, v238, v238
	v_fmac_f32_e32 v115, v239, v239
	v_fmac_f32_e32 v115, v240, v240
	v_fmac_f32_e32 v115, v241, v241
	v_fmac_f32_e32 v115, v242, v242
	v_fmac_f32_e32 v115, v243, v243
	ds_bpermute_b32 v116, v122, v112
	ds_bpermute_b32 v117, v122, v113
	ds_bpermute_b32 v118, v122, v114
	ds_bpermute_b32 v119, v122, v115
	s_waitcnt lgkmcnt(0)
	v_add_f32_e32 v112, v112, v116
	v_add_f32_e32 v113, v113, v117
	v_add_f32_e32 v114, v114, v118
	v_add_f32_e32 v115, v115, v119
	ds_bpermute_b32 v116, v123, v112
	ds_bpermute_b32 v117, v123, v113
	ds_bpermute_b32 v118, v123, v114
	ds_bpermute_b32 v119, v123, v115
	s_waitcnt lgkmcnt(0)
	v_add_f32_e32 v112, v112, v116
	v_add_f32_e32 v113, v113, v117
	v_add_f32_e32 v114, v114, v118
	v_add_f32_e32 v115, v115, v119
	ds_bpermute_b32 v116, v124, v112
	ds_bpermute_b32 v117, v124, v113
	ds_bpermute_b32 v118, v124, v114
	ds_bpermute_b32 v119, v124, v115
	s_waitcnt lgkmcnt(0)
	v_add_f32_e32 v112, v112, v116
	v_add_f32_e32 v113, v113, v117
	v_add_f32_e32 v114, v114, v118
	v_add_f32_e32 v115, v115, v119
	ds_bpermute_b32 v116, v125, v112
	ds_bpermute_b32 v117, v125, v113
	ds_bpermute_b32 v118, v125, v114
	ds_bpermute_b32 v119, v125, v115
	s_waitcnt lgkmcnt(0)
	v_add_f32_e32 v112, v112, v116
	v_add_f32_e32 v113, v113, v117
	v_add_f32_e32 v114, v114, v118
	v_add_f32_e32 v115, v115, v119
	ds_bpermute_b32 v116, v126, v112
	ds_bpermute_b32 v117, v126, v113
	ds_bpermute_b32 v118, v126, v114
	ds_bpermute_b32 v119, v126, v115
	s_waitcnt lgkmcnt(0)
	v_add_f32_e32 v112, v112, v116
	v_add_f32_e32 v113, v113, v117
	v_add_f32_e32 v114, v114, v118
	v_add_f32_e32 v115, v115, v119
	ds_bpermute_b32 v116, v127, v112
	ds_bpermute_b32 v117, v127, v113
	ds_bpermute_b32 v118, v127, v114
	ds_bpermute_b32 v119, v127, v115
	s_waitcnt lgkmcnt(0)
	v_add_f32_e32 v112, v112, v116
	v_add_f32_e32 v113, v113, v117
	v_add_f32_e32 v114, v114, v118
	v_add_f32_e32 v115, v115, v119
	v_fmamk_f32 v112, v112, 0x3a800000, v208
	v_fmamk_f32 v113, v113, 0x3a800000, v208
	v_fmamk_f32 v114, v114, 0x3a800000, v208
	v_fmamk_f32 v115, v115, 0x3a800000, v208
	v_rsq_f32_e32 v112, v112
	v_rsq_f32_e32 v113, v113
	v_rsq_f32_e32 v114, v114
	v_rsq_f32_e32 v115, v115
	s_nop 1
	v_mul_f32_e32 v132, v132, v112
	v_mul_f32_e32 v133, v133, v112
	v_mul_f32_e32 v134, v134, v112
	v_mul_f32_e32 v135, v135, v112
	v_mul_f32_e32 v132, v0, v132
	v_mul_f32_e32 v133, v1, v133
	v_mul_f32_e32 v134, v2, v134
	v_mul_f32_e32 v135, v3, v135
	global_store_dwordx4 v120, v[132:135], s[6:7] offset:0 nt
	v_mul_f32_e32 v136, v136, v112
	v_mul_f32_e32 v137, v137, v112
	v_mul_f32_e32 v138, v138, v112
	v_mul_f32_e32 v139, v139, v112
	v_mul_f32_e32 v136, v4, v136
	v_mul_f32_e32 v137, v5, v137
	v_mul_f32_e32 v138, v6, v138
	v_mul_f32_e32 v139, v7, v139
	global_store_dwordx4 v120, v[136:139], s[6:7] offset:1024 nt
	v_mul_f32_e32 v140, v140, v112
	v_mul_f32_e32 v141, v141, v112
	v_mul_f32_e32 v142, v142, v112
	v_mul_f32_e32 v143, v143, v112
	v_mul_f32_e32 v140, v8, v140
	v_mul_f32_e32 v141, v9, v141
	v_mul_f32_e32 v142, v10, v142
	v_mul_f32_e32 v143, v11, v143
	global_store_dwordx4 v120, v[140:143], s[6:7] offset:2048 nt
	v_mul_f32_e32 v144, v144, v112
	v_mul_f32_e32 v145, v145, v112
	v_mul_f32_e32 v146, v146, v112
	v_mul_f32_e32 v147, v147, v112
	v_mul_f32_e32 v144, v12, v144
	v_mul_f32_e32 v145, v13, v145
	v_mul_f32_e32 v146, v14, v146
	v_mul_f32_e32 v147, v15, v147
	global_store_dwordx4 v120, v[144:147], s[6:7] offset:3072 nt
	s_add_u32 s6, s6, 0x40000
	s_addc_u32 s7, s7, 0
	v_mul_f32_e32 v166, v166, v113
	v_mul_f32_e32 v167, v167, v113
	v_mul_f32_e32 v168, v168, v113
	v_mul_f32_e32 v169, v169, v113
	v_mul_f32_e32 v166, v0, v166
	v_mul_f32_e32 v167, v1, v167
	v_mul_f32_e32 v168, v2, v168
	v_mul_f32_e32 v169, v3, v169
	global_store_dwordx4 v120, v[166:169], s[6:7] offset:0 nt
	v_mul_f32_e32 v170, v170, v113
	v_mul_f32_e32 v171, v171, v113
	v_mul_f32_e32 v172, v172, v113
	v_mul_f32_e32 v173, v173, v113
	v_mul_f32_e32 v170, v4, v170
	v_mul_f32_e32 v171, v5, v171
	v_mul_f32_e32 v172, v6, v172
	v_mul_f32_e32 v173, v7, v173
	global_store_dwordx4 v120, v[170:173], s[6:7] offset:1024 nt
	v_mul_f32_e32 v174, v174, v113
	v_mul_f32_e32 v175, v175, v113
	v_mul_f32_e32 v176, v176, v113
	v_mul_f32_e32 v177, v177, v113
	v_mul_f32_e32 v174, v8, v174
	v_mul_f32_e32 v175, v9, v175
	v_mul_f32_e32 v176, v10, v176
	v_mul_f32_e32 v177, v11, v177
	global_store_dwordx4 v120, v[174:177], s[6:7] offset:2048 nt
	v_mul_f32_e32 v178, v178, v113
	v_mul_f32_e32 v179, v179, v113
	v_mul_f32_e32 v180, v180, v113
	v_mul_f32_e32 v181, v181, v113
	v_mul_f32_e32 v178, v12, v178
	v_mul_f32_e32 v179, v13, v179
	v_mul_f32_e32 v180, v14, v180
	v_mul_f32_e32 v181, v15, v181
	global_store_dwordx4 v120, v[178:181], s[6:7] offset:3072 nt
	s_add_u32 s6, s6, 0x40000
	s_addc_u32 s7, s7, 0
	v_mul_f32_e32 v182, v182, v114
	v_mul_f32_e32 v183, v183, v114
	v_mul_f32_e32 v184, v184, v114
	v_mul_f32_e32 v185, v185, v114
	v_mul_f32_e32 v182, v0, v182
	v_mul_f32_e32 v183, v1, v183
	v_mul_f32_e32 v184, v2, v184
	v_mul_f32_e32 v185, v3, v185
	global_store_dwordx4 v120, v[182:185], s[6:7] offset:0 nt
	v_mul_f32_e32 v186, v186, v114
	v_mul_f32_e32 v187, v187, v114
	v_mul_f32_e32 v188, v188, v114
	v_mul_f32_e32 v189, v189, v114
	v_mul_f32_e32 v186, v4, v186
	v_mul_f32_e32 v187, v5, v187
	v_mul_f32_e32 v188, v6, v188
	v_mul_f32_e32 v189, v7, v189
	global_store_dwordx4 v120, v[186:189], s[6:7] offset:1024 nt
	v_mul_f32_e32 v190, v190, v114
	v_mul_f32_e32 v191, v191, v114
	v_mul_f32_e32 v192, v192, v114
	v_mul_f32_e32 v193, v193, v114
	v_mul_f32_e32 v190, v8, v190
	v_mul_f32_e32 v191, v9, v191
	v_mul_f32_e32 v192, v10, v192
	v_mul_f32_e32 v193, v11, v193
	global_store_dwordx4 v120, v[190:193], s[6:7] offset:2048 nt
	v_mul_f32_e32 v194, v194, v114
	v_mul_f32_e32 v195, v195, v114
	v_mul_f32_e32 v196, v196, v114
	v_mul_f32_e32 v197, v197, v114
	v_mul_f32_e32 v194, v12, v194
	v_mul_f32_e32 v195, v13, v195
	v_mul_f32_e32 v196, v14, v196
	v_mul_f32_e32 v197, v15, v197
	global_store_dwordx4 v120, v[194:197], s[6:7] offset:3072 nt
	s_add_u32 s6, s6, 0x40000
	s_addc_u32 s7, s7, 0
	v_mul_f32_e32 v228, v228, v115
	v_mul_f32_e32 v229, v229, v115
	v_mul_f32_e32 v230, v230, v115
	v_mul_f32_e32 v231, v231, v115
	v_mul_f32_e32 v228, v0, v228
	v_mul_f32_e32 v229, v1, v229
	v_mul_f32_e32 v230, v2, v230
	v_mul_f32_e32 v231, v3, v231
	global_store_dwordx4 v120, v[228:231], s[6:7] offset:0 nt
	v_mul_f32_e32 v232, v232, v115
	v_mul_f32_e32 v233, v233, v115
	v_mul_f32_e32 v234, v234, v115
	v_mul_f32_e32 v235, v235, v115
	v_mul_f32_e32 v232, v4, v232
	v_mul_f32_e32 v233, v5, v233
	v_mul_f32_e32 v234, v6, v234
	v_mul_f32_e32 v235, v7, v235
	global_store_dwordx4 v120, v[232:235], s[6:7] offset:1024 nt
	v_mul_f32_e32 v236, v236, v115
	v_mul_f32_e32 v237, v237, v115
	v_mul_f32_e32 v238, v238, v115
	v_mul_f32_e32 v239, v239, v115
	v_mul_f32_e32 v236, v8, v236
	v_mul_f32_e32 v237, v9, v237
	v_mul_f32_e32 v238, v10, v238
	v_mul_f32_e32 v239, v11, v239
	global_store_dwordx4 v120, v[236:239], s[6:7] offset:2048 nt
	v_mul_f32_e32 v240, v240, v115
	v_mul_f32_e32 v241, v241, v115
	v_mul_f32_e32 v242, v242, v115
	v_mul_f32_e32 v243, v243, v115
	v_mul_f32_e32 v240, v12, v240
	v_mul_f32_e32 v241, v13, v241
	v_mul_f32_e32 v242, v14, v242
	v_mul_f32_e32 v243, v15, v243
	global_store_dwordx4 v120, v[240:243], s[6:7] offset:3072 nt
	s_add_u32 s6, s6, 0x40000
	s_addc_u32 s7, s7, 0

.LBB0_108:
	s_ashr_i32 s11, s39, 3
	s_mul_hi_i32 s13, s11, 0x6000
	s_mulk_i32 s11, 0x6000
	s_add_u32 s18, s31, s11
	s_addc_u32 s19, s34, s13
	v_readlane_b32 s20, v252, 25
	v_readlane_b32 s21, v252, 26
	v_lshl_add_u32 v154, s39, 8, v156
	v_lshl_add_u32 v155, s38, 8, v158
	v_lshlrev_b32_e32 v154, 12, v154
	v_lshlrev_b32_e32 v155, 2, v155
	v_add_u32_e32 v154, v154, v155
	s_andn2_b64 vcc, exec, s[6:7]
	s_waitcnt lgkmcnt(0)
	global_load_dwordx4 v[128:131], v155, s[18:19]
	global_load_dwordx4 v[132:135], v155, s[18:19] offset:16
	global_load_dwordx4 v[146:149], v155, s[18:19] offset:512
	global_load_dwordx4 v[150:153], v155, s[18:19] offset:528
	s_add_u32 s100, s20, 0x0
	s_addc_u32 s101, s21, 0
	global_load_dwordx4 v[166:169], v154, s[100:101] nt
	global_load_dwordx4 v[170:173], v154, s[100:101] offset:16 nt
	s_add_u32 s100, s20, 0x10000
	s_addc_u32 s101, s21, 0
	global_load_dwordx4 v[174:177], v154, s[100:101] nt
	global_load_dwordx4 v[178:181], v154, s[100:101] offset:16 nt
	s_add_u32 s100, s20, 0x20000
	s_addc_u32 s101, s21, 0
	global_load_dwordx4 v[182:185], v154, s[100:101] nt
	global_load_dwordx4 v[186:189], v154, s[100:101] offset:16 nt
	s_add_u32 s100, s20, 0x30000
	s_addc_u32 s101, s21, 0
	global_load_dwordx4 v[190:193], v154, s[100:101] nt
	global_load_dwordx4 v[194:197], v154, s[100:101] offset:16 nt
	s_add_u32 s100, s20, 0x80000
	s_addc_u32 s101, s21, 0
	global_load_dwordx4 v[198:201], v154, s[100:101] nt
	global_load_dwordx4 v[202:205], v154, s[100:101] offset:16 nt
	s_add_u32 s100, s20, 0x90000
	s_addc_u32 s101, s21, 0
	global_load_dwordx4 v[228:231], v154, s[100:101] nt
	global_load_dwordx4 v[232:235], v154, s[100:101] offset:16 nt
	s_waitcnt vmcnt(10)
	v_pk_fma_f32 v[166:167], v[124:125], v[128:129], v[166:167]
	v_pk_fma_f32 v[168:169], v[126:127], v[130:131], v[168:169]
	v_pk_fma_f32 v[170:171], v[120:121], v[132:133], v[170:171]
	v_pk_fma_f32 v[172:173], v[122:123], v[134:135], v[172:173]
	s_add_u32 s18, s8, 0x0
	s_addc_u32 s19, s9, 0
	global_store_dwordx4 v154, v[166:169], s[18:19]
	global_store_dwordx4 v154, v[170:173], s[18:19] offset:16
	s_add_u32 s100, s20, 0xa0000
	s_addc_u32 s101, s21, 0
	global_load_dwordx4 v[166:169], v154, s[100:101] nt
	global_load_dwordx4 v[170:173], v154, s[100:101] offset:16 nt
	s_waitcnt vmcnt(12)
	v_pk_fma_f32 v[174:175], v[116:117], v[128:129], v[174:175]
	v_pk_fma_f32 v[176:177], v[118:119], v[130:131], v[176:177]
	v_pk_fma_f32 v[178:179], v[112:113], v[132:133], v[178:179]
	v_pk_fma_f32 v[180:181], v[114:115], v[134:135], v[180:181]
	s_add_u32 s18, s8, 0x10000
	s_addc_u32 s19, s9, 0
	global_store_dwordx4 v154, v[174:177], s[18:19]
	global_store_dwordx4 v154, v[178:181], s[18:19] offset:16
	s_add_u32 s100, s20, 0xb0000
	s_addc_u32 s101, s21, 0
	global_load_dwordx4 v[174:177], v154, s[100:101] nt
	global_load_dwordx4 v[178:181], v154, s[100:101] offset:16 nt
	s_waitcnt vmcnt(14)
	v_pk_fma_f32 v[182:183], v[108:109], v[128:129], v[182:183]
	v_pk_fma_f32 v[184:185], v[110:111], v[130:131], v[184:185]
	v_pk_fma_f32 v[186:187], v[104:105], v[132:133], v[186:187]
	v_pk_fma_f32 v[188:189], v[106:107], v[134:135], v[188:189]
	s_add_u32 s18, s8, 0x20000
	s_addc_u32 s19, s9, 0
	global_store_dwordx4 v154, v[182:185], s[18:19]
	global_store_dwordx4 v154, v[186:189], s[18:19] offset:16
	s_add_u32 s100, s20, 0x0
	s_addc_u32 s101, s21, 0
	global_load_dwordx4 v[182:185], v154, s[100:101] offset:512 nt
	global_load_dwordx4 v[186:189], v154, s[100:101] offset:528 nt
	s_waitcnt vmcnt(16)
	v_pk_fma_f32 v[190:191], v[100:101], v[128:129], v[190:191]
	v_pk_fma_f32 v[192:193], v[102:103], v[130:131], v[192:193]
	v_pk_fma_f32 v[194:195], v[96:97], v[132:133], v[194:195]
	v_pk_fma_f32 v[196:197], v[98:99], v[134:135], v[196:197]
	s_add_u32 s18, s8, 0x30000
	s_addc_u32 s19, s9, 0
	global_store_dwordx4 v154, v[190:193], s[18:19]
	global_store_dwordx4 v154, v[194:197], s[18:19] offset:16
	s_add_u32 s100, s20, 0x10000
	s_addc_u32 s101, s21, 0
	global_load_dwordx4 v[190:193], v154, s[100:101] offset:512 nt
	global_load_dwordx4 v[194:197], v154, s[100:101] offset:528 nt
	s_waitcnt vmcnt(18)
	v_pk_fma_f32 v[198:199], v[92:93], v[128:129], v[198:199]
	v_pk_fma_f32 v[200:201], v[94:95], v[130:131], v[200:201]
	v_pk_fma_f32 v[202:203], v[88:89], v[132:133], v[202:203]
	v_pk_fma_f32 v[204:205], v[90:91], v[134:135], v[204:205]
	s_add_u32 s18, s8, 0x80000
	s_addc_u32 s19, s9, 0
	global_store_dwordx4 v154, v[198:201], s[18:19]
	global_store_dwordx4 v154, v[202:205], s[18:19] offset:16
	s_add_u32 s100, s20, 0x20000
	s_addc_u32 s101, s21, 0
	global_load_dwordx4 v[198:201], v154, s[100:101] offset:512 nt
	global_load_dwordx4 v[202:205], v154, s[100:101] offset:528 nt
	s_waitcnt vmcnt(20)
	v_pk_fma_f32 v[228:229], v[84:85], v[128:129], v[228:229]
	v_pk_fma_f32 v[230:231], v[86:87], v[130:131], v[230:231]
	v_pk_fma_f32 v[232:233], v[80:81], v[132:133], v[232:233]
	v_pk_fma_f32 v[234:235], v[82:83], v[134:135], v[234:235]
	s_add_u32 s18, s8, 0x90000
	s_addc_u32 s19, s9, 0
	global_store_dwordx4 v154, v[228:231], s[18:19]
	global_store_dwordx4 v154, v[232:235], s[18:19] offset:16
	s_add_u32 s100, s20, 0x30000
	s_addc_u32 s101, s21, 0
	global_load_dwordx4 v[228:231], v154, s[100:101] offset:512 nt
	global_load_dwordx4 v[232:235], v154, s[100:101] offset:528 nt
	s_waitcnt vmcnt(20)
	v_pk_fma_f32 v[166:167], v[76:77], v[128:129], v[166:167]
	v_pk_fma_f32 v[168:169], v[78:79], v[130:131], v[168:169]
	v_pk_fma_f32 v[170:171], v[72:73], v[132:133], v[170:171]
	v_pk_fma_f32 v[172:173], v[74:75], v[134:135], v[172:173]
	s_add_u32 s18, s8, 0xa0000
	s_addc_u32 s19, s9, 0
	global_store_dwordx4 v154, v[166:169], s[18:19]
	global_store_dwordx4 v154, v[170:173], s[18:19] offset:16
	s_add_u32 s100, s20, 0x80000
	s_addc_u32 s101, s21, 0
	global_load_dwordx4 v[166:169], v154, s[100:101] offset:512 nt
	global_load_dwordx4 v[170:173], v154, s[100:101] offset:528 nt
	s_waitcnt vmcnt(20)
	v_pk_fma_f32 v[174:175], v[68:69], v[128:129], v[174:175]
	v_pk_fma_f32 v[176:177], v[70:71], v[130:131], v[176:177]
	v_pk_fma_f32 v[178:179], v[56:57], v[132:133], v[178:179]
	v_pk_fma_f32 v[180:181], v[58:59], v[134:135], v[180:181]
	s_add_u32 s18, s8, 0xb0000
	s_addc_u32 s19, s9, 0
	global_store_dwordx4 v154, v[174:177], s[18:19]
	global_store_dwordx4 v154, v[178:181], s[18:19] offset:16
	s_add_u32 s100, s20, 0x90000
	s_addc_u32 s101, s21, 0
	global_load_dwordx4 v[174:177], v154, s[100:101] offset:512 nt
	global_load_dwordx4 v[178:181], v154, s[100:101] offset:528 nt
	s_waitcnt vmcnt(20)
	v_pk_fma_f32 v[182:183], v[64:65], v[146:147], v[182:183]
	v_pk_fma_f32 v[184:185], v[66:67], v[148:149], v[184:185]
	v_pk_fma_f32 v[186:187], v[60:61], v[150:151], v[186:187]
	v_pk_fma_f32 v[188:189], v[62:63], v[152:153], v[188:189]
	s_add_u32 s18, s8, 0x0
	s_addc_u32 s19, s9, 0
	global_store_dwordx4 v154, v[182:185], s[18:19] offset:512
	global_store_dwordx4 v154, v[186:189], s[18:19] offset:528
	s_add_u32 s100, s20, 0xa0000
	s_addc_u32 s101, s21, 0
	global_load_dwordx4 v[182:185], v154, s[100:101] offset:512 nt
	global_load_dwordx4 v[186:189], v154, s[100:101] offset:528 nt
	s_waitcnt vmcnt(20)
	v_pk_fma_f32 v[190:191], v[52:53], v[146:147], v[190:191]
	v_pk_fma_f32 v[192:193], v[54:55], v[148:149], v[192:193]
	v_pk_fma_f32 v[194:195], v[48:49], v[150:151], v[194:195]
	v_pk_fma_f32 v[196:197], v[50:51], v[152:153], v[196:197]
	s_add_u32 s18, s8, 0x10000
	s_addc_u32 s19, s9, 0
	global_store_dwordx4 v154, v[190:193], s[18:19] offset:512
	global_store_dwordx4 v154, v[194:197], s[18:19] offset:528
	s_add_u32 s100, s20, 0xb0000
	s_addc_u32 s101, s21, 0
	global_load_dwordx4 v[190:193], v154, s[100:101] offset:512 nt
	global_load_dwordx4 v[194:197], v154, s[100:101] offset:528 nt
	s_waitcnt vmcnt(20)
	v_pk_fma_f32 v[198:199], v[44:45], v[146:147], v[198:199]
	v_pk_fma_f32 v[200:201], v[46:47], v[148:149], v[200:201]
	v_pk_fma_f32 v[202:203], v[40:41], v[150:151], v[202:203]
	v_pk_fma_f32 v[204:205], v[42:43], v[152:153], v[204:205]
	s_add_u32 s18, s8, 0x20000
	s_addc_u32 s19, s9, 0
	global_store_dwordx4 v154, v[198:201], s[18:19] offset:512
	global_store_dwordx4 v154, v[202:205], s[18:19] offset:528
	s_waitcnt vmcnt(18)
	v_pk_fma_f32 v[228:229], v[36:37], v[146:147], v[228:229]
	v_pk_fma_f32 v[230:231], v[38:39], v[148:149], v[230:231]
	v_pk_fma_f32 v[232:233], v[32:33], v[150:151], v[232:233]
	v_pk_fma_f32 v[234:235], v[34:35], v[152:153], v[234:235]
	s_add_u32 s18, s8, 0x30000
	s_addc_u32 s19, s9, 0
	global_store_dwordx4 v154, v[228:231], s[18:19] offset:512
	global_store_dwordx4 v154, v[232:235], s[18:19] offset:528
	s_waitcnt vmcnt(16)
	v_pk_fma_f32 v[166:167], v[28:29], v[146:147], v[166:167]
	v_pk_fma_f32 v[168:169], v[30:31], v[148:149], v[168:169]
	v_pk_fma_f32 v[170:171], v[24:25], v[150:151], v[170:171]
	v_pk_fma_f32 v[172:173], v[26:27], v[152:153], v[172:173]
	s_add_u32 s18, s8, 0x80000
	s_addc_u32 s19, s9, 0
	global_store_dwordx4 v154, v[166:169], s[18:19] offset:512
	global_store_dwordx4 v154, v[170:173], s[18:19] offset:528
	s_waitcnt vmcnt(14)
	v_pk_fma_f32 v[174:175], v[20:21], v[146:147], v[174:175]
	v_pk_fma_f32 v[176:177], v[22:23], v[148:149], v[176:177]
	v_pk_fma_f32 v[178:179], v[16:17], v[150:151], v[178:179]
	v_pk_fma_f32 v[180:181], v[18:19], v[152:153], v[180:181]
	s_add_u32 s18, s8, 0x90000
	s_addc_u32 s19, s9, 0
	global_store_dwordx4 v154, v[174:177], s[18:19] offset:512
	global_store_dwordx4 v154, v[178:181], s[18:19] offset:528
	s_waitcnt vmcnt(12)
	v_pk_fma_f32 v[182:183], v[12:13], v[146:147], v[182:183]
	v_pk_fma_f32 v[184:185], v[14:15], v[148:149], v[184:185]
	v_pk_fma_f32 v[186:187], v[8:9], v[150:151], v[186:187]
	v_pk_fma_f32 v[188:189], v[10:11], v[152:153], v[188:189]
	s_add_u32 s18, s8, 0xa0000
	s_addc_u32 s19, s9, 0
	global_store_dwordx4 v154, v[182:185], s[18:19] offset:512
	global_store_dwordx4 v154, v[186:189], s[18:19] offset:528
	s_waitcnt vmcnt(10)
	v_pk_fma_f32 v[190:191], v[4:5], v[146:147], v[190:191]
	v_pk_fma_f32 v[192:193], v[6:7], v[148:149], v[192:193]
	v_pk_fma_f32 v[194:195], v[0:1], v[150:151], v[194:195]
	v_pk_fma_f32 v[196:197], v[2:3], v[152:153], v[196:197]
	s_add_u32 s18, s8, 0xb0000
	s_addc_u32 s19, s9, 0
	global_store_dwordx4 v154, v[190:193], s[18:19] offset:512
	global_store_dwordx4 v154, v[194:197], s[18:19] offset:528
	s_mov_b64 s[18:19], -1
	s_cbranch_vccnz .LBB0_97
	s_and_b64 vcc, exec, s[4:5]
	s_cbranch_vccnz .LBB0_96
	s_barrier
	s_branch .LBB0_96

.LBB0_130:
	v_lshl_add_u32 v150, s41, 8, v144
	v_lshl_add_u32 v151, s40, 8, v146
	v_lshlrev_b32_e32 v150, 10, v150
	v_add_lshl_u32 v138, v150, v151, 1
	v_add_u32_e32 v139, 0x8000, v138
	v_add_u32_e32 v140, 0x10000, v138
	v_add_u32_e32 v141, 0x18000, v138
	v_add_u32_e32 v142, 0x40000, v138
	v_add_u32_e32 v143, 0x48000, v138
	v_add_u32_e32 v148, 0x50000, v138
	v_add_u32_e32 v149, 0x58000, v138
	s_andn2_b64 vcc, exec, s[8:9]
	s_waitcnt lgkmcnt(0)
	global_load_dwordx4 v[166:169], v138, s[12:13] nt
	global_load_dwordx4 v[170:173], v138, s[12:13] offset:256 nt
	global_load_dwordx4 v[174:177], v139, s[12:13] nt
	global_load_dwordx4 v[178:181], v139, s[12:13] offset:256 nt
	global_load_dwordx4 v[182:185], v140, s[12:13] nt
	global_load_dwordx4 v[186:189], v140, s[12:13] offset:256 nt
	global_load_dwordx4 v[190:193], v141, s[12:13] nt
	global_load_dwordx4 v[194:197], v141, s[12:13] offset:256 nt
	global_load_dwordx4 v[198:201], v142, s[12:13] nt
	global_load_dwordx4 v[202:205], v142, s[12:13] offset:256 nt
	global_load_dwordx4 v[228:231], v143, s[12:13] nt
	global_load_dwordx4 v[232:235], v143, s[12:13] offset:256 nt
	global_load_dwordx4 v[236:239], v148, s[12:13] nt
	global_load_dwordx4 v[156:159], v148, s[12:13] offset:256 nt
	s_waitcnt vmcnt(13)
	v_lshlrev_b32_e32 v150, 16, v166
	v_and_b32_e32 v151, 0xffff0000, v166
	v_pk_mul_f32 v[124:125], v[124:125], v[150:151]
	v_lshlrev_b32_e32 v150, 16, v167
	v_and_b32_e32 v151, 0xffff0000, v167
	v_pk_mul_f32 v[126:127], v[126:127], v[150:151]
	v_lshlrev_b32_e32 v150, 16, v168
	v_and_b32_e32 v151, 0xffff0000, v168
	v_pk_mul_f32 v[120:121], v[120:121], v[150:151]
	v_lshlrev_b32_e32 v150, 16, v169
	v_and_b32_e32 v151, 0xffff0000, v169
	v_pk_mul_f32 v[122:123], v[122:123], v[150:151]
	v_cvt_pk_bf16_f32 v166, v124, v125
	v_cvt_pk_bf16_f32 v167, v126, v127
	v_cvt_pk_bf16_f32 v168, v120, v121
	v_cvt_pk_bf16_f32 v169, v122, v123
	global_store_dwordx4 v138, v[166:169], s[10:11]
	global_load_dwordx4 v[166:169], v149, s[12:13] nt
	s_waitcnt vmcnt(14)
	v_lshlrev_b32_e32 v150, 16, v170
	v_and_b32_e32 v151, 0xffff0000, v170
	v_pk_mul_f32 v[116:117], v[116:117], v[150:151]
	v_lshlrev_b32_e32 v150, 16, v171
	v_and_b32_e32 v151, 0xffff0000, v171
	v_pk_mul_f32 v[118:119], v[118:119], v[150:151]
	v_lshlrev_b32_e32 v150, 16, v172
	v_and_b32_e32 v151, 0xffff0000, v172
	v_pk_mul_f32 v[112:113], v[112:113], v[150:151]
	v_lshlrev_b32_e32 v150, 16, v173
	v_and_b32_e32 v151, 0xffff0000, v173
	v_pk_mul_f32 v[114:115], v[114:115], v[150:151]
	v_cvt_pk_bf16_f32 v170, v116, v117
	v_cvt_pk_bf16_f32 v171, v118, v119
	v_cvt_pk_bf16_f32 v172, v112, v113
	v_cvt_pk_bf16_f32 v173, v114, v115
	global_store_dwordx4 v138, v[170:173], s[10:11] offset:256
	global_load_dwordx4 v[170:173], v149, s[12:13] offset:256 nt
	s_waitcnt vmcnt(15)
	v_lshlrev_b32_e32 v150, 16, v174
	v_and_b32_e32 v151, 0xffff0000, v174
	v_pk_mul_f32 v[108:109], v[108:109], v[150:151]
	v_lshlrev_b32_e32 v150, 16, v175
	v_and_b32_e32 v151, 0xffff0000, v175
	v_pk_mul_f32 v[110:111], v[110:111], v[150:151]
	v_lshlrev_b32_e32 v150, 16, v176
	v_and_b32_e32 v151, 0xffff0000, v176
	v_pk_mul_f32 v[104:105], v[104:105], v[150:151]
	v_lshlrev_b32_e32 v150, 16, v177
	v_and_b32_e32 v151, 0xffff0000, v177
	v_pk_mul_f32 v[106:107], v[106:107], v[150:151]
	v_cvt_pk_bf16_f32 v174, v108, v109
	v_cvt_pk_bf16_f32 v175, v110, v111
	v_cvt_pk_bf16_f32 v176, v104, v105
	v_cvt_pk_bf16_f32 v177, v106, v107
	global_store_dwordx4 v139, v[174:177], s[10:11]
	s_waitcnt vmcnt(15)
	v_lshlrev_b32_e32 v150, 16, v178
	v_and_b32_e32 v151, 0xffff0000, v178
	v_pk_mul_f32 v[100:101], v[100:101], v[150:151]
	v_lshlrev_b32_e32 v150, 16, v179
	v_and_b32_e32 v151, 0xffff0000, v179
	v_pk_mul_f32 v[102:103], v[102:103], v[150:151]
	v_lshlrev_b32_e32 v150, 16, v180
	v_and_b32_e32 v151, 0xffff0000, v180
	v_pk_mul_f32 v[96:97], v[96:97], v[150:151]
	v_lshlrev_b32_e32 v150, 16, v181
	v_and_b32_e32 v151, 0xffff0000, v181
	v_pk_mul_f32 v[98:99], v[98:99], v[150:151]
	v_cvt_pk_bf16_f32 v178, v100, v101
	v_cvt_pk_bf16_f32 v179, v102, v103
	v_cvt_pk_bf16_f32 v180, v96, v97
	v_cvt_pk_bf16_f32 v181, v98, v99
	global_store_dwordx4 v139, v[178:181], s[10:11] offset:256
	s_waitcnt vmcnt(15)
	v_lshlrev_b32_e32 v150, 16, v182
	v_and_b32_e32 v151, 0xffff0000, v182
	v_pk_mul_f32 v[92:93], v[92:93], v[150:151]
	v_lshlrev_b32_e32 v150, 16, v183
	v_and_b32_e32 v151, 0xffff0000, v183
	v_pk_mul_f32 v[94:95], v[94:95], v[150:151]
	v_lshlrev_b32_e32 v150, 16, v184
	v_and_b32_e32 v151, 0xffff0000, v184
	v_pk_mul_f32 v[88:89], v[88:89], v[150:151]
	v_lshlrev_b32_e32 v150, 16, v185
	v_and_b32_e32 v151, 0xffff0000, v185
	v_pk_mul_f32 v[90:91], v[90:91], v[150:151]
	v_cvt_pk_bf16_f32 v182, v92, v93
	v_cvt_pk_bf16_f32 v183, v94, v95
	v_cvt_pk_bf16_f32 v184, v88, v89
	v_cvt_pk_bf16_f32 v185, v90, v91
	global_store_dwordx4 v140, v[182:185], s[10:11]
	s_waitcnt vmcnt(15)
	v_lshlrev_b32_e32 v150, 16, v186
	v_and_b32_e32 v151, 0xffff0000, v186
	v_pk_mul_f32 v[84:85], v[84:85], v[150:151]
	v_lshlrev_b32_e32 v150, 16, v187
	v_and_b32_e32 v151, 0xffff0000, v187
	v_pk_mul_f32 v[86:87], v[86:87], v[150:151]
	v_lshlrev_b32_e32 v150, 16, v188
	v_and_b32_e32 v151, 0xffff0000, v188
	v_pk_mul_f32 v[80:81], v[80:81], v[150:151]
	v_lshlrev_b32_e32 v150, 16, v189
	v_and_b32_e32 v151, 0xffff0000, v189
	v_pk_mul_f32 v[82:83], v[82:83], v[150:151]
	v_cvt_pk_bf16_f32 v186, v84, v85
	v_cvt_pk_bf16_f32 v187, v86, v87
	v_cvt_pk_bf16_f32 v188, v80, v81
	v_cvt_pk_bf16_f32 v189, v82, v83
	global_store_dwordx4 v140, v[186:189], s[10:11] offset:256
	s_waitcnt vmcnt(15)
	v_lshlrev_b32_e32 v150, 16, v190
	v_and_b32_e32 v151, 0xffff0000, v190
	v_pk_mul_f32 v[76:77], v[76:77], v[150:151]
	v_lshlrev_b32_e32 v150, 16, v191
	v_and_b32_e32 v151, 0xffff0000, v191
	v_pk_mul_f32 v[78:79], v[78:79], v[150:151]
	v_lshlrev_b32_e32 v150, 16, v192
	v_and_b32_e32 v151, 0xffff0000, v192
	v_pk_mul_f32 v[72:73], v[72:73], v[150:151]
	v_lshlrev_b32_e32 v150, 16, v193
	v_and_b32_e32 v151, 0xffff0000, v193
	v_pk_mul_f32 v[74:75], v[74:75], v[150:151]
	v_cvt_pk_bf16_f32 v190, v76, v77
	v_cvt_pk_bf16_f32 v191, v78, v79
	v_cvt_pk_bf16_f32 v192, v72, v73
	v_cvt_pk_bf16_f32 v193, v74, v75
	global_store_dwordx4 v141, v[190:193], s[10:11]
	s_waitcnt vmcnt(15)
	v_lshlrev_b32_e32 v150, 16, v194
	v_and_b32_e32 v151, 0xffff0000, v194
	v_pk_mul_f32 v[68:69], v[68:69], v[150:151]
	v_lshlrev_b32_e32 v150, 16, v195
	v_and_b32_e32 v151, 0xffff0000, v195
	v_pk_mul_f32 v[70:71], v[70:71], v[150:151]
	v_lshlrev_b32_e32 v150, 16, v196
	v_and_b32_e32 v151, 0xffff0000, v196
	v_pk_mul_f32 v[64:65], v[64:65], v[150:151]
	v_lshlrev_b32_e32 v150, 16, v197
	v_and_b32_e32 v151, 0xffff0000, v197
	v_pk_mul_f32 v[66:67], v[66:67], v[150:151]
	v_cvt_pk_bf16_f32 v194, v68, v69
	v_cvt_pk_bf16_f32 v195, v70, v71
	v_cvt_pk_bf16_f32 v196, v64, v65
	v_cvt_pk_bf16_f32 v197, v66, v67
	global_store_dwordx4 v141, v[194:197], s[10:11] offset:256
	s_waitcnt vmcnt(15)
	v_lshlrev_b32_e32 v150, 16, v198
	v_and_b32_e32 v151, 0xffff0000, v198
	v_pk_mul_f32 v[60:61], v[60:61], v[150:151]
	v_lshlrev_b32_e32 v150, 16, v199
	v_and_b32_e32 v151, 0xffff0000, v199
	v_pk_mul_f32 v[62:63], v[62:63], v[150:151]
	v_lshlrev_b32_e32 v150, 16, v200
	v_and_b32_e32 v151, 0xffff0000, v200
	v_pk_mul_f32 v[56:57], v[56:57], v[150:151]
	v_lshlrev_b32_e32 v150, 16, v201
	v_and_b32_e32 v151, 0xffff0000, v201
	v_pk_mul_f32 v[58:59], v[58:59], v[150:151]
	v_cvt_pk_bf16_f32 v198, v60, v61
	v_cvt_pk_bf16_f32 v199, v62, v63
	v_cvt_pk_bf16_f32 v200, v56, v57
	v_cvt_pk_bf16_f32 v201, v58, v59
	global_store_dwordx4 v142, v[198:201], s[10:11]
	s_waitcnt vmcnt(15)
	v_lshlrev_b32_e32 v150, 16, v202
	v_and_b32_e32 v151, 0xffff0000, v202
	v_pk_mul_f32 v[52:53], v[52:53], v[150:151]
	v_lshlrev_b32_e32 v150, 16, v203
	v_and_b32_e32 v151, 0xffff0000, v203
	v_pk_mul_f32 v[54:55], v[54:55], v[150:151]
	v_lshlrev_b32_e32 v150, 16, v204
	v_and_b32_e32 v151, 0xffff0000, v204
	v_pk_mul_f32 v[48:49], v[48:49], v[150:151]
	v_lshlrev_b32_e32 v150, 16, v205
	v_and_b32_e32 v151, 0xffff0000, v205
	v_pk_mul_f32 v[50:51], v[50:51], v[150:151]
	v_cvt_pk_bf16_f32 v202, v52, v53
	v_cvt_pk_bf16_f32 v203, v54, v55
	v_cvt_pk_bf16_f32 v204, v48, v49
	v_cvt_pk_bf16_f32 v205, v50, v51
	global_store_dwordx4 v142, v[202:205], s[10:11] offset:256
	s_waitcnt vmcnt(15)
	v_lshlrev_b32_e32 v150, 16, v228
	v_and_b32_e32 v151, 0xffff0000, v228
	v_pk_mul_f32 v[44:45], v[44:45], v[150:151]
	v_lshlrev_b32_e32 v150, 16, v229
	v_and_b32_e32 v151, 0xffff0000, v229
	v_pk_mul_f32 v[46:47], v[46:47], v[150:151]
	v_lshlrev_b32_e32 v150, 16, v230
	v_and_b32_e32 v151, 0xffff0000, v230
	v_pk_mul_f32 v[40:41], v[40:41], v[150:151]
	v_lshlrev_b32_e32 v150, 16, v231
	v_and_b32_e32 v151, 0xffff0000, v231
	v_pk_mul_f32 v[42:43], v[42:43], v[150:151]
	v_cvt_pk_bf16_f32 v228, v44, v45
	v_cvt_pk_bf16_f32 v229, v46, v47
	v_cvt_pk_bf16_f32 v230, v40, v41
	v_cvt_pk_bf16_f32 v231, v42, v43
	global_store_dwordx4 v143, v[228:231], s[10:11]
	s_waitcnt vmcnt(15)
	v_lshlrev_b32_e32 v150, 16, v232
	v_and_b32_e32 v151, 0xffff0000, v232
	v_pk_mul_f32 v[36:37], v[36:37], v[150:151]
	v_lshlrev_b32_e32 v150, 16, v233
	v_and_b32_e32 v151, 0xffff0000, v233
	v_pk_mul_f32 v[38:39], v[38:39], v[150:151]
	v_lshlrev_b32_e32 v150, 16, v234
	v_and_b32_e32 v151, 0xffff0000, v234
	v_pk_mul_f32 v[32:33], v[32:33], v[150:151]
	v_lshlrev_b32_e32 v150, 16, v235
	v_and_b32_e32 v151, 0xffff0000, v235
	v_pk_mul_f32 v[34:35], v[34:35], v[150:151]
	v_cvt_pk_bf16_f32 v232, v36, v37
	v_cvt_pk_bf16_f32 v233, v38, v39
	v_cvt_pk_bf16_f32 v234, v32, v33
	v_cvt_pk_bf16_f32 v235, v34, v35
	global_store_dwordx4 v143, v[232:235], s[10:11] offset:256
	s_waitcnt vmcnt(15)
	v_lshlrev_b32_e32 v150, 16, v236
	v_and_b32_e32 v151, 0xffff0000, v236
	v_pk_mul_f32 v[28:29], v[28:29], v[150:151]
	v_lshlrev_b32_e32 v150, 16, v237
	v_and_b32_e32 v151, 0xffff0000, v237
	v_pk_mul_f32 v[30:31], v[30:31], v[150:151]
	v_lshlrev_b32_e32 v150, 16, v238
	v_and_b32_e32 v151, 0xffff0000, v238
	v_pk_mul_f32 v[24:25], v[24:25], v[150:151]
	v_lshlrev_b32_e32 v150, 16, v239
	v_and_b32_e32 v151, 0xffff0000, v239
	v_pk_mul_f32 v[26:27], v[26:27], v[150:151]
	v_cvt_pk_bf16_f32 v236, v28, v29
	v_cvt_pk_bf16_f32 v237, v30, v31
	v_cvt_pk_bf16_f32 v238, v24, v25
	v_cvt_pk_bf16_f32 v239, v26, v27
	global_store_dwordx4 v148, v[236:239], s[10:11]
	s_waitcnt vmcnt(15)
	v_lshlrev_b32_e32 v150, 16, v156
	v_and_b32_e32 v151, 0xffff0000, v156
	v_pk_mul_f32 v[20:21], v[20:21], v[150:151]
	v_lshlrev_b32_e32 v150, 16, v157
	v_and_b32_e32 v151, 0xffff0000, v157
	v_pk_mul_f32 v[22:23], v[22:23], v[150:151]
	v_lshlrev_b32_e32 v150, 16, v158
	v_and_b32_e32 v151, 0xffff0000, v158
	v_pk_mul_f32 v[16:17], v[16:17], v[150:151]
	v_lshlrev_b32_e32 v150, 16, v159
	v_and_b32_e32 v151, 0xffff0000, v159
	v_pk_mul_f32 v[18:19], v[18:19], v[150:151]
	v_cvt_pk_bf16_f32 v156, v20, v21
	v_cvt_pk_bf16_f32 v157, v22, v23
	v_cvt_pk_bf16_f32 v158, v16, v17
	v_cvt_pk_bf16_f32 v159, v18, v19
	global_store_dwordx4 v148, v[156:159], s[10:11] offset:256
	s_waitcnt vmcnt(14)
	v_lshlrev_b32_e32 v150, 16, v166
	v_and_b32_e32 v151, 0xffff0000, v166
	v_pk_mul_f32 v[12:13], v[12:13], v[150:151]
	v_lshlrev_b32_e32 v150, 16, v167
	v_and_b32_e32 v151, 0xffff0000, v167
	v_pk_mul_f32 v[14:15], v[14:15], v[150:151]
	v_lshlrev_b32_e32 v150, 16, v168
	v_and_b32_e32 v151, 0xffff0000, v168
	v_pk_mul_f32 v[8:9], v[8:9], v[150:151]
	v_lshlrev_b32_e32 v150, 16, v169
	v_and_b32_e32 v151, 0xffff0000, v169
	v_pk_mul_f32 v[10:11], v[10:11], v[150:151]
	v_cvt_pk_bf16_f32 v166, v12, v13
	v_cvt_pk_bf16_f32 v167, v14, v15
	v_cvt_pk_bf16_f32 v168, v8, v9
	v_cvt_pk_bf16_f32 v169, v10, v11
	global_store_dwordx4 v149, v[166:169], s[10:11]
	s_waitcnt vmcnt(13)
	v_lshlrev_b32_e32 v150, 16, v170
	v_and_b32_e32 v151, 0xffff0000, v170
	v_pk_mul_f32 v[4:5], v[4:5], v[150:151]
	v_lshlrev_b32_e32 v150, 16, v171
	v_and_b32_e32 v151, 0xffff0000, v171
	v_pk_mul_f32 v[6:7], v[6:7], v[150:151]
	v_lshlrev_b32_e32 v150, 16, v172
	v_and_b32_e32 v151, 0xffff0000, v172
	v_pk_mul_f32 v[0:1], v[0:1], v[150:151]
	v_lshlrev_b32_e32 v150, 16, v173
	v_and_b32_e32 v151, 0xffff0000, v173
	v_pk_mul_f32 v[2:3], v[2:3], v[150:151]
	v_cvt_pk_bf16_f32 v170, v4, v5
	v_cvt_pk_bf16_f32 v171, v6, v7
	v_cvt_pk_bf16_f32 v172, v0, v1
	v_cvt_pk_bf16_f32 v173, v2, v3
	global_store_dwordx4 v149, v[170:173], s[10:11] offset:256
	s_mov_b64 s[22:23], -1
	s_cbranch_vccnz .LBB0_119
	s_and_b64 vcc, exec, s[6:7]
	s_cbranch_vccnz .LBB0_118
	s_barrier
	s_branch .LBB0_118

.LBB0_150:
	v_lshl_add_u32 v150, s41, 8, v144
	v_lshl_add_u32 v151, s2, 8, v146
	v_lshlrev_b32_e32 v150, 10, v150
	v_add_lshl_u32 v138, v150, v151, 1
	v_add_u32_e32 v139, 0x8000, v138
	v_add_u32_e32 v140, 0x10000, v138
	v_add_u32_e32 v141, 0x18000, v138
	v_add_u32_e32 v142, 0x40000, v138
	v_add_u32_e32 v143, 0x48000, v138
	v_add_u32_e32 v148, 0x50000, v138
	v_add_u32_e32 v149, 0x58000, v138
	s_andn2_b64 vcc, exec, s[8:9]
	s_waitcnt lgkmcnt(0)
	global_load_dwordx4 v[166:169], v138, s[12:13] nt
	global_load_dwordx4 v[170:173], v138, s[10:11]
	global_load_dwordx4 v[174:177], v138, s[12:13] offset:256 nt
	global_load_dwordx4 v[178:181], v138, s[10:11] offset:256
	global_load_dwordx4 v[182:185], v139, s[12:13] nt
	global_load_dwordx4 v[186:189], v139, s[10:11]
	global_load_dwordx4 v[190:193], v139, s[12:13] offset:256 nt
	global_load_dwordx4 v[194:197], v139, s[10:11] offset:256
	global_load_dwordx4 v[198:201], v140, s[12:13] nt
	global_load_dwordx4 v[202:205], v140, s[10:11]
	global_load_dwordx4 v[228:231], v140, s[12:13] offset:256 nt
	global_load_dwordx4 v[232:235], v140, s[10:11] offset:256
	global_load_dwordx4 v[236:239], v141, s[12:13] nt
	global_load_dwordx4 v[156:159], v141, s[10:11]
	s_waitcnt vmcnt(12)
	v_lshlrev_b32_e32 v150, 16, v166
	v_and_b32_e32 v151, 0xffff0000, v166
	v_lshlrev_b32_e32 v152, 16, v170
	v_and_b32_e32 v153, 0xffff0000, v170
	v_pk_fma_f32 v[124:125], v[124:125], v[150:151], v[152:153]
	v_lshlrev_b32_e32 v150, 16, v167
	v_and_b32_e32 v151, 0xffff0000, v167
	v_lshlrev_b32_e32 v152, 16, v171
	v_and_b32_e32 v153, 0xffff0000, v171
	v_pk_fma_f32 v[126:127], v[126:127], v[150:151], v[152:153]
	v_lshlrev_b32_e32 v150, 16, v168
	v_and_b32_e32 v151, 0xffff0000, v168
	v_lshlrev_b32_e32 v152, 16, v172
	v_and_b32_e32 v153, 0xffff0000, v172
	v_pk_fma_f32 v[120:121], v[120:121], v[150:151], v[152:153]
	v_lshlrev_b32_e32 v150, 16, v169
	v_and_b32_e32 v151, 0xffff0000, v169
	v_lshlrev_b32_e32 v152, 16, v173
	v_and_b32_e32 v153, 0xffff0000, v173
	v_pk_fma_f32 v[122:123], v[122:123], v[150:151], v[152:153]
	v_cvt_pk_bf16_f32 v166, v124, v125
	v_cvt_pk_bf16_f32 v167, v126, v127
	v_cvt_pk_bf16_f32 v168, v120, v121
	v_cvt_pk_bf16_f32 v169, v122, v123
	global_store_dwordx4 v138, v[166:169], s[10:11]
	global_load_dwordx4 v[166:169], v141, s[12:13] offset:256 nt
	global_load_dwordx4 v[170:173], v141, s[10:11] offset:256
	s_waitcnt vmcnt(13)
	v_lshlrev_b32_e32 v150, 16, v174
	v_and_b32_e32 v151, 0xffff0000, v174
	v_lshlrev_b32_e32 v152, 16, v178
	v_and_b32_e32 v153, 0xffff0000, v178
	v_pk_fma_f32 v[116:117], v[116:117], v[150:151], v[152:153]
	v_lshlrev_b32_e32 v150, 16, v175
	v_and_b32_e32 v151, 0xffff0000, v175
	v_lshlrev_b32_e32 v152, 16, v179
	v_and_b32_e32 v153, 0xffff0000, v179
	v_pk_fma_f32 v[118:119], v[118:119], v[150:151], v[152:153]
	v_lshlrev_b32_e32 v150, 16, v176
	v_and_b32_e32 v151, 0xffff0000, v176
	v_lshlrev_b32_e32 v152, 16, v180
	v_and_b32_e32 v153, 0xffff0000, v180
	v_pk_fma_f32 v[112:113], v[112:113], v[150:151], v[152:153]
	v_lshlrev_b32_e32 v150, 16, v177
	v_and_b32_e32 v151, 0xffff0000, v177
	v_lshlrev_b32_e32 v152, 16, v181
	v_and_b32_e32 v153, 0xffff0000, v181
	v_pk_fma_f32 v[114:115], v[114:115], v[150:151], v[152:153]
	v_cvt_pk_bf16_f32 v174, v116, v117
	v_cvt_pk_bf16_f32 v175, v118, v119
	v_cvt_pk_bf16_f32 v176, v112, v113
	v_cvt_pk_bf16_f32 v177, v114, v115
	global_store_dwordx4 v138, v[174:177], s[10:11] offset:256
	global_load_dwordx4 v[174:177], v142, s[12:13] nt
	global_load_dwordx4 v[178:181], v142, s[10:11]
	s_waitcnt vmcnt(14)
	v_lshlrev_b32_e32 v150, 16, v182
	v_and_b32_e32 v151, 0xffff0000, v182
	v_lshlrev_b32_e32 v152, 16, v186
	v_and_b32_e32 v153, 0xffff0000, v186
	v_pk_fma_f32 v[108:109], v[108:109], v[150:151], v[152:153]
	v_lshlrev_b32_e32 v150, 16, v183
	v_and_b32_e32 v151, 0xffff0000, v183
	v_lshlrev_b32_e32 v152, 16, v187
	v_and_b32_e32 v153, 0xffff0000, v187
	v_pk_fma_f32 v[110:111], v[110:111], v[150:151], v[152:153]
	v_lshlrev_b32_e32 v150, 16, v184
	v_and_b32_e32 v151, 0xffff0000, v184
	v_lshlrev_b32_e32 v152, 16, v188
	v_and_b32_e32 v153, 0xffff0000, v188
	v_pk_fma_f32 v[104:105], v[104:105], v[150:151], v[152:153]
	v_lshlrev_b32_e32 v150, 16, v185
	v_and_b32_e32 v151, 0xffff0000, v185
	v_lshlrev_b32_e32 v152, 16, v189
	v_and_b32_e32 v153, 0xffff0000, v189
	v_pk_fma_f32 v[106:107], v[106:107], v[150:151], v[152:153]
	v_cvt_pk_bf16_f32 v182, v108, v109
	v_cvt_pk_bf16_f32 v183, v110, v111
	v_cvt_pk_bf16_f32 v184, v104, v105
	v_cvt_pk_bf16_f32 v185, v106, v107
	global_store_dwordx4 v139, v[182:185], s[10:11]
	global_load_dwordx4 v[182:185], v142, s[12:13] offset:256 nt
	global_load_dwordx4 v[186:189], v142, s[10:11] offset:256
	s_waitcnt vmcnt(15)
	v_lshlrev_b32_e32 v150, 16, v190
	v_and_b32_e32 v151, 0xffff0000, v190
	v_lshlrev_b32_e32 v152, 16, v194
	v_and_b32_e32 v153, 0xffff0000, v194
	v_pk_fma_f32 v[100:101], v[100:101], v[150:151], v[152:153]
	v_lshlrev_b32_e32 v150, 16, v191
	v_and_b32_e32 v151, 0xffff0000, v191
	v_lshlrev_b32_e32 v152, 16, v195
	v_and_b32_e32 v153, 0xffff0000, v195
	v_pk_fma_f32 v[102:103], v[102:103], v[150:151], v[152:153]
	v_lshlrev_b32_e32 v150, 16, v192
	v_and_b32_e32 v151, 0xffff0000, v192
	v_lshlrev_b32_e32 v152, 16, v196
	v_and_b32_e32 v153, 0xffff0000, v196
	v_pk_fma_f32 v[96:97], v[96:97], v[150:151], v[152:153]
	v_lshlrev_b32_e32 v150, 16, v193
	v_and_b32_e32 v151, 0xffff0000, v193
	v_lshlrev_b32_e32 v152, 16, v197
	v_and_b32_e32 v153, 0xffff0000, v197
	v_pk_fma_f32 v[98:99], v[98:99], v[150:151], v[152:153]
	v_cvt_pk_bf16_f32 v190, v100, v101
	v_cvt_pk_bf16_f32 v191, v102, v103
	v_cvt_pk_bf16_f32 v192, v96, v97
	v_cvt_pk_bf16_f32 v193, v98, v99
	global_store_dwordx4 v139, v[190:193], s[10:11] offset:256
	global_load_dwordx4 v[190:193], v143, s[12:13] nt
	global_load_dwordx4 v[194:197], v143, s[10:11]
	s_waitcnt vmcnt(16)
	v_lshlrev_b32_e32 v150, 16, v198
	v_and_b32_e32 v151, 0xffff0000, v198
	v_lshlrev_b32_e32 v152, 16, v202
	v_and_b32_e32 v153, 0xffff0000, v202
	v_pk_fma_f32 v[92:93], v[92:93], v[150:151], v[152:153]
	v_lshlrev_b32_e32 v150, 16, v199
	v_and_b32_e32 v151, 0xffff0000, v199
	v_lshlrev_b32_e32 v152, 16, v203
	v_and_b32_e32 v153, 0xffff0000, v203
	v_pk_fma_f32 v[94:95], v[94:95], v[150:151], v[152:153]
	v_lshlrev_b32_e32 v150, 16, v200
	v_and_b32_e32 v151, 0xffff0000, v200
	v_lshlrev_b32_e32 v152, 16, v204
	v_and_b32_e32 v153, 0xffff0000, v204
	v_pk_fma_f32 v[88:89], v[88:89], v[150:151], v[152:153]
	v_lshlrev_b32_e32 v150, 16, v201
	v_and_b32_e32 v151, 0xffff0000, v201
	v_lshlrev_b32_e32 v152, 16, v205
	v_and_b32_e32 v153, 0xffff0000, v205
	v_pk_fma_f32 v[90:91], v[90:91], v[150:151], v[152:153]
	v_cvt_pk_bf16_f32 v198, v92, v93
	v_cvt_pk_bf16_f32 v199, v94, v95
	v_cvt_pk_bf16_f32 v200, v88, v89
	v_cvt_pk_bf16_f32 v201, v90, v91
	global_store_dwordx4 v140, v[198:201], s[10:11]
	global_load_dwordx4 v[198:201], v143, s[12:13] offset:256 nt
	global_load_dwordx4 v[202:205], v143, s[10:11] offset:256
	s_waitcnt vmcnt(17)
	v_lshlrev_b32_e32 v150, 16, v228
	v_and_b32_e32 v151, 0xffff0000, v228
	v_lshlrev_b32_e32 v152, 16, v232
	v_and_b32_e32 v153, 0xffff0000, v232
	v_pk_fma_f32 v[84:85], v[84:85], v[150:151], v[152:153]
	v_lshlrev_b32_e32 v150, 16, v229
	v_and_b32_e32 v151, 0xffff0000, v229
	v_lshlrev_b32_e32 v152, 16, v233
	v_and_b32_e32 v153, 0xffff0000, v233
	v_pk_fma_f32 v[86:87], v[86:87], v[150:151], v[152:153]
	v_lshlrev_b32_e32 v150, 16, v230
	v_and_b32_e32 v151, 0xffff0000, v230
	v_lshlrev_b32_e32 v152, 16, v234
	v_and_b32_e32 v153, 0xffff0000, v234
	v_pk_fma_f32 v[80:81], v[80:81], v[150:151], v[152:153]
	v_lshlrev_b32_e32 v150, 16, v231
	v_and_b32_e32 v151, 0xffff0000, v231
	v_lshlrev_b32_e32 v152, 16, v235
	v_and_b32_e32 v153, 0xffff0000, v235
	v_pk_fma_f32 v[82:83], v[82:83], v[150:151], v[152:153]
	v_cvt_pk_bf16_f32 v228, v84, v85
	v_cvt_pk_bf16_f32 v229, v86, v87
	v_cvt_pk_bf16_f32 v230, v80, v81
	v_cvt_pk_bf16_f32 v231, v82, v83
	global_store_dwordx4 v140, v[228:231], s[10:11] offset:256
	global_load_dwordx4 v[228:231], v148, s[12:13] nt
	global_load_dwordx4 v[232:235], v148, s[10:11]
	s_waitcnt vmcnt(18)
	v_lshlrev_b32_e32 v150, 16, v236
	v_and_b32_e32 v151, 0xffff0000, v236
	v_lshlrev_b32_e32 v152, 16, v156
	v_and_b32_e32 v153, 0xffff0000, v156
	v_pk_fma_f32 v[76:77], v[76:77], v[150:151], v[152:153]
	v_lshlrev_b32_e32 v150, 16, v237
	v_and_b32_e32 v151, 0xffff0000, v237
	v_lshlrev_b32_e32 v152, 16, v157
	v_and_b32_e32 v153, 0xffff0000, v157
	v_pk_fma_f32 v[78:79], v[78:79], v[150:151], v[152:153]
	v_lshlrev_b32_e32 v150, 16, v238
	v_and_b32_e32 v151, 0xffff0000, v238
	v_lshlrev_b32_e32 v152, 16, v158
	v_and_b32_e32 v153, 0xffff0000, v158
	v_pk_fma_f32 v[72:73], v[72:73], v[150:151], v[152:153]
	v_lshlrev_b32_e32 v150, 16, v239
	v_and_b32_e32 v151, 0xffff0000, v239
	v_lshlrev_b32_e32 v152, 16, v159
	v_and_b32_e32 v153, 0xffff0000, v159
	v_pk_fma_f32 v[74:75], v[74:75], v[150:151], v[152:153]
	v_cvt_pk_bf16_f32 v236, v76, v77
	v_cvt_pk_bf16_f32 v237, v78, v79
	v_cvt_pk_bf16_f32 v238, v72, v73
	v_cvt_pk_bf16_f32 v239, v74, v75
	global_store_dwordx4 v141, v[236:239], s[10:11]
	global_load_dwordx4 v[236:239], v148, s[12:13] offset:256 nt
	global_load_dwordx4 v[156:159], v148, s[10:11] offset:256
	s_waitcnt vmcnt(18)
	v_lshlrev_b32_e32 v150, 16, v166
	v_and_b32_e32 v151, 0xffff0000, v166
	v_lshlrev_b32_e32 v152, 16, v170
	v_and_b32_e32 v153, 0xffff0000, v170
	v_pk_fma_f32 v[68:69], v[68:69], v[150:151], v[152:153]
	v_lshlrev_b32_e32 v150, 16, v167
	v_and_b32_e32 v151, 0xffff0000, v167
	v_lshlrev_b32_e32 v152, 16, v171
	v_and_b32_e32 v153, 0xffff0000, v171
	v_pk_fma_f32 v[70:71], v[70:71], v[150:151], v[152:153]
	v_lshlrev_b32_e32 v150, 16, v168
	v_and_b32_e32 v151, 0xffff0000, v168
	v_lshlrev_b32_e32 v152, 16, v172
	v_and_b32_e32 v153, 0xffff0000, v172
	v_pk_fma_f32 v[64:65], v[64:65], v[150:151], v[152:153]
	v_lshlrev_b32_e32 v150, 16, v169
	v_and_b32_e32 v151, 0xffff0000, v169
	v_lshlrev_b32_e32 v152, 16, v173
	v_and_b32_e32 v153, 0xffff0000, v173
	v_pk_fma_f32 v[66:67], v[66:67], v[150:151], v[152:153]
	v_cvt_pk_bf16_f32 v166, v68, v69
	v_cvt_pk_bf16_f32 v167, v70, v71
	v_cvt_pk_bf16_f32 v168, v64, v65
	v_cvt_pk_bf16_f32 v169, v66, v67
	global_store_dwordx4 v141, v[166:169], s[10:11] offset:256
	global_load_dwordx4 v[166:169], v149, s[12:13] nt
	global_load_dwordx4 v[170:173], v149, s[10:11]
	s_waitcnt vmcnt(18)
	v_lshlrev_b32_e32 v150, 16, v174
	v_and_b32_e32 v151, 0xffff0000, v174
	v_lshlrev_b32_e32 v152, 16, v178
	v_and_b32_e32 v153, 0xffff0000, v178
	v_pk_fma_f32 v[60:61], v[60:61], v[150:151], v[152:153]
	v_lshlrev_b32_e32 v150, 16, v175
	v_and_b32_e32 v151, 0xffff0000, v175
	v_lshlrev_b32_e32 v152, 16, v179
	v_and_b32_e32 v153, 0xffff0000, v179
	v_pk_fma_f32 v[62:63], v[62:63], v[150:151], v[152:153]
	v_lshlrev_b32_e32 v150, 16, v176
	v_and_b32_e32 v151, 0xffff0000, v176
	v_lshlrev_b32_e32 v152, 16, v180
	v_and_b32_e32 v153, 0xffff0000, v180
	v_pk_fma_f32 v[56:57], v[56:57], v[150:151], v[152:153]
	v_lshlrev_b32_e32 v150, 16, v177
	v_and_b32_e32 v151, 0xffff0000, v177
	v_lshlrev_b32_e32 v152, 16, v181
	v_and_b32_e32 v153, 0xffff0000, v181
	v_pk_fma_f32 v[58:59], v[58:59], v[150:151], v[152:153]
	v_cvt_pk_bf16_f32 v174, v60, v61
	v_cvt_pk_bf16_f32 v175, v62, v63
	v_cvt_pk_bf16_f32 v176, v56, v57
	v_cvt_pk_bf16_f32 v177, v58, v59
	global_store_dwordx4 v142, v[174:177], s[10:11]
	global_load_dwordx4 v[174:177], v149, s[12:13] offset:256 nt
	global_load_dwordx4 v[178:181], v149, s[10:11] offset:256
	s_waitcnt vmcnt(18)
	v_lshlrev_b32_e32 v150, 16, v182
	v_and_b32_e32 v151, 0xffff0000, v182
	v_lshlrev_b32_e32 v152, 16, v186
	v_and_b32_e32 v153, 0xffff0000, v186
	v_pk_fma_f32 v[52:53], v[52:53], v[150:151], v[152:153]
	v_lshlrev_b32_e32 v150, 16, v183
	v_and_b32_e32 v151, 0xffff0000, v183
	v_lshlrev_b32_e32 v152, 16, v187
	v_and_b32_e32 v153, 0xffff0000, v187
	v_pk_fma_f32 v[54:55], v[54:55], v[150:151], v[152:153]
	v_lshlrev_b32_e32 v150, 16, v184
	v_and_b32_e32 v151, 0xffff0000, v184
	v_lshlrev_b32_e32 v152, 16, v188
	v_and_b32_e32 v153, 0xffff0000, v188
	v_pk_fma_f32 v[48:49], v[48:49], v[150:151], v[152:153]
	v_lshlrev_b32_e32 v150, 16, v185
	v_and_b32_e32 v151, 0xffff0000, v185
	v_lshlrev_b32_e32 v152, 16, v189
	v_and_b32_e32 v153, 0xffff0000, v189
	v_pk_fma_f32 v[50:51], v[50:51], v[150:151], v[152:153]
	v_cvt_pk_bf16_f32 v182, v52, v53
	v_cvt_pk_bf16_f32 v183, v54, v55
	v_cvt_pk_bf16_f32 v184, v48, v49
	v_cvt_pk_bf16_f32 v185, v50, v51
	global_store_dwordx4 v142, v[182:185], s[10:11] offset:256
	s_waitcnt vmcnt(16)
	v_lshlrev_b32_e32 v150, 16, v190
	v_and_b32_e32 v151, 0xffff0000, v190
	v_lshlrev_b32_e32 v152, 16, v194
	v_and_b32_e32 v153, 0xffff0000, v194
	v_pk_fma_f32 v[44:45], v[44:45], v[150:151], v[152:153]
	v_lshlrev_b32_e32 v150, 16, v191
	v_and_b32_e32 v151, 0xffff0000, v191
	v_lshlrev_b32_e32 v152, 16, v195
	v_and_b32_e32 v153, 0xffff0000, v195
	v_pk_fma_f32 v[46:47], v[46:47], v[150:151], v[152:153]
	v_lshlrev_b32_e32 v150, 16, v192
	v_and_b32_e32 v151, 0xffff0000, v192
	v_lshlrev_b32_e32 v152, 16, v196
	v_and_b32_e32 v153, 0xffff0000, v196
	v_pk_fma_f32 v[40:41], v[40:41], v[150:151], v[152:153]
	v_lshlrev_b32_e32 v150, 16, v193
	v_and_b32_e32 v151, 0xffff0000, v193
	v_lshlrev_b32_e32 v152, 16, v197
	v_and_b32_e32 v153, 0xffff0000, v197
	v_pk_fma_f32 v[42:43], v[42:43], v[150:151], v[152:153]
	v_cvt_pk_bf16_f32 v190, v44, v45
	v_cvt_pk_bf16_f32 v191, v46, v47
	v_cvt_pk_bf16_f32 v192, v40, v41
	v_cvt_pk_bf16_f32 v193, v42, v43
	global_store_dwordx4 v143, v[190:193], s[10:11]
	s_waitcnt vmcnt(14)
	v_lshlrev_b32_e32 v150, 16, v198
	v_and_b32_e32 v151, 0xffff0000, v198
	v_lshlrev_b32_e32 v152, 16, v202
	v_and_b32_e32 v153, 0xffff0000, v202
	v_pk_fma_f32 v[36:37], v[36:37], v[150:151], v[152:153]
	v_lshlrev_b32_e32 v150, 16, v199
	v_and_b32_e32 v151, 0xffff0000, v199
	v_lshlrev_b32_e32 v152, 16, v203
	v_and_b32_e32 v153, 0xffff0000, v203
	v_pk_fma_f32 v[38:39], v[38:39], v[150:151], v[152:153]
	v_lshlrev_b32_e32 v150, 16, v200
	v_and_b32_e32 v151, 0xffff0000, v200
	v_lshlrev_b32_e32 v152, 16, v204
	v_and_b32_e32 v153, 0xffff0000, v204
	v_pk_fma_f32 v[32:33], v[32:33], v[150:151], v[152:153]
	v_lshlrev_b32_e32 v150, 16, v201
	v_and_b32_e32 v151, 0xffff0000, v201
	v_lshlrev_b32_e32 v152, 16, v205
	v_and_b32_e32 v153, 0xffff0000, v205
	v_pk_fma_f32 v[34:35], v[34:35], v[150:151], v[152:153]
	v_cvt_pk_bf16_f32 v198, v36, v37
	v_cvt_pk_bf16_f32 v199, v38, v39
	v_cvt_pk_bf16_f32 v200, v32, v33
	v_cvt_pk_bf16_f32 v201, v34, v35
	global_store_dwordx4 v143, v[198:201], s[10:11] offset:256
	s_waitcnt vmcnt(12)
	v_lshlrev_b32_e32 v150, 16, v228
	v_and_b32_e32 v151, 0xffff0000, v228
	v_lshlrev_b32_e32 v152, 16, v232
	v_and_b32_e32 v153, 0xffff0000, v232
	v_pk_fma_f32 v[28:29], v[28:29], v[150:151], v[152:153]
	v_lshlrev_b32_e32 v150, 16, v229
	v_and_b32_e32 v151, 0xffff0000, v229
	v_lshlrev_b32_e32 v152, 16, v233
	v_and_b32_e32 v153, 0xffff0000, v233
	v_pk_fma_f32 v[30:31], v[30:31], v[150:151], v[152:153]
	v_lshlrev_b32_e32 v150, 16, v230
	v_and_b32_e32 v151, 0xffff0000, v230
	v_lshlrev_b32_e32 v152, 16, v234
	v_and_b32_e32 v153, 0xffff0000, v234
	v_pk_fma_f32 v[24:25], v[24:25], v[150:151], v[152:153]
	v_lshlrev_b32_e32 v150, 16, v231
	v_and_b32_e32 v151, 0xffff0000, v231
	v_lshlrev_b32_e32 v152, 16, v235
	v_and_b32_e32 v153, 0xffff0000, v235
	v_pk_fma_f32 v[26:27], v[26:27], v[150:151], v[152:153]
	v_cvt_pk_bf16_f32 v228, v28, v29
	v_cvt_pk_bf16_f32 v229, v30, v31
	v_cvt_pk_bf16_f32 v230, v24, v25
	v_cvt_pk_bf16_f32 v231, v26, v27
	global_store_dwordx4 v148, v[228:231], s[10:11]
	s_waitcnt vmcnt(10)
	v_lshlrev_b32_e32 v150, 16, v236
	v_and_b32_e32 v151, 0xffff0000, v236
	v_lshlrev_b32_e32 v152, 16, v156
	v_and_b32_e32 v153, 0xffff0000, v156
	v_pk_fma_f32 v[20:21], v[20:21], v[150:151], v[152:153]
	v_lshlrev_b32_e32 v150, 16, v237
	v_and_b32_e32 v151, 0xffff0000, v237
	v_lshlrev_b32_e32 v152, 16, v157
	v_and_b32_e32 v153, 0xffff0000, v157
	v_pk_fma_f32 v[22:23], v[22:23], v[150:151], v[152:153]
	v_lshlrev_b32_e32 v150, 16, v238
	v_and_b32_e32 v151, 0xffff0000, v238
	v_lshlrev_b32_e32 v152, 16, v158
	v_and_b32_e32 v153, 0xffff0000, v158
	v_pk_fma_f32 v[16:17], v[16:17], v[150:151], v[152:153]
	v_lshlrev_b32_e32 v150, 16, v239
	v_and_b32_e32 v151, 0xffff0000, v239
	v_lshlrev_b32_e32 v152, 16, v159
	v_and_b32_e32 v153, 0xffff0000, v159
	v_pk_fma_f32 v[18:19], v[18:19], v[150:151], v[152:153]
	v_cvt_pk_bf16_f32 v236, v20, v21
	v_cvt_pk_bf16_f32 v237, v22, v23
	v_cvt_pk_bf16_f32 v238, v16, v17
	v_cvt_pk_bf16_f32 v239, v18, v19
	global_store_dwordx4 v148, v[236:239], s[10:11] offset:256
	s_waitcnt vmcnt(8)
	v_lshlrev_b32_e32 v150, 16, v166
	v_and_b32_e32 v151, 0xffff0000, v166
	v_lshlrev_b32_e32 v152, 16, v170
	v_and_b32_e32 v153, 0xffff0000, v170
	v_pk_fma_f32 v[12:13], v[12:13], v[150:151], v[152:153]
	v_lshlrev_b32_e32 v150, 16, v167
	v_and_b32_e32 v151, 0xffff0000, v167
	v_lshlrev_b32_e32 v152, 16, v171
	v_and_b32_e32 v153, 0xffff0000, v171
	v_pk_fma_f32 v[14:15], v[14:15], v[150:151], v[152:153]
	v_lshlrev_b32_e32 v150, 16, v168
	v_and_b32_e32 v151, 0xffff0000, v168
	v_lshlrev_b32_e32 v152, 16, v172
	v_and_b32_e32 v153, 0xffff0000, v172
	v_pk_fma_f32 v[8:9], v[8:9], v[150:151], v[152:153]
	v_lshlrev_b32_e32 v150, 16, v169
	v_and_b32_e32 v151, 0xffff0000, v169
	v_lshlrev_b32_e32 v152, 16, v173
	v_and_b32_e32 v153, 0xffff0000, v173
	v_pk_fma_f32 v[10:11], v[10:11], v[150:151], v[152:153]
	v_cvt_pk_bf16_f32 v166, v12, v13
	v_cvt_pk_bf16_f32 v167, v14, v15
	v_cvt_pk_bf16_f32 v168, v8, v9
	v_cvt_pk_bf16_f32 v169, v10, v11
	global_store_dwordx4 v149, v[166:169], s[10:11]
	s_waitcnt vmcnt(6)
	v_lshlrev_b32_e32 v150, 16, v174
	v_and_b32_e32 v151, 0xffff0000, v174
	v_lshlrev_b32_e32 v152, 16, v178
	v_and_b32_e32 v153, 0xffff0000, v178
	v_pk_fma_f32 v[4:5], v[4:5], v[150:151], v[152:153]
	v_lshlrev_b32_e32 v150, 16, v175
	v_and_b32_e32 v151, 0xffff0000, v175
	v_lshlrev_b32_e32 v152, 16, v179
	v_and_b32_e32 v153, 0xffff0000, v179
	v_pk_fma_f32 v[6:7], v[6:7], v[150:151], v[152:153]
	v_lshlrev_b32_e32 v150, 16, v176
	v_and_b32_e32 v151, 0xffff0000, v176
	v_lshlrev_b32_e32 v152, 16, v180
	v_and_b32_e32 v153, 0xffff0000, v180
	v_pk_fma_f32 v[0:1], v[0:1], v[150:151], v[152:153]
	v_lshlrev_b32_e32 v150, 16, v177
	v_and_b32_e32 v151, 0xffff0000, v177
	v_lshlrev_b32_e32 v152, 16, v181
	v_and_b32_e32 v153, 0xffff0000, v181
	v_pk_fma_f32 v[2:3], v[2:3], v[150:151], v[152:153]
	v_cvt_pk_bf16_f32 v174, v4, v5
	v_cvt_pk_bf16_f32 v175, v6, v7
	v_cvt_pk_bf16_f32 v176, v0, v1
	v_cvt_pk_bf16_f32 v177, v2, v3
	global_store_dwordx4 v149, v[174:177], s[10:11] offset:256
	s_mov_b64 s[22:23], -1
	s_cbranch_vccnz .LBB0_139
	s_and_b64 vcc, exec, s[6:7]
	s_cbranch_vccnz .LBB0_138
	s_barrier
	s_branch .LBB0_138

.LBB0_170:
	v_lshl_add_u32 v150, s39, 8, v144
	v_lshl_add_u32 v151, s2, 8, v146
	v_lshlrev_b32_e32 v150, 10, v150
	v_add_lshl_u32 v138, v150, v151, 1
	v_add_u32_e32 v139, 0x8000, v138
	v_add_u32_e32 v140, 0x10000, v138
	v_add_u32_e32 v141, 0x18000, v138
	v_add_u32_e32 v142, 0x40000, v138
	v_add_u32_e32 v143, 0x48000, v138
	v_add_u32_e32 v148, 0x50000, v138
	v_add_u32_e32 v149, 0x58000, v138
	s_andn2_b64 vcc, exec, s[6:7]
	s_waitcnt lgkmcnt(0)
	global_load_dwordx4 v[166:169], v138, s[10:11] nt
	global_load_dwordx4 v[170:173], v138, s[8:9]
	global_load_dwordx4 v[174:177], v138, s[10:11] offset:256 nt
	global_load_dwordx4 v[178:181], v138, s[8:9] offset:256
	global_load_dwordx4 v[182:185], v139, s[10:11] nt
	global_load_dwordx4 v[186:189], v139, s[8:9]
	global_load_dwordx4 v[190:193], v139, s[10:11] offset:256 nt
	global_load_dwordx4 v[194:197], v139, s[8:9] offset:256
	global_load_dwordx4 v[198:201], v140, s[10:11] nt
	global_load_dwordx4 v[202:205], v140, s[8:9]
	global_load_dwordx4 v[228:231], v140, s[10:11] offset:256 nt
	global_load_dwordx4 v[232:235], v140, s[8:9] offset:256
	global_load_dwordx4 v[236:239], v141, s[10:11] nt
	global_load_dwordx4 v[156:159], v141, s[8:9]
	s_waitcnt vmcnt(12)
	v_lshlrev_b32_e32 v150, 16, v166
	v_and_b32_e32 v151, 0xffff0000, v166
	v_lshlrev_b32_e32 v152, 16, v170
	v_and_b32_e32 v153, 0xffff0000, v170
	v_pk_fma_f32 v[124:125], v[124:125], v[150:151], v[152:153]
	v_lshlrev_b32_e32 v150, 16, v167
	v_and_b32_e32 v151, 0xffff0000, v167
	v_lshlrev_b32_e32 v152, 16, v171
	v_and_b32_e32 v153, 0xffff0000, v171
	v_pk_fma_f32 v[126:127], v[126:127], v[150:151], v[152:153]
	v_lshlrev_b32_e32 v150, 16, v168
	v_and_b32_e32 v151, 0xffff0000, v168
	v_lshlrev_b32_e32 v152, 16, v172
	v_and_b32_e32 v153, 0xffff0000, v172
	v_pk_fma_f32 v[120:121], v[120:121], v[150:151], v[152:153]
	v_lshlrev_b32_e32 v150, 16, v169
	v_and_b32_e32 v151, 0xffff0000, v169
	v_lshlrev_b32_e32 v152, 16, v173
	v_and_b32_e32 v153, 0xffff0000, v173
	v_pk_fma_f32 v[122:123], v[122:123], v[150:151], v[152:153]
	v_cvt_pk_bf16_f32 v166, v124, v125
	v_cvt_pk_bf16_f32 v167, v126, v127
	v_cvt_pk_bf16_f32 v168, v120, v121
	v_cvt_pk_bf16_f32 v169, v122, v123
	global_store_dwordx4 v138, v[166:169], s[8:9]
	global_load_dwordx4 v[166:169], v141, s[10:11] offset:256 nt
	global_load_dwordx4 v[170:173], v141, s[8:9] offset:256
	s_waitcnt vmcnt(13)
	v_lshlrev_b32_e32 v150, 16, v174
	v_and_b32_e32 v151, 0xffff0000, v174
	v_lshlrev_b32_e32 v152, 16, v178
	v_and_b32_e32 v153, 0xffff0000, v178
	v_pk_fma_f32 v[116:117], v[116:117], v[150:151], v[152:153]
	v_lshlrev_b32_e32 v150, 16, v175
	v_and_b32_e32 v151, 0xffff0000, v175
	v_lshlrev_b32_e32 v152, 16, v179
	v_and_b32_e32 v153, 0xffff0000, v179
	v_pk_fma_f32 v[118:119], v[118:119], v[150:151], v[152:153]
	v_lshlrev_b32_e32 v150, 16, v176
	v_and_b32_e32 v151, 0xffff0000, v176
	v_lshlrev_b32_e32 v152, 16, v180
	v_and_b32_e32 v153, 0xffff0000, v180
	v_pk_fma_f32 v[112:113], v[112:113], v[150:151], v[152:153]
	v_lshlrev_b32_e32 v150, 16, v177
	v_and_b32_e32 v151, 0xffff0000, v177
	v_lshlrev_b32_e32 v152, 16, v181
	v_and_b32_e32 v153, 0xffff0000, v181
	v_pk_fma_f32 v[114:115], v[114:115], v[150:151], v[152:153]
	v_cvt_pk_bf16_f32 v174, v116, v117
	v_cvt_pk_bf16_f32 v175, v118, v119
	v_cvt_pk_bf16_f32 v176, v112, v113
	v_cvt_pk_bf16_f32 v177, v114, v115
	global_store_dwordx4 v138, v[174:177], s[8:9] offset:256
	global_load_dwordx4 v[174:177], v142, s[10:11] nt
	global_load_dwordx4 v[178:181], v142, s[8:9]
	s_waitcnt vmcnt(14)
	v_lshlrev_b32_e32 v150, 16, v182
	v_and_b32_e32 v151, 0xffff0000, v182
	v_lshlrev_b32_e32 v152, 16, v186
	v_and_b32_e32 v153, 0xffff0000, v186
	v_pk_fma_f32 v[108:109], v[108:109], v[150:151], v[152:153]
	v_lshlrev_b32_e32 v150, 16, v183
	v_and_b32_e32 v151, 0xffff0000, v183
	v_lshlrev_b32_e32 v152, 16, v187
	v_and_b32_e32 v153, 0xffff0000, v187
	v_pk_fma_f32 v[110:111], v[110:111], v[150:151], v[152:153]
	v_lshlrev_b32_e32 v150, 16, v184
	v_and_b32_e32 v151, 0xffff0000, v184
	v_lshlrev_b32_e32 v152, 16, v188
	v_and_b32_e32 v153, 0xffff0000, v188
	v_pk_fma_f32 v[104:105], v[104:105], v[150:151], v[152:153]
	v_lshlrev_b32_e32 v150, 16, v185
	v_and_b32_e32 v151, 0xffff0000, v185
	v_lshlrev_b32_e32 v152, 16, v189
	v_and_b32_e32 v153, 0xffff0000, v189
	v_pk_fma_f32 v[106:107], v[106:107], v[150:151], v[152:153]
	v_cvt_pk_bf16_f32 v182, v108, v109
	v_cvt_pk_bf16_f32 v183, v110, v111
	v_cvt_pk_bf16_f32 v184, v104, v105
	v_cvt_pk_bf16_f32 v185, v106, v107
	global_store_dwordx4 v139, v[182:185], s[8:9]
	global_load_dwordx4 v[182:185], v142, s[10:11] offset:256 nt
	global_load_dwordx4 v[186:189], v142, s[8:9] offset:256
	s_waitcnt vmcnt(15)
	v_lshlrev_b32_e32 v150, 16, v190
	v_and_b32_e32 v151, 0xffff0000, v190
	v_lshlrev_b32_e32 v152, 16, v194
	v_and_b32_e32 v153, 0xffff0000, v194
	v_pk_fma_f32 v[100:101], v[100:101], v[150:151], v[152:153]
	v_lshlrev_b32_e32 v150, 16, v191
	v_and_b32_e32 v151, 0xffff0000, v191
	v_lshlrev_b32_e32 v152, 16, v195
	v_and_b32_e32 v153, 0xffff0000, v195
	v_pk_fma_f32 v[102:103], v[102:103], v[150:151], v[152:153]
	v_lshlrev_b32_e32 v150, 16, v192
	v_and_b32_e32 v151, 0xffff0000, v192
	v_lshlrev_b32_e32 v152, 16, v196
	v_and_b32_e32 v153, 0xffff0000, v196
	v_pk_fma_f32 v[96:97], v[96:97], v[150:151], v[152:153]
	v_lshlrev_b32_e32 v150, 16, v193
	v_and_b32_e32 v151, 0xffff0000, v193
	v_lshlrev_b32_e32 v152, 16, v197
	v_and_b32_e32 v153, 0xffff0000, v197
	v_pk_fma_f32 v[98:99], v[98:99], v[150:151], v[152:153]
	v_cvt_pk_bf16_f32 v190, v100, v101
	v_cvt_pk_bf16_f32 v191, v102, v103
	v_cvt_pk_bf16_f32 v192, v96, v97
	v_cvt_pk_bf16_f32 v193, v98, v99
	global_store_dwordx4 v139, v[190:193], s[8:9] offset:256
	global_load_dwordx4 v[190:193], v143, s[10:11] nt
	global_load_dwordx4 v[194:197], v143, s[8:9]
	s_waitcnt vmcnt(16)
	v_lshlrev_b32_e32 v150, 16, v198
	v_and_b32_e32 v151, 0xffff0000, v198
	v_lshlrev_b32_e32 v152, 16, v202
	v_and_b32_e32 v153, 0xffff0000, v202
	v_pk_fma_f32 v[92:93], v[92:93], v[150:151], v[152:153]
	v_lshlrev_b32_e32 v150, 16, v199
	v_and_b32_e32 v151, 0xffff0000, v199
	v_lshlrev_b32_e32 v152, 16, v203
	v_and_b32_e32 v153, 0xffff0000, v203
	v_pk_fma_f32 v[94:95], v[94:95], v[150:151], v[152:153]
	v_lshlrev_b32_e32 v150, 16, v200
	v_and_b32_e32 v151, 0xffff0000, v200
	v_lshlrev_b32_e32 v152, 16, v204
	v_and_b32_e32 v153, 0xffff0000, v204
	v_pk_fma_f32 v[88:89], v[88:89], v[150:151], v[152:153]
	v_lshlrev_b32_e32 v150, 16, v201
	v_and_b32_e32 v151, 0xffff0000, v201
	v_lshlrev_b32_e32 v152, 16, v205
	v_and_b32_e32 v153, 0xffff0000, v205
	v_pk_fma_f32 v[90:91], v[90:91], v[150:151], v[152:153]
	v_cvt_pk_bf16_f32 v198, v92, v93
	v_cvt_pk_bf16_f32 v199, v94, v95
	v_cvt_pk_bf16_f32 v200, v88, v89
	v_cvt_pk_bf16_f32 v201, v90, v91
	global_store_dwordx4 v140, v[198:201], s[8:9]
	global_load_dwordx4 v[198:201], v143, s[10:11] offset:256 nt
	global_load_dwordx4 v[202:205], v143, s[8:9] offset:256
	s_waitcnt vmcnt(17)
	v_lshlrev_b32_e32 v150, 16, v228
	v_and_b32_e32 v151, 0xffff0000, v228
	v_lshlrev_b32_e32 v152, 16, v232
	v_and_b32_e32 v153, 0xffff0000, v232
	v_pk_fma_f32 v[84:85], v[84:85], v[150:151], v[152:153]
	v_lshlrev_b32_e32 v150, 16, v229
	v_and_b32_e32 v151, 0xffff0000, v229
	v_lshlrev_b32_e32 v152, 16, v233
	v_and_b32_e32 v153, 0xffff0000, v233
	v_pk_fma_f32 v[86:87], v[86:87], v[150:151], v[152:153]
	v_lshlrev_b32_e32 v150, 16, v230
	v_and_b32_e32 v151, 0xffff0000, v230
	v_lshlrev_b32_e32 v152, 16, v234
	v_and_b32_e32 v153, 0xffff0000, v234
	v_pk_fma_f32 v[80:81], v[80:81], v[150:151], v[152:153]
	v_lshlrev_b32_e32 v150, 16, v231
	v_and_b32_e32 v151, 0xffff0000, v231
	v_lshlrev_b32_e32 v152, 16, v235
	v_and_b32_e32 v153, 0xffff0000, v235
	v_pk_fma_f32 v[82:83], v[82:83], v[150:151], v[152:153]
	v_cvt_pk_bf16_f32 v228, v84, v85
	v_cvt_pk_bf16_f32 v229, v86, v87
	v_cvt_pk_bf16_f32 v230, v80, v81
	v_cvt_pk_bf16_f32 v231, v82, v83
	global_store_dwordx4 v140, v[228:231], s[8:9] offset:256
	global_load_dwordx4 v[228:231], v148, s[10:11] nt
	global_load_dwordx4 v[232:235], v148, s[8:9]
	s_waitcnt vmcnt(18)
	v_lshlrev_b32_e32 v150, 16, v236
	v_and_b32_e32 v151, 0xffff0000, v236
	v_lshlrev_b32_e32 v152, 16, v156
	v_and_b32_e32 v153, 0xffff0000, v156
	v_pk_fma_f32 v[76:77], v[76:77], v[150:151], v[152:153]
	v_lshlrev_b32_e32 v150, 16, v237
	v_and_b32_e32 v151, 0xffff0000, v237
	v_lshlrev_b32_e32 v152, 16, v157
	v_and_b32_e32 v153, 0xffff0000, v157
	v_pk_fma_f32 v[78:79], v[78:79], v[150:151], v[152:153]
	v_lshlrev_b32_e32 v150, 16, v238
	v_and_b32_e32 v151, 0xffff0000, v238
	v_lshlrev_b32_e32 v152, 16, v158
	v_and_b32_e32 v153, 0xffff0000, v158
	v_pk_fma_f32 v[72:73], v[72:73], v[150:151], v[152:153]
	v_lshlrev_b32_e32 v150, 16, v239
	v_and_b32_e32 v151, 0xffff0000, v239
	v_lshlrev_b32_e32 v152, 16, v159
	v_and_b32_e32 v153, 0xffff0000, v159
	v_pk_fma_f32 v[74:75], v[74:75], v[150:151], v[152:153]
	v_cvt_pk_bf16_f32 v236, v76, v77
	v_cvt_pk_bf16_f32 v237, v78, v79
	v_cvt_pk_bf16_f32 v238, v72, v73
	v_cvt_pk_bf16_f32 v239, v74, v75
	global_store_dwordx4 v141, v[236:239], s[8:9]
	global_load_dwordx4 v[236:239], v148, s[10:11] offset:256 nt
	global_load_dwordx4 v[156:159], v148, s[8:9] offset:256
	s_waitcnt vmcnt(18)
	v_lshlrev_b32_e32 v150, 16, v166
	v_and_b32_e32 v151, 0xffff0000, v166
	v_lshlrev_b32_e32 v152, 16, v170
	v_and_b32_e32 v153, 0xffff0000, v170
	v_pk_fma_f32 v[68:69], v[68:69], v[150:151], v[152:153]
	v_lshlrev_b32_e32 v150, 16, v167
	v_and_b32_e32 v151, 0xffff0000, v167
	v_lshlrev_b32_e32 v152, 16, v171
	v_and_b32_e32 v153, 0xffff0000, v171
	v_pk_fma_f32 v[70:71], v[70:71], v[150:151], v[152:153]
	v_lshlrev_b32_e32 v150, 16, v168
	v_and_b32_e32 v151, 0xffff0000, v168
	v_lshlrev_b32_e32 v152, 16, v172
	v_and_b32_e32 v153, 0xffff0000, v172
	v_pk_fma_f32 v[64:65], v[64:65], v[150:151], v[152:153]
	v_lshlrev_b32_e32 v150, 16, v169
	v_and_b32_e32 v151, 0xffff0000, v169
	v_lshlrev_b32_e32 v152, 16, v173
	v_and_b32_e32 v153, 0xffff0000, v173
	v_pk_fma_f32 v[66:67], v[66:67], v[150:151], v[152:153]
	v_cvt_pk_bf16_f32 v166, v68, v69
	v_cvt_pk_bf16_f32 v167, v70, v71
	v_cvt_pk_bf16_f32 v168, v64, v65
	v_cvt_pk_bf16_f32 v169, v66, v67
	global_store_dwordx4 v141, v[166:169], s[8:9] offset:256
	global_load_dwordx4 v[166:169], v149, s[10:11] nt
	global_load_dwordx4 v[170:173], v149, s[8:9]
	s_waitcnt vmcnt(18)
	v_lshlrev_b32_e32 v150, 16, v174
	v_and_b32_e32 v151, 0xffff0000, v174
	v_lshlrev_b32_e32 v152, 16, v178
	v_and_b32_e32 v153, 0xffff0000, v178
	v_pk_fma_f32 v[60:61], v[60:61], v[150:151], v[152:153]
	v_lshlrev_b32_e32 v150, 16, v175
	v_and_b32_e32 v151, 0xffff0000, v175
	v_lshlrev_b32_e32 v152, 16, v179
	v_and_b32_e32 v153, 0xffff0000, v179
	v_pk_fma_f32 v[62:63], v[62:63], v[150:151], v[152:153]
	v_lshlrev_b32_e32 v150, 16, v176
	v_and_b32_e32 v151, 0xffff0000, v176
	v_lshlrev_b32_e32 v152, 16, v180
	v_and_b32_e32 v153, 0xffff0000, v180
	v_pk_fma_f32 v[56:57], v[56:57], v[150:151], v[152:153]
	v_lshlrev_b32_e32 v150, 16, v177
	v_and_b32_e32 v151, 0xffff0000, v177
	v_lshlrev_b32_e32 v152, 16, v181
	v_and_b32_e32 v153, 0xffff0000, v181
	v_pk_fma_f32 v[58:59], v[58:59], v[150:151], v[152:153]
	v_cvt_pk_bf16_f32 v174, v60, v61
	v_cvt_pk_bf16_f32 v175, v62, v63
	v_cvt_pk_bf16_f32 v176, v56, v57
	v_cvt_pk_bf16_f32 v177, v58, v59
	global_store_dwordx4 v142, v[174:177], s[8:9]
	global_load_dwordx4 v[174:177], v149, s[10:11] offset:256 nt
	global_load_dwordx4 v[178:181], v149, s[8:9] offset:256
	s_waitcnt vmcnt(18)
	v_lshlrev_b32_e32 v150, 16, v182
	v_and_b32_e32 v151, 0xffff0000, v182
	v_lshlrev_b32_e32 v152, 16, v186
	v_and_b32_e32 v153, 0xffff0000, v186
	v_pk_fma_f32 v[52:53], v[52:53], v[150:151], v[152:153]
	v_lshlrev_b32_e32 v150, 16, v183
	v_and_b32_e32 v151, 0xffff0000, v183
	v_lshlrev_b32_e32 v152, 16, v187
	v_and_b32_e32 v153, 0xffff0000, v187
	v_pk_fma_f32 v[54:55], v[54:55], v[150:151], v[152:153]
	v_lshlrev_b32_e32 v150, 16, v184
	v_and_b32_e32 v151, 0xffff0000, v184
	v_lshlrev_b32_e32 v152, 16, v188
	v_and_b32_e32 v153, 0xffff0000, v188
	v_pk_fma_f32 v[48:49], v[48:49], v[150:151], v[152:153]
	v_lshlrev_b32_e32 v150, 16, v185
	v_and_b32_e32 v151, 0xffff0000, v185
	v_lshlrev_b32_e32 v152, 16, v189
	v_and_b32_e32 v153, 0xffff0000, v189
	v_pk_fma_f32 v[50:51], v[50:51], v[150:151], v[152:153]
	v_cvt_pk_bf16_f32 v182, v52, v53
	v_cvt_pk_bf16_f32 v183, v54, v55
	v_cvt_pk_bf16_f32 v184, v48, v49
	v_cvt_pk_bf16_f32 v185, v50, v51
	global_store_dwordx4 v142, v[182:185], s[8:9] offset:256
	s_waitcnt vmcnt(16)
	v_lshlrev_b32_e32 v150, 16, v190
	v_and_b32_e32 v151, 0xffff0000, v190
	v_lshlrev_b32_e32 v152, 16, v194
	v_and_b32_e32 v153, 0xffff0000, v194
	v_pk_fma_f32 v[44:45], v[44:45], v[150:151], v[152:153]
	v_lshlrev_b32_e32 v150, 16, v191
	v_and_b32_e32 v151, 0xffff0000, v191
	v_lshlrev_b32_e32 v152, 16, v195
	v_and_b32_e32 v153, 0xffff0000, v195
	v_pk_fma_f32 v[46:47], v[46:47], v[150:151], v[152:153]
	v_lshlrev_b32_e32 v150, 16, v192
	v_and_b32_e32 v151, 0xffff0000, v192
	v_lshlrev_b32_e32 v152, 16, v196
	v_and_b32_e32 v153, 0xffff0000, v196
	v_pk_fma_f32 v[40:41], v[40:41], v[150:151], v[152:153]
	v_lshlrev_b32_e32 v150, 16, v193
	v_and_b32_e32 v151, 0xffff0000, v193
	v_lshlrev_b32_e32 v152, 16, v197
	v_and_b32_e32 v153, 0xffff0000, v197
	v_pk_fma_f32 v[42:43], v[42:43], v[150:151], v[152:153]
	v_cvt_pk_bf16_f32 v190, v44, v45
	v_cvt_pk_bf16_f32 v191, v46, v47
	v_cvt_pk_bf16_f32 v192, v40, v41
	v_cvt_pk_bf16_f32 v193, v42, v43
	global_store_dwordx4 v143, v[190:193], s[8:9]
	s_waitcnt vmcnt(14)
	v_lshlrev_b32_e32 v150, 16, v198
	v_and_b32_e32 v151, 0xffff0000, v198
	v_lshlrev_b32_e32 v152, 16, v202
	v_and_b32_e32 v153, 0xffff0000, v202
	v_pk_fma_f32 v[36:37], v[36:37], v[150:151], v[152:153]
	v_lshlrev_b32_e32 v150, 16, v199
	v_and_b32_e32 v151, 0xffff0000, v199
	v_lshlrev_b32_e32 v152, 16, v203
	v_and_b32_e32 v153, 0xffff0000, v203
	v_pk_fma_f32 v[38:39], v[38:39], v[150:151], v[152:153]
	v_lshlrev_b32_e32 v150, 16, v200
	v_and_b32_e32 v151, 0xffff0000, v200
	v_lshlrev_b32_e32 v152, 16, v204
	v_and_b32_e32 v153, 0xffff0000, v204
	v_pk_fma_f32 v[32:33], v[32:33], v[150:151], v[152:153]
	v_lshlrev_b32_e32 v150, 16, v201
	v_and_b32_e32 v151, 0xffff0000, v201
	v_lshlrev_b32_e32 v152, 16, v205
	v_and_b32_e32 v153, 0xffff0000, v205
	v_pk_fma_f32 v[34:35], v[34:35], v[150:151], v[152:153]
	v_cvt_pk_bf16_f32 v198, v36, v37
	v_cvt_pk_bf16_f32 v199, v38, v39
	v_cvt_pk_bf16_f32 v200, v32, v33
	v_cvt_pk_bf16_f32 v201, v34, v35
	global_store_dwordx4 v143, v[198:201], s[8:9] offset:256
	s_waitcnt vmcnt(12)
	v_lshlrev_b32_e32 v150, 16, v228
	v_and_b32_e32 v151, 0xffff0000, v228
	v_lshlrev_b32_e32 v152, 16, v232
	v_and_b32_e32 v153, 0xffff0000, v232
	v_pk_fma_f32 v[28:29], v[28:29], v[150:151], v[152:153]
	v_lshlrev_b32_e32 v150, 16, v229
	v_and_b32_e32 v151, 0xffff0000, v229
	v_lshlrev_b32_e32 v152, 16, v233
	v_and_b32_e32 v153, 0xffff0000, v233
	v_pk_fma_f32 v[30:31], v[30:31], v[150:151], v[152:153]
	v_lshlrev_b32_e32 v150, 16, v230
	v_and_b32_e32 v151, 0xffff0000, v230
	v_lshlrev_b32_e32 v152, 16, v234
	v_and_b32_e32 v153, 0xffff0000, v234
	v_pk_fma_f32 v[24:25], v[24:25], v[150:151], v[152:153]
	v_lshlrev_b32_e32 v150, 16, v231
	v_and_b32_e32 v151, 0xffff0000, v231
	v_lshlrev_b32_e32 v152, 16, v235
	v_and_b32_e32 v153, 0xffff0000, v235
	v_pk_fma_f32 v[26:27], v[26:27], v[150:151], v[152:153]
	v_cvt_pk_bf16_f32 v228, v28, v29
	v_cvt_pk_bf16_f32 v229, v30, v31
	v_cvt_pk_bf16_f32 v230, v24, v25
	v_cvt_pk_bf16_f32 v231, v26, v27
	global_store_dwordx4 v148, v[228:231], s[8:9]
	s_waitcnt vmcnt(10)
	v_lshlrev_b32_e32 v150, 16, v236
	v_and_b32_e32 v151, 0xffff0000, v236
	v_lshlrev_b32_e32 v152, 16, v156
	v_and_b32_e32 v153, 0xffff0000, v156
	v_pk_fma_f32 v[20:21], v[20:21], v[150:151], v[152:153]
	v_lshlrev_b32_e32 v150, 16, v237
	v_and_b32_e32 v151, 0xffff0000, v237
	v_lshlrev_b32_e32 v152, 16, v157
	v_and_b32_e32 v153, 0xffff0000, v157
	v_pk_fma_f32 v[22:23], v[22:23], v[150:151], v[152:153]
	v_lshlrev_b32_e32 v150, 16, v238
	v_and_b32_e32 v151, 0xffff0000, v238
	v_lshlrev_b32_e32 v152, 16, v158
	v_and_b32_e32 v153, 0xffff0000, v158
	v_pk_fma_f32 v[16:17], v[16:17], v[150:151], v[152:153]
	v_lshlrev_b32_e32 v150, 16, v239
	v_and_b32_e32 v151, 0xffff0000, v239
	v_lshlrev_b32_e32 v152, 16, v159
	v_and_b32_e32 v153, 0xffff0000, v159
	v_pk_fma_f32 v[18:19], v[18:19], v[150:151], v[152:153]
	v_cvt_pk_bf16_f32 v236, v20, v21
	v_cvt_pk_bf16_f32 v237, v22, v23
	v_cvt_pk_bf16_f32 v238, v16, v17
	v_cvt_pk_bf16_f32 v239, v18, v19
	global_store_dwordx4 v148, v[236:239], s[8:9] offset:256
	s_waitcnt vmcnt(8)
	v_lshlrev_b32_e32 v150, 16, v166
	v_and_b32_e32 v151, 0xffff0000, v166
	v_lshlrev_b32_e32 v152, 16, v170
	v_and_b32_e32 v153, 0xffff0000, v170
	v_pk_fma_f32 v[12:13], v[12:13], v[150:151], v[152:153]
	v_lshlrev_b32_e32 v150, 16, v167
	v_and_b32_e32 v151, 0xffff0000, v167
	v_lshlrev_b32_e32 v152, 16, v171
	v_and_b32_e32 v153, 0xffff0000, v171
	v_pk_fma_f32 v[14:15], v[14:15], v[150:151], v[152:153]
	v_lshlrev_b32_e32 v150, 16, v168
	v_and_b32_e32 v151, 0xffff0000, v168
	v_lshlrev_b32_e32 v152, 16, v172
	v_and_b32_e32 v153, 0xffff0000, v172
	v_pk_fma_f32 v[8:9], v[8:9], v[150:151], v[152:153]
	v_lshlrev_b32_e32 v150, 16, v169
	v_and_b32_e32 v151, 0xffff0000, v169
	v_lshlrev_b32_e32 v152, 16, v173
	v_and_b32_e32 v153, 0xffff0000, v173
	v_pk_fma_f32 v[10:11], v[10:11], v[150:151], v[152:153]
	v_cvt_pk_bf16_f32 v166, v12, v13
	v_cvt_pk_bf16_f32 v167, v14, v15
	v_cvt_pk_bf16_f32 v168, v8, v9
	v_cvt_pk_bf16_f32 v169, v10, v11
	global_store_dwordx4 v149, v[166:169], s[8:9]
	s_waitcnt vmcnt(6)
	v_lshlrev_b32_e32 v150, 16, v174
	v_and_b32_e32 v151, 0xffff0000, v174
	v_lshlrev_b32_e32 v152, 16, v178
	v_and_b32_e32 v153, 0xffff0000, v178
	v_pk_fma_f32 v[4:5], v[4:5], v[150:151], v[152:153]
	v_lshlrev_b32_e32 v150, 16, v175
	v_and_b32_e32 v151, 0xffff0000, v175
	v_lshlrev_b32_e32 v152, 16, v179
	v_and_b32_e32 v153, 0xffff0000, v179
	v_pk_fma_f32 v[6:7], v[6:7], v[150:151], v[152:153]
	v_lshlrev_b32_e32 v150, 16, v176
	v_and_b32_e32 v151, 0xffff0000, v176
	v_lshlrev_b32_e32 v152, 16, v180
	v_and_b32_e32 v153, 0xffff0000, v180
	v_pk_fma_f32 v[0:1], v[0:1], v[150:151], v[152:153]
	v_lshlrev_b32_e32 v150, 16, v177
	v_and_b32_e32 v151, 0xffff0000, v177
	v_lshlrev_b32_e32 v152, 16, v181
	v_and_b32_e32 v153, 0xffff0000, v181
	v_pk_fma_f32 v[2:3], v[2:3], v[150:151], v[152:153]
	v_cvt_pk_bf16_f32 v174, v4, v5
	v_cvt_pk_bf16_f32 v175, v6, v7
	v_cvt_pk_bf16_f32 v176, v0, v1
	v_cvt_pk_bf16_f32 v177, v2, v3
	global_store_dwordx4 v149, v[174:177], s[8:9] offset:256
	s_mov_b64 s[20:21], -1
	s_cbranch_vccnz .LBB0_159
	s_and_b64 vcc, exec, s[4:5]
	s_cbranch_vccnz .LBB0_158
	s_barrier
	s_branch .LBB0_158

.LBB0_557:
	s_ashr_i32 s11, s39, 3
	s_mul_hi_i32 s13, s11, 0x6000
	s_mulk_i32 s11, 0x6000
	s_add_u32 s18, s31, s11
	s_addc_u32 s19, s34, s13
	v_lshl_add_u32 v154, s39, 8, v156
	v_lshl_add_u32 v155, s38, 8, v158
	v_lshlrev_b32_e32 v154, 12, v154
	v_lshlrev_b32_e32 v155, 2, v155
	v_add_u32_e32 v154, v154, v155
	s_andn2_b64 vcc, exec, s[6:7]
	s_waitcnt lgkmcnt(0)
	global_load_dwordx4 v[128:131], v155, s[18:19]
	global_load_dwordx4 v[132:135], v155, s[18:19] offset:16
	global_load_dwordx4 v[146:149], v155, s[18:19] offset:512
	global_load_dwordx4 v[150:153], v155, s[18:19] offset:528
	s_add_u32 s100, s0, 0x0
	s_addc_u32 s101, s1, 0
	global_load_dwordx4 v[166:169], v154, s[100:101] nt
	global_load_dwordx4 v[170:173], v154, s[100:101] offset:16 nt
	s_add_u32 s100, s0, 0x10000
	s_addc_u32 s101, s1, 0
	global_load_dwordx4 v[174:177], v154, s[100:101] nt
	global_load_dwordx4 v[178:181], v154, s[100:101] offset:16 nt
	s_add_u32 s100, s0, 0x20000
	s_addc_u32 s101, s1, 0
	global_load_dwordx4 v[182:185], v154, s[100:101] nt
	global_load_dwordx4 v[186:189], v154, s[100:101] offset:16 nt
	s_add_u32 s100, s0, 0x30000
	s_addc_u32 s101, s1, 0
	global_load_dwordx4 v[190:193], v154, s[100:101] nt
	global_load_dwordx4 v[194:197], v154, s[100:101] offset:16 nt
	s_add_u32 s100, s0, 0x80000
	s_addc_u32 s101, s1, 0
	global_load_dwordx4 v[198:201], v154, s[100:101] nt
	global_load_dwordx4 v[202:205], v154, s[100:101] offset:16 nt
	s_add_u32 s100, s0, 0x90000
	s_addc_u32 s101, s1, 0
	global_load_dwordx4 v[228:231], v154, s[100:101] nt
	global_load_dwordx4 v[232:235], v154, s[100:101] offset:16 nt
	s_waitcnt vmcnt(10)
	v_pk_fma_f32 v[166:167], v[124:125], v[128:129], v[166:167]
	v_pk_fma_f32 v[168:169], v[126:127], v[130:131], v[168:169]
	v_pk_fma_f32 v[170:171], v[120:121], v[132:133], v[170:171]
	v_pk_fma_f32 v[172:173], v[122:123], v[134:135], v[172:173]
	s_add_u32 s18, s8, 0x0
	s_addc_u32 s19, s9, 0
	global_store_dwordx4 v154, v[166:169], s[18:19]
	global_store_dwordx4 v154, v[170:173], s[18:19] offset:16
	s_add_u32 s100, s0, 0xa0000
	s_addc_u32 s101, s1, 0
	global_load_dwordx4 v[166:169], v154, s[100:101] nt
	global_load_dwordx4 v[170:173], v154, s[100:101] offset:16 nt
	s_waitcnt vmcnt(12)
	v_pk_fma_f32 v[174:175], v[116:117], v[128:129], v[174:175]
	v_pk_fma_f32 v[176:177], v[118:119], v[130:131], v[176:177]
	v_pk_fma_f32 v[178:179], v[112:113], v[132:133], v[178:179]
	v_pk_fma_f32 v[180:181], v[114:115], v[134:135], v[180:181]
	s_add_u32 s18, s8, 0x10000
	s_addc_u32 s19, s9, 0
	global_store_dwordx4 v154, v[174:177], s[18:19]
	global_store_dwordx4 v154, v[178:181], s[18:19] offset:16
	s_add_u32 s100, s0, 0xb0000
	s_addc_u32 s101, s1, 0
	global_load_dwordx4 v[174:177], v154, s[100:101] nt
	global_load_dwordx4 v[178:181], v154, s[100:101] offset:16 nt
	s_waitcnt vmcnt(14)
	v_pk_fma_f32 v[182:183], v[108:109], v[128:129], v[182:183]
	v_pk_fma_f32 v[184:185], v[110:111], v[130:131], v[184:185]
	v_pk_fma_f32 v[186:187], v[104:105], v[132:133], v[186:187]
	v_pk_fma_f32 v[188:189], v[106:107], v[134:135], v[188:189]
	s_add_u32 s18, s8, 0x20000
	s_addc_u32 s19, s9, 0
	global_store_dwordx4 v154, v[182:185], s[18:19]
	global_store_dwordx4 v154, v[186:189], s[18:19] offset:16
	s_add_u32 s100, s0, 0x0
	s_addc_u32 s101, s1, 0
	global_load_dwordx4 v[182:185], v154, s[100:101] offset:512 nt
	global_load_dwordx4 v[186:189], v154, s[100:101] offset:528 nt
	s_waitcnt vmcnt(16)
	v_pk_fma_f32 v[190:191], v[100:101], v[128:129], v[190:191]
	v_pk_fma_f32 v[192:193], v[102:103], v[130:131], v[192:193]
	v_pk_fma_f32 v[194:195], v[96:97], v[132:133], v[194:195]
	v_pk_fma_f32 v[196:197], v[98:99], v[134:135], v[196:197]
	s_add_u32 s18, s8, 0x30000
	s_addc_u32 s19, s9, 0
	global_store_dwordx4 v154, v[190:193], s[18:19]
	global_store_dwordx4 v154, v[194:197], s[18:19] offset:16
	s_add_u32 s100, s0, 0x10000
	s_addc_u32 s101, s1, 0
	global_load_dwordx4 v[190:193], v154, s[100:101] offset:512 nt
	global_load_dwordx4 v[194:197], v154, s[100:101] offset:528 nt
	s_waitcnt vmcnt(18)
	v_pk_fma_f32 v[198:199], v[92:93], v[128:129], v[198:199]
	v_pk_fma_f32 v[200:201], v[94:95], v[130:131], v[200:201]
	v_pk_fma_f32 v[202:203], v[88:89], v[132:133], v[202:203]
	v_pk_fma_f32 v[204:205], v[90:91], v[134:135], v[204:205]
	s_add_u32 s18, s8, 0x80000
	s_addc_u32 s19, s9, 0
	global_store_dwordx4 v154, v[198:201], s[18:19]
	global_store_dwordx4 v154, v[202:205], s[18:19] offset:16
	s_add_u32 s100, s0, 0x20000
	s_addc_u32 s101, s1, 0
	global_load_dwordx4 v[198:201], v154, s[100:101] offset:512 nt
	global_load_dwordx4 v[202:205], v154, s[100:101] offset:528 nt
	s_waitcnt vmcnt(20)
	v_pk_fma_f32 v[228:229], v[84:85], v[128:129], v[228:229]
	v_pk_fma_f32 v[230:231], v[86:87], v[130:131], v[230:231]
	v_pk_fma_f32 v[232:233], v[80:81], v[132:133], v[232:233]
	v_pk_fma_f32 v[234:235], v[82:83], v[134:135], v[234:235]
	s_add_u32 s18, s8, 0x90000
	s_addc_u32 s19, s9, 0
	global_store_dwordx4 v154, v[228:231], s[18:19]
	global_store_dwordx4 v154, v[232:235], s[18:19] offset:16
	s_add_u32 s100, s0, 0x30000
	s_addc_u32 s101, s1, 0
	global_load_dwordx4 v[228:231], v154, s[100:101] offset:512 nt
	global_load_dwordx4 v[232:235], v154, s[100:101] offset:528 nt
	s_waitcnt vmcnt(20)
	v_pk_fma_f32 v[166:167], v[76:77], v[128:129], v[166:167]
	v_pk_fma_f32 v[168:169], v[78:79], v[130:131], v[168:169]
	v_pk_fma_f32 v[170:171], v[72:73], v[132:133], v[170:171]
	v_pk_fma_f32 v[172:173], v[74:75], v[134:135], v[172:173]
	s_add_u32 s18, s8, 0xa0000
	s_addc_u32 s19, s9, 0
	global_store_dwordx4 v154, v[166:169], s[18:19]
	global_store_dwordx4 v154, v[170:173], s[18:19] offset:16
	s_add_u32 s100, s0, 0x80000
	s_addc_u32 s101, s1, 0
	global_load_dwordx4 v[166:169], v154, s[100:101] offset:512 nt
	global_load_dwordx4 v[170:173], v154, s[100:101] offset:528 nt
	s_waitcnt vmcnt(20)
	v_pk_fma_f32 v[174:175], v[68:69], v[128:129], v[174:175]
	v_pk_fma_f32 v[176:177], v[70:71], v[130:131], v[176:177]
	v_pk_fma_f32 v[178:179], v[56:57], v[132:133], v[178:179]
	v_pk_fma_f32 v[180:181], v[58:59], v[134:135], v[180:181]
	s_add_u32 s18, s8, 0xb0000
	s_addc_u32 s19, s9, 0
	global_store_dwordx4 v154, v[174:177], s[18:19]
	global_store_dwordx4 v154, v[178:181], s[18:19] offset:16
	s_add_u32 s100, s0, 0x90000
	s_addc_u32 s101, s1, 0
	global_load_dwordx4 v[174:177], v154, s[100:101] offset:512 nt
	global_load_dwordx4 v[178:181], v154, s[100:101] offset:528 nt
	s_waitcnt vmcnt(20)
	v_pk_fma_f32 v[182:183], v[64:65], v[146:147], v[182:183]
	v_pk_fma_f32 v[184:185], v[66:67], v[148:149], v[184:185]
	v_pk_fma_f32 v[186:187], v[60:61], v[150:151], v[186:187]
	v_pk_fma_f32 v[188:189], v[62:63], v[152:153], v[188:189]
	s_add_u32 s18, s8, 0x0
	s_addc_u32 s19, s9, 0
	global_store_dwordx4 v154, v[182:185], s[18:19] offset:512
	global_store_dwordx4 v154, v[186:189], s[18:19] offset:528
	s_add_u32 s100, s0, 0xa0000
	s_addc_u32 s101, s1, 0
	global_load_dwordx4 v[182:185], v154, s[100:101] offset:512 nt
	global_load_dwordx4 v[186:189], v154, s[100:101] offset:528 nt
	s_waitcnt vmcnt(20)
	v_pk_fma_f32 v[190:191], v[52:53], v[146:147], v[190:191]
	v_pk_fma_f32 v[192:193], v[54:55], v[148:149], v[192:193]
	v_pk_fma_f32 v[194:195], v[48:49], v[150:151], v[194:195]
	v_pk_fma_f32 v[196:197], v[50:51], v[152:153], v[196:197]
	s_add_u32 s18, s8, 0x10000
	s_addc_u32 s19, s9, 0
	global_store_dwordx4 v154, v[190:193], s[18:19] offset:512
	global_store_dwordx4 v154, v[194:197], s[18:19] offset:528
	s_add_u32 s100, s0, 0xb0000
	s_addc_u32 s101, s1, 0
	global_load_dwordx4 v[190:193], v154, s[100:101] offset:512 nt
	global_load_dwordx4 v[194:197], v154, s[100:101] offset:528 nt
	s_waitcnt vmcnt(20)
	v_pk_fma_f32 v[198:199], v[44:45], v[146:147], v[198:199]
	v_pk_fma_f32 v[200:201], v[46:47], v[148:149], v[200:201]
	v_pk_fma_f32 v[202:203], v[40:41], v[150:151], v[202:203]
	v_pk_fma_f32 v[204:205], v[42:43], v[152:153], v[204:205]
	s_add_u32 s18, s8, 0x20000
	s_addc_u32 s19, s9, 0
	global_store_dwordx4 v154, v[198:201], s[18:19] offset:512
	global_store_dwordx4 v154, v[202:205], s[18:19] offset:528
	s_waitcnt vmcnt(18)
	v_pk_fma_f32 v[228:229], v[36:37], v[146:147], v[228:229]
	v_pk_fma_f32 v[230:231], v[38:39], v[148:149], v[230:231]
	v_pk_fma_f32 v[232:233], v[32:33], v[150:151], v[232:233]
	v_pk_fma_f32 v[234:235], v[34:35], v[152:153], v[234:235]
	s_add_u32 s18, s8, 0x30000
	s_addc_u32 s19, s9, 0
	global_store_dwordx4 v154, v[228:231], s[18:19] offset:512
	global_store_dwordx4 v154, v[232:235], s[18:19] offset:528
	s_waitcnt vmcnt(16)
	v_pk_fma_f32 v[166:167], v[28:29], v[146:147], v[166:167]
	v_pk_fma_f32 v[168:169], v[30:31], v[148:149], v[168:169]
	v_pk_fma_f32 v[170:171], v[24:25], v[150:151], v[170:171]
	v_pk_fma_f32 v[172:173], v[26:27], v[152:153], v[172:173]
	s_add_u32 s18, s8, 0x80000
	s_addc_u32 s19, s9, 0
	global_store_dwordx4 v154, v[166:169], s[18:19] offset:512
	global_store_dwordx4 v154, v[170:173], s[18:19] offset:528
	s_waitcnt vmcnt(14)
	v_pk_fma_f32 v[174:175], v[20:21], v[146:147], v[174:175]
	v_pk_fma_f32 v[176:177], v[22:23], v[148:149], v[176:177]
	v_pk_fma_f32 v[178:179], v[16:17], v[150:151], v[178:179]
	v_pk_fma_f32 v[180:181], v[18:19], v[152:153], v[180:181]
	s_add_u32 s18, s8, 0x90000
	s_addc_u32 s19, s9, 0
	global_store_dwordx4 v154, v[174:177], s[18:19] offset:512
	global_store_dwordx4 v154, v[178:181], s[18:19] offset:528
	s_waitcnt vmcnt(12)
	v_pk_fma_f32 v[182:183], v[12:13], v[146:147], v[182:183]
	v_pk_fma_f32 v[184:185], v[14:15], v[148:149], v[184:185]
	v_pk_fma_f32 v[186:187], v[8:9], v[150:151], v[186:187]
	v_pk_fma_f32 v[188:189], v[10:11], v[152:153], v[188:189]
	s_add_u32 s18, s8, 0xa0000
	s_addc_u32 s19, s9, 0
	global_store_dwordx4 v154, v[182:185], s[18:19] offset:512
	global_store_dwordx4 v154, v[186:189], s[18:19] offset:528
	s_waitcnt vmcnt(10)
	v_pk_fma_f32 v[190:191], v[4:5], v[146:147], v[190:191]
	v_pk_fma_f32 v[192:193], v[6:7], v[148:149], v[192:193]
	v_pk_fma_f32 v[194:195], v[0:1], v[150:151], v[194:195]
	v_pk_fma_f32 v[196:197], v[2:3], v[152:153], v[196:197]
	s_add_u32 s18, s8, 0xb0000
	s_addc_u32 s19, s9, 0
	global_store_dwordx4 v154, v[190:193], s[18:19] offset:512
	global_store_dwordx4 v154, v[194:197], s[18:19] offset:528
	s_mov_b64 s[18:19], -1
	s_cbranch_vccnz .LBB0_546
	s_and_b64 vcc, exec, s[4:5]
	s_cbranch_vccnz .LBB0_545
	s_barrier
	s_branch .LBB0_545

.LBB0_636:
	global_load_dword v78, v[0:1], off nt
	v_lshl_add_u64 v[0:1], v[0:1], 0, s[10:11]
	global_load_dword v79, v[0:1], off nt
	v_lshl_add_u64 v[0:1], v[0:1], 0, s[10:11]
	global_load_dword v80, v[0:1], off nt
	v_lshl_add_u64 v[0:1], v[0:1], 0, s[10:11]
	global_load_dword v81, v[0:1], off nt
	v_lshl_add_u64 v[0:1], v[0:1], 0, s[10:11]
	global_load_dword v82, v[0:1], off nt
	v_lshl_add_u64 v[0:1], v[0:1], 0, s[10:11]
	global_load_dword v83, v[0:1], off nt
	v_lshl_add_u64 v[0:1], v[0:1], 0, s[10:11]
	global_load_dword v84, v[0:1], off nt
	v_lshl_add_u64 v[0:1], v[0:1], 0, s[10:11]
	global_load_dword v85, v[0:1], off nt
	v_lshl_add_u64 v[0:1], v[0:1], 0, s[10:11]
	global_load_dword v86, v[0:1], off nt
	v_lshl_add_u64 v[0:1], v[0:1], 0, s[10:11]
	global_load_dword v87, v[0:1], off nt
	v_lshl_add_u64 v[0:1], v[0:1], 0, s[10:11]
	global_load_dword v88, v[0:1], off nt
	v_lshl_add_u64 v[0:1], v[0:1], 0, s[10:11]
	global_load_dword v89, v[0:1], off nt
	v_lshl_add_u64 v[0:1], v[0:1], 0, s[10:11]
	global_load_dword v90, v[0:1], off nt
	v_lshl_add_u64 v[0:1], v[0:1], 0, s[10:11]
	global_load_dword v91, v[0:1], off nt
	v_lshl_add_u64 v[0:1], v[0:1], 0, s[10:11]
	global_load_dword v92, v[0:1], off nt
	v_lshl_add_u64 v[0:1], v[0:1], 0, s[10:11]
	global_load_dword v93, v[0:1], off nt
	v_lshl_add_u64 v[0:1], v[0:1], 0, s[10:11]
	global_load_dword v94, v[0:1], off nt
	v_lshl_add_u64 v[0:1], v[0:1], 0, s[10:11]
	global_load_dword v95, v[0:1], off nt
	v_lshl_add_u64 v[0:1], v[0:1], 0, s[10:11]
	global_load_dword v96, v[0:1], off nt
	v_lshl_add_u64 v[0:1], v[0:1], 0, s[10:11]
	global_load_dword v97, v[0:1], off nt
	v_lshl_add_u64 v[0:1], v[0:1], 0, s[10:11]
	global_load_dword v98, v[0:1], off nt
	v_lshl_add_u64 v[0:1], v[0:1], 0, s[10:11]
	global_load_dword v99, v[0:1], off nt
	v_lshl_add_u64 v[0:1], v[0:1], 0, s[10:11]
	global_load_dword v100, v[0:1], off nt
	v_lshl_add_u64 v[0:1], v[0:1], 0, s[10:11]
	global_load_dword v101, v[0:1], off nt
	v_lshl_add_u64 v[0:1], v[0:1], 0, s[10:11]
	global_load_dword v102, v[0:1], off nt
	v_lshl_add_u64 v[0:1], v[0:1], 0, s[10:11]
	global_load_dword v103, v[0:1], off nt
	v_lshl_add_u64 v[0:1], v[0:1], 0, s[10:11]
	global_load_dword v104, v[0:1], off nt
	v_lshl_add_u64 v[0:1], v[0:1], 0, s[10:11]
	global_load_dword v105, v[0:1], off nt
	v_lshl_add_u64 v[0:1], v[0:1], 0, s[10:11]
	global_load_dword v106, v[0:1], off nt
	v_lshl_add_u64 v[0:1], v[0:1], 0, s[10:11]
	global_load_dword v107, v[0:1], off nt
	v_lshl_add_u64 v[0:1], v[0:1], 0, s[10:11]
	global_load_dword v108, v[0:1], off nt
	v_lshl_add_u64 v[0:1], v[0:1], 0, s[10:11]
	global_load_dword v109, v[0:1], off nt
	v_lshl_add_u64 v[0:1], v[0:1], 0, s[10:11]
	s_mov_b64 s[100:101], vcc
	s_ashr_i32 s1, s0, 31
	s_lshl_b64 s[0:1], s[0:1], 1
	s_add_u32 s0, s4, s0
	s_addc_u32 s1, s5, s1
	v_lshl_add_u64 v[150:151], s[0:1], 0, v[160:161]
	v_or_b32_e32 v14, s9, v4
	v_mul_hi_i32_i24_e32 v15, s8, v14
	v_mul_i32_i24_e32 v14, s8, v14
	v_lshl_add_u64 v[142:143], v[14:15], 1, v[150:151]
	v_or_b32_e32 v14, s9, v6
	v_mul_hi_i32_i24_e32 v15, s8, v14
	v_mul_i32_i24_e32 v14, s8, v14
	v_lshl_add_u64 v[144:145], v[14:15], 1, v[150:151]
	v_or_b32_e32 v14, s9, v7
	v_mul_hi_i32_i24_e32 v15, s8, v14
	v_mul_i32_i24_e32 v14, s8, v14
	v_lshl_add_u64 v[146:147], v[14:15], 1, v[150:151]
	v_or_b32_e32 v14, s9, v8
	v_mul_hi_i32_i24_e32 v15, s8, v14
	v_mul_i32_i24_e32 v14, s8, v14
	v_lshl_add_u64 v[148:149], v[14:15], 1, v[150:151]
	s_add_i32 s19, s19, s12
	v_readlane_b32 s0, v255, 10
	s_nop 3
	s_cmp_ge_i32 s19, s0
	s_cbranch_scc1 .Lw2_last
	s_mul_hi_i32 s0, s19, 0x3815e88f
	s_lshr_b32 s1, s0, 31
	s_ashr_i32 s0, s0, 11
	s_add_i32 s6, s0, s1
	s_mul_i32 s0, s6, 0x2484
	s_sub_i32 s20, s19, s0
	s_ashr_i32 s7, s6, 31
	s_mul_i32 s1, s6, 0x2500000
	s_mul_hi_i32 s0, s6, 0x2500000
	s_add_u32 s4, s2, s1
	s_addc_u32 s5, s18, s0
	s_cmpk_gt_i32 s20, 0xeff
	s_cselect_b64 s[0:1], -1, 0
	s_mov_b64 s[8:9], -1
	s_and_b64 vcc, exec, s[0:1]
	s_cbranch_vccnz .Lw2_587
	v_mov_b32_e32 v0, 48
	s_mul_i32 s9, s6, 0x1d20000
	v_add_u32_e32 v0, 0, v0
	v_add_u32_e32 v0, 0x20400, v0
	ds_read_b64 v[0:1], v0
	s_mul_hi_i32 s8, s6, 0x1d20000
	s_waitcnt lgkmcnt(0)
	v_readfirstlane_b32 s10, v0
	v_readfirstlane_b32 s11, v1
	s_add_u32 s10, s10, s9
	s_addc_u32 s11, s11, s8
	s_mov_b64 s[8:9], 0

.Lw2_635:
	s_or_b64 exec, exec, s[6:7]
	s_sext_i32_i16 s0, s16
	s_lshl_b32 s0, s0, 6
	v_or_b32_e32 v1, s0, v3
	v_cmp_lt_i32_e32 vcc, -1, v0
	v_mul_hi_i32_i24_e32 v11, s14, v1
	v_mul_i32_i24_e32 v10, s14, v1
	v_cndmask_b32_e32 v0, 0, v0, vcc
	v_lshl_add_u64 v[10:11], v[10:11], 2, s[10:11]
	v_ashrrev_i32_e32 v1, 31, v0
	s_mov_b32 s1, 0
	v_lshl_add_u64 v[0:1], v[0:1], 2, v[10:11]
	s_lshl_b64 s[6:7], s[14:15], 6
	s_lshl_b64 s[10:11], s[14:15], 3
	global_load_dword v110, v[0:1], off nt
	v_lshl_add_u64 v[0:1], v[0:1], 0, s[10:11]
	global_load_dword v111, v[0:1], off nt
	v_lshl_add_u64 v[0:1], v[0:1], 0, s[10:11]
	global_load_dword v112, v[0:1], off nt
	v_lshl_add_u64 v[0:1], v[0:1], 0, s[10:11]
	global_load_dword v113, v[0:1], off nt
	v_lshl_add_u64 v[0:1], v[0:1], 0, s[10:11]
	global_load_dword v114, v[0:1], off nt
	v_lshl_add_u64 v[0:1], v[0:1], 0, s[10:11]
	global_load_dword v115, v[0:1], off nt
	v_lshl_add_u64 v[0:1], v[0:1], 0, s[10:11]
	global_load_dword v116, v[0:1], off nt
	v_lshl_add_u64 v[0:1], v[0:1], 0, s[10:11]
	global_load_dword v117, v[0:1], off nt
	v_lshl_add_u64 v[0:1], v[0:1], 0, s[10:11]
	global_load_dword v118, v[0:1], off nt
	v_lshl_add_u64 v[0:1], v[0:1], 0, s[10:11]
	global_load_dword v119, v[0:1], off nt
	v_lshl_add_u64 v[0:1], v[0:1], 0, s[10:11]
	global_load_dword v120, v[0:1], off nt
	v_lshl_add_u64 v[0:1], v[0:1], 0, s[10:11]
	global_load_dword v121, v[0:1], off nt
	v_lshl_add_u64 v[0:1], v[0:1], 0, s[10:11]
	global_load_dword v122, v[0:1], off nt
	v_lshl_add_u64 v[0:1], v[0:1], 0, s[10:11]
	global_load_dword v123, v[0:1], off nt
	v_lshl_add_u64 v[0:1], v[0:1], 0, s[10:11]
	global_load_dword v124, v[0:1], off nt
	v_lshl_add_u64 v[0:1], v[0:1], 0, s[10:11]
	global_load_dword v125, v[0:1], off nt
	v_lshl_add_u64 v[0:1], v[0:1], 0, s[10:11]
	global_load_dword v126, v[0:1], off nt
	v_lshl_add_u64 v[0:1], v[0:1], 0, s[10:11]
	global_load_dword v127, v[0:1], off nt
	v_lshl_add_u64 v[0:1], v[0:1], 0, s[10:11]
	global_load_dword v128, v[0:1], off nt
	v_lshl_add_u64 v[0:1], v[0:1], 0, s[10:11]
	global_load_dword v129, v[0:1], off nt
	v_lshl_add_u64 v[0:1], v[0:1], 0, s[10:11]
	global_load_dword v130, v[0:1], off nt
	v_lshl_add_u64 v[0:1], v[0:1], 0, s[10:11]
	global_load_dword v131, v[0:1], off nt
	v_lshl_add_u64 v[0:1], v[0:1], 0, s[10:11]
	global_load_dword v132, v[0:1], off nt
	v_lshl_add_u64 v[0:1], v[0:1], 0, s[10:11]
	global_load_dword v133, v[0:1], off nt
	v_lshl_add_u64 v[0:1], v[0:1], 0, s[10:11]
	global_load_dword v134, v[0:1], off nt
	v_lshl_add_u64 v[0:1], v[0:1], 0, s[10:11]
	global_load_dword v135, v[0:1], off nt
	v_lshl_add_u64 v[0:1], v[0:1], 0, s[10:11]
	global_load_dword v136, v[0:1], off nt
	v_lshl_add_u64 v[0:1], v[0:1], 0, s[10:11]
	global_load_dword v137, v[0:1], off nt
	v_lshl_add_u64 v[0:1], v[0:1], 0, s[10:11]
	global_load_dword v138, v[0:1], off nt
	v_lshl_add_u64 v[0:1], v[0:1], 0, s[10:11]
	global_load_dword v139, v[0:1], off nt
	v_lshl_add_u64 v[0:1], v[0:1], 0, s[10:11]
	global_load_dword v140, v[0:1], off nt
	v_lshl_add_u64 v[0:1], v[0:1], 0, s[10:11]
	global_load_dword v141, v[0:1], off nt
	v_lshl_add_u64 v[0:1], v[0:1], 0, s[10:11]
	s_ashr_i32 s1, s0, 31
	s_lshl_b64 s[0:1], s[0:1], 1
	s_add_u32 s0, s4, s0
	s_addc_u32 s1, s5, s1
	v_lshl_add_u64 v[150:151], s[0:1], 0, v[160:161]
	v_or_b32_e32 v14, s9, v4
	v_mul_hi_i32_i24_e32 v15, s8, v14
	v_mul_i32_i24_e32 v14, s8, v14
	v_lshl_add_u64 v[152:153], v[14:15], 1, v[150:151]
	v_or_b32_e32 v14, s9, v6
	v_mul_hi_i32_i24_e32 v15, s8, v14
	v_mul_i32_i24_e32 v14, s8, v14
	v_lshl_add_u64 v[154:155], v[14:15], 1, v[150:151]
	v_or_b32_e32 v14, s9, v7
	v_mul_hi_i32_i24_e32 v15, s8, v14
	v_mul_i32_i24_e32 v14, s8, v14
	v_lshl_add_u64 v[156:157], v[14:15], 1, v[150:151]
	v_or_b32_e32 v14, s9, v8
	v_mul_hi_i32_i24_e32 v15, s8, v14
	v_mul_i32_i24_e32 v14, s8, v14
	v_lshl_add_u64 v[158:159], v[14:15], 1, v[150:151]
	s_waitcnt vmcnt(63)
	v_cndmask_b32_e64 v78, 0, v78, s[100:101]
	ds_write_b32 v9, v78
	s_waitcnt vmcnt(62)
	v_cndmask_b32_e64 v79, 0, v79, s[100:101]
	ds_write_b32 v9, v79 offset:264
	s_waitcnt vmcnt(61)
	v_cndmask_b32_e64 v80, 0, v80, s[100:101]
	ds_write_b32 v9, v80 offset:528
	s_waitcnt vmcnt(60)
	v_cndmask_b32_e64 v81, 0, v81, s[100:101]
	ds_write_b32 v9, v81 offset:792
	s_waitcnt vmcnt(59)
	v_cndmask_b32_e64 v82, 0, v82, s[100:101]
	ds_write_b32 v9, v82 offset:1056
	s_waitcnt vmcnt(58)
	v_cndmask_b32_e64 v83, 0, v83, s[100:101]
	ds_write_b32 v9, v83 offset:1320
	s_waitcnt vmcnt(57)
	v_cndmask_b32_e64 v84, 0, v84, s[100:101]
	ds_write_b32 v9, v84 offset:1584
	s_waitcnt vmcnt(56)
	v_cndmask_b32_e64 v85, 0, v85, s[100:101]
	ds_write_b32 v9, v85 offset:1848
	s_waitcnt vmcnt(55)
	v_cndmask_b32_e64 v86, 0, v86, s[100:101]
	ds_write_b32 v9, v86 offset:2112
	s_waitcnt vmcnt(54)
	v_cndmask_b32_e64 v87, 0, v87, s[100:101]
	ds_write_b32 v9, v87 offset:2376
	s_waitcnt vmcnt(53)
	v_cndmask_b32_e64 v88, 0, v88, s[100:101]
	ds_write_b32 v9, v88 offset:2640
	s_waitcnt vmcnt(52)
	v_cndmask_b32_e64 v89, 0, v89, s[100:101]
	ds_write_b32 v9, v89 offset:2904
	s_waitcnt vmcnt(51)
	v_cndmask_b32_e64 v90, 0, v90, s[100:101]
	ds_write_b32 v9, v90 offset:3168
	s_waitcnt vmcnt(50)
	v_cndmask_b32_e64 v91, 0, v91, s[100:101]
	ds_write_b32 v9, v91 offset:3432
	s_waitcnt vmcnt(49)
	v_cndmask_b32_e64 v92, 0, v92, s[100:101]
	ds_write_b32 v9, v92 offset:3696
	s_waitcnt vmcnt(48)
	v_cndmask_b32_e64 v93, 0, v93, s[100:101]
	ds_write_b32 v9, v93 offset:3960
	s_waitcnt vmcnt(47)
	v_cndmask_b32_e64 v94, 0, v94, s[100:101]
	ds_write_b32 v9, v94 offset:4224
	s_waitcnt vmcnt(46)
	v_cndmask_b32_e64 v95, 0, v95, s[100:101]
	ds_write_b32 v9, v95 offset:4488
	s_waitcnt vmcnt(45)
	v_cndmask_b32_e64 v96, 0, v96, s[100:101]
	ds_write_b32 v9, v96 offset:4752
	s_waitcnt vmcnt(44)
	v_cndmask_b32_e64 v97, 0, v97, s[100:101]
	ds_write_b32 v9, v97 offset:5016
	s_waitcnt vmcnt(43)
	v_cndmask_b32_e64 v98, 0, v98, s[100:101]
	ds_write_b32 v9, v98 offset:5280
	s_waitcnt vmcnt(42)
	v_cndmask_b32_e64 v99, 0, v99, s[100:101]
	ds_write_b32 v9, v99 offset:5544
	s_waitcnt vmcnt(41)
	v_cndmask_b32_e64 v100, 0, v100, s[100:101]
	ds_write_b32 v9, v100 offset:5808
	s_waitcnt vmcnt(40)
	v_cndmask_b32_e64 v101, 0, v101, s[100:101]
	ds_write_b32 v9, v101 offset:6072
	s_waitcnt vmcnt(39)
	v_cndmask_b32_e64 v102, 0, v102, s[100:101]
	ds_write_b32 v9, v102 offset:6336
	s_waitcnt vmcnt(38)
	v_cndmask_b32_e64 v103, 0, v103, s[100:101]
	ds_write_b32 v9, v103 offset:6600
	s_waitcnt vmcnt(37)
	v_cndmask_b32_e64 v104, 0, v104, s[100:101]
	ds_write_b32 v9, v104 offset:6864
	s_waitcnt vmcnt(36)
	v_cndmask_b32_e64 v105, 0, v105, s[100:101]
	ds_write_b32 v9, v105 offset:7128
	s_waitcnt vmcnt(35)
	v_cndmask_b32_e64 v106, 0, v106, s[100:101]
	ds_write_b32 v9, v106 offset:7392
	s_waitcnt vmcnt(34)
	v_cndmask_b32_e64 v107, 0, v107, s[100:101]
	ds_write_b32 v9, v107 offset:7656
	s_waitcnt vmcnt(33)
	v_cndmask_b32_e64 v108, 0, v108, s[100:101]
	ds_write_b32 v9, v108 offset:7920
	s_waitcnt vmcnt(32)
	v_cndmask_b32_e64 v109, 0, v109, s[100:101]
	ds_write_b32 v9, v109 offset:8184
	ds_read_b32 v10, v5
	ds_read_b32 v11, v5 offset:132
	ds_read_b32 v12, v5 offset:264
	ds_read_b32 v13, v5 offset:396
	ds_read_b32 v14, v5 offset:528
	ds_read_b32 v15, v5 offset:660
	ds_read_b32 v16, v5 offset:792
	ds_read_b32 v17, v5 offset:924
	s_waitcnt lgkmcnt(0)
	v_cvt_pk_bf16_f32 v10, v10, v11
	v_cvt_pk_bf16_f32 v11, v12, v13
	v_cvt_pk_bf16_f32 v12, v14, v15
	v_cvt_pk_bf16_f32 v13, v16, v17
	global_store_dwordx4 v[142:143], v[10:13], off
	ds_read_b32 v10, v5 offset:32
	ds_read_b32 v11, v5 offset:164
	ds_read_b32 v12, v5 offset:296
	ds_read_b32 v13, v5 offset:428
	ds_read_b32 v14, v5 offset:560
	ds_read_b32 v15, v5 offset:692
	ds_read_b32 v16, v5 offset:824
	ds_read_b32 v17, v5 offset:956
	s_waitcnt lgkmcnt(0)
	v_cvt_pk_bf16_f32 v10, v10, v11
	v_cvt_pk_bf16_f32 v11, v12, v13
	v_cvt_pk_bf16_f32 v12, v14, v15
	v_cvt_pk_bf16_f32 v13, v16, v17
	global_store_dwordx4 v[144:145], v[10:13], off
	ds_read_b32 v10, v5 offset:64
	ds_read_b32 v11, v5 offset:196
	ds_read_b32 v12, v5 offset:328
	ds_read_b32 v13, v5 offset:460
	ds_read_b32 v14, v5 offset:592
	ds_read_b32 v15, v5 offset:724
	ds_read_b32 v16, v5 offset:856
	ds_read_b32 v17, v5 offset:988
	s_waitcnt lgkmcnt(0)
	v_cvt_pk_bf16_f32 v10, v10, v11
	v_cvt_pk_bf16_f32 v11, v12, v13
	v_cvt_pk_bf16_f32 v12, v14, v15
	v_cvt_pk_bf16_f32 v13, v16, v17
	global_store_dwordx4 v[146:147], v[10:13], off
	ds_read_b32 v10, v5 offset:96
	ds_read_b32 v11, v5 offset:228
	ds_read_b32 v12, v5 offset:360
	ds_read_b32 v13, v5 offset:492
	ds_read_b32 v14, v5 offset:624
	ds_read_b32 v15, v5 offset:756
	ds_read_b32 v16, v5 offset:888
	ds_read_b32 v17, v5 offset:1020
	s_waitcnt lgkmcnt(0)
	v_cvt_pk_bf16_f32 v10, v10, v11
	v_cvt_pk_bf16_f32 v11, v12, v13
	v_cvt_pk_bf16_f32 v12, v14, v15
	v_cvt_pk_bf16_f32 v13, v16, v17
	global_store_dwordx4 v[148:149], v[10:13], off
	s_waitcnt vmcnt(35)
	v_cndmask_b32_e32 v110, 0, v110, vcc
	ds_write_b32 v9, v110
	s_waitcnt vmcnt(34)
	v_cndmask_b32_e32 v111, 0, v111, vcc
	ds_write_b32 v9, v111 offset:264
	s_waitcnt vmcnt(33)
	v_cndmask_b32_e32 v112, 0, v112, vcc
	ds_write_b32 v9, v112 offset:528
	s_waitcnt vmcnt(32)
	v_cndmask_b32_e32 v113, 0, v113, vcc
	ds_write_b32 v9, v113 offset:792
	s_waitcnt vmcnt(31)
	v_cndmask_b32_e32 v114, 0, v114, vcc
	ds_write_b32 v9, v114 offset:1056
	s_waitcnt vmcnt(30)
	v_cndmask_b32_e32 v115, 0, v115, vcc
	ds_write_b32 v9, v115 offset:1320
	s_waitcnt vmcnt(29)
	v_cndmask_b32_e32 v116, 0, v116, vcc
	ds_write_b32 v9, v116 offset:1584
	s_waitcnt vmcnt(28)
	v_cndmask_b32_e32 v117, 0, v117, vcc
	ds_write_b32 v9, v117 offset:1848
	s_waitcnt vmcnt(27)
	v_cndmask_b32_e32 v118, 0, v118, vcc
	ds_write_b32 v9, v118 offset:2112
	s_waitcnt vmcnt(26)
	v_cndmask_b32_e32 v119, 0, v119, vcc
	ds_write_b32 v9, v119 offset:2376
	s_waitcnt vmcnt(25)
	v_cndmask_b32_e32 v120, 0, v120, vcc
	ds_write_b32 v9, v120 offset:2640
	s_waitcnt vmcnt(24)
	v_cndmask_b32_e32 v121, 0, v121, vcc
	ds_write_b32 v9, v121 offset:2904
	s_waitcnt vmcnt(23)
	v_cndmask_b32_e32 v122, 0, v122, vcc
	ds_write_b32 v9, v122 offset:3168
	s_waitcnt vmcnt(22)
	v_cndmask_b32_e32 v123, 0, v123, vcc
	ds_write_b32 v9, v123 offset:3432
	s_waitcnt vmcnt(21)
	v_cndmask_b32_e32 v124, 0, v124, vcc
	ds_write_b32 v9, v124 offset:3696
	s_waitcnt vmcnt(20)
	v_cndmask_b32_e32 v125, 0, v125, vcc
	ds_write_b32 v9, v125 offset:3960
	s_waitcnt vmcnt(19)
	v_cndmask_b32_e32 v126, 0, v126, vcc
	ds_write_b32 v9, v126 offset:4224
	s_waitcnt vmcnt(18)
	v_cndmask_b32_e32 v127, 0, v127, vcc
	ds_write_b32 v9, v127 offset:4488
	s_waitcnt vmcnt(17)
	v_cndmask_b32_e32 v128, 0, v128, vcc
	ds_write_b32 v9, v128 offset:4752
	s_waitcnt vmcnt(16)
	v_cndmask_b32_e32 v129, 0, v129, vcc
	ds_write_b32 v9, v129 offset:5016
	s_waitcnt vmcnt(15)
	v_cndmask_b32_e32 v130, 0, v130, vcc
	ds_write_b32 v9, v130 offset:5280
	s_waitcnt vmcnt(14)
	v_cndmask_b32_e32 v131, 0, v131, vcc
	ds_write_b32 v9, v131 offset:5544
	s_waitcnt vmcnt(13)
	v_cndmask_b32_e32 v132, 0, v132, vcc
	ds_write_b32 v9, v132 offset:5808
	s_waitcnt vmcnt(12)
	v_cndmask_b32_e32 v133, 0, v133, vcc
	ds_write_b32 v9, v133 offset:6072
	s_waitcnt vmcnt(11)
	v_cndmask_b32_e32 v134, 0, v134, vcc
	ds_write_b32 v9, v134 offset:6336
	s_waitcnt vmcnt(10)
	v_cndmask_b32_e32 v135, 0, v135, vcc
	ds_write_b32 v9, v135 offset:6600
	s_waitcnt vmcnt(9)
	v_cndmask_b32_e32 v136, 0, v136, vcc
	ds_write_b32 v9, v136 offset:6864
	s_waitcnt vmcnt(8)
	v_cndmask_b32_e32 v137, 0, v137, vcc
	ds_write_b32 v9, v137 offset:7128
	s_waitcnt vmcnt(7)
	v_cndmask_b32_e32 v138, 0, v138, vcc
	ds_write_b32 v9, v138 offset:7392
	s_waitcnt vmcnt(6)
	v_cndmask_b32_e32 v139, 0, v139, vcc
	ds_write_b32 v9, v139 offset:7656
	s_waitcnt vmcnt(5)
	v_cndmask_b32_e32 v140, 0, v140, vcc
	ds_write_b32 v9, v140 offset:7920
	s_waitcnt vmcnt(4)
	v_cndmask_b32_e32 v141, 0, v141, vcc
	ds_write_b32 v9, v141 offset:8184
	ds_read_b32 v10, v5
	ds_read_b32 v11, v5 offset:132
	ds_read_b32 v12, v5 offset:264
	ds_read_b32 v13, v5 offset:396
	ds_read_b32 v14, v5 offset:528
	ds_read_b32 v15, v5 offset:660
	ds_read_b32 v16, v5 offset:792
	ds_read_b32 v17, v5 offset:924
	s_waitcnt lgkmcnt(0)
	v_cvt_pk_bf16_f32 v10, v10, v11
	v_cvt_pk_bf16_f32 v11, v12, v13
	v_cvt_pk_bf16_f32 v12, v14, v15
	v_cvt_pk_bf16_f32 v13, v16, v17
	global_store_dwordx4 v[152:153], v[10:13], off
	ds_read_b32 v10, v5 offset:32
	ds_read_b32 v11, v5 offset:164
	ds_read_b32 v12, v5 offset:296
	ds_read_b32 v13, v5 offset:428
	ds_read_b32 v14, v5 offset:560
	ds_read_b32 v15, v5 offset:692
	ds_read_b32 v16, v5 offset:824
	ds_read_b32 v17, v5 offset:956
	s_waitcnt lgkmcnt(0)
	v_cvt_pk_bf16_f32 v10, v10, v11
	v_cvt_pk_bf16_f32 v11, v12, v13
	v_cvt_pk_bf16_f32 v12, v14, v15
	v_cvt_pk_bf16_f32 v13, v16, v17
	global_store_dwordx4 v[154:155], v[10:13], off
	ds_read_b32 v10, v5 offset:64
	ds_read_b32 v11, v5 offset:196
	ds_read_b32 v12, v5 offset:328
	ds_read_b32 v13, v5 offset:460
	ds_read_b32 v14, v5 offset:592
	ds_read_b32 v15, v5 offset:724
	ds_read_b32 v16, v5 offset:856
	ds_read_b32 v17, v5 offset:988
	s_waitcnt lgkmcnt(0)
	v_cvt_pk_bf16_f32 v10, v10, v11
	v_cvt_pk_bf16_f32 v11, v12, v13
	v_cvt_pk_bf16_f32 v12, v14, v15
	v_cvt_pk_bf16_f32 v13, v16, v17
	global_store_dwordx4 v[156:157], v[10:13], off
	ds_read_b32 v10, v5 offset:96
	ds_read_b32 v11, v5 offset:228
	ds_read_b32 v12, v5 offset:360
	ds_read_b32 v13, v5 offset:492
	ds_read_b32 v14, v5 offset:624
	ds_read_b32 v15, v5 offset:756
	ds_read_b32 v16, v5 offset:888
	ds_read_b32 v17, v5 offset:1020
	s_waitcnt lgkmcnt(0)
	v_cvt_pk_bf16_f32 v10, v10, v11
	v_cvt_pk_bf16_f32 v11, v12, v13
	v_cvt_pk_bf16_f32 v12, v14, v15
	v_cvt_pk_bf16_f32 v13, v16, v17
	global_store_dwordx4 v[158:159], v[10:13], off
	s_add_i32 s19, s19, s12
	v_readlane_b32 s0, v255, 10
	s_nop 3
	s_cmp_ge_i32 s19, s0
	s_cbranch_scc0 .LBB0_585
	s_branch .LBB0_639
